# RWKV scan: output dot products written to LDS as one b128 per four steps
# speedup vs baseline: 1.0056x; 1.0056x over previous
.Lrw0_gdone:
	s_sub_u32 s29, s23, 1
	s_lshr_b32 s30, s23, 1
	s_cmp_eq_u32 s18, 0
	s_cselect_b32 s25, s30, s23
	s_sub_u32 s31, s18, 1
	s_cmp_lt_u32 s31, 2
	s_cselect_b32 s24, s30, 0
	s_cmp_eq_u32 s18, 2
	s_cselect_b32 s40, 0, 1.0
	s_mov_b32 s41, s40
	s_lshl_b32 s42, s21, 1
	s_add_u32 s42, s42, 0
	s_lshl_b32 s42, s42, 1
	s_add_u32 s42, s42, s20
	s_lshl_b32 s42, s42, 2
	s_add_u32 s42, s42, s19
	v_readlane_b32 s14, v246, 10
	v_readlane_b32 s15, v246, 11
	s_nop 4
	s_load_dwordx2 s[4:5], s[14:15], 0x178
	s_load_dwordx2 s[6:7], s[14:15], 0x188
	s_load_dwordx2 s[8:9], s[14:15], 0x198
	s_load_dwordx2 s[10:11], s[14:15], 0x98
	s_load_dwordx2 s[12:13], s[14:15], 0xc8
	s_load_dwordx2 s[26:27], s[14:15], 0xd0
	v_and_b32_e32 v87, 15, v226
	v_lshrrev_b32_e32 v127, 4, v226
	v_lshlrev_b32_e32 v95, 4, v87
	v_lshrrev_b32_e32 v108, 3, v226
	v_lshlrev_b32_e32 v108, 2, v108
	v_and_b32_e32 v112, 7, v226
	v_lshlrev_b32_e32 v112, 5, v112
	v_mul_u32_u24_e32 v93, 80, v87
	v_lshlrev_b32_e32 v110, 4, v226
	v_lshlrev_b32_e32 v115, 2, v226
	v_mul_u32_u24_e32 v1, 0x180, v127
	v_lshl_add_u32 v1, v87, 3, v1
	v_lshlrev_b32_e32 v2, 8, v127
	v_add_u32_e32 v3, v2, v95
	v_lshl_add_u32 v2, v87, 3, v2
	v_lshrrev_b32_e32 v89, 3, v87
	v_and_b32_e32 v90, 7, v87
	v_lshlrev_b32_e32 v91, 7, v127
	v_lshl_add_u32 v91, v90, 4, v91
	s_lshr_b32 s98, s17, 1
	v_add_u32_e32 v91, 0x5000, v91
	v_add_u32_e32 v92, 0xa000, v110
	v_cmp_eq_u32_e32 vcc, s98, v89
	s_nop 1
	v_cndmask_b32_e32 v4, v92, v91, vcc
	v_lshlrev_b32_e32 v5, 2, v127
	v_lshl_add_u32 v5, v87, 6, v5
	v_lshlrev_b32_e32 v113, 4, v108
	s_mov_b32 s30, 0xaaaaaab
	s_lshl_b32 s31, s19, 7
	v_mul_hi_u32 v87, v226, s30
	v_mul_u32_u24_e32 v89, 24, v87
	v_sub_u32_e32 v89, v226, v89
	v_add_u32_e32 v15, -1, v87
	v_lshrrev_b32_e32 v90, 3, v89
	v_and_b32_e32 v89, 7, v89
	v_lshlrev_b32_e32 v90, 9, v90
	v_lshl_add_u32 v91, v89, 4, v90
	v_add_u32_e32 v91, s31, v91
	v_add_u32_e32 v91, 0xd20, v91
	s_add_u32 s34, s22, s29
	s_cmp_eq_u32 s20, 0
	s_cselect_b32 s34, s22, s34
	s_waitcnt lgkmcnt(0)
	s_mul_i32 s98, s34, 0x1520
	s_mul_hi_u32 s99, s34, 0x1520
	s_add_u32 s100, s4, s98
	s_addc_u32 s101, s5, s99
	s_mul_i32 s98, s34, 0xa00
	s_mul_hi_u32 s99, s34, 0xa00
	s_add_u32 s98, s6, s98
	s_addc_u32 s99, s7, s99
	v_mov_b32_e32 v92, 0
	v_mov_b32_e32 v6, s100
	v_mov_b32_e32 v7, s101
	v_add_co_u32_e32 v6, vcc, v6, v91
	s_nop 1
	v_addc_co_u32_e32 v7, vcc, 0, v7, vcc
	s_movk_i32 s36, 0x1520
	s_mul_i32 s37, s36, -1
	s_cmp_eq_u32 s20, 0
	s_cselect_b32 s34, s36, s37
	s_movk_i32 s36, 0xa00
	s_mul_i32 s37, s36, -1
	s_cselect_b32 s35, s36, s37
	v_mov_b32_e32 v12, s34
	v_add_u32_e32 v92, 0x100, v226
	v_mul_hi_u32 v87, v92, s30
	v_mul_u32_u24_e32 v89, 24, v87
	v_sub_u32_e32 v89, v92, v89
	v_add_u32_e32 v16, -1, v87
	v_lshrrev_b32_e32 v90, 3, v89
	v_and_b32_e32 v89, 7, v89
	v_lshlrev_b32_e32 v90, 9, v90
	v_lshl_add_u32 v91, v89, 4, v90
	v_add_u32_e32 v91, s31, v91
	v_add_u32_e32 v91, 0xd20, v91
	s_lshl_b32 s36, s20, 9
	s_add_u32 s36, s36, s31
	v_add_u32_e32 v92, 0xffffff50, v226
	v_lshrrev_b32_e32 v21, 4, v92
	v_and_b32_e32 v87, 15, v92
	v_lshrrev_b32_e32 v89, 3, v87
	v_and_b32_e32 v87, 7, v87
	v_lshlrev_b32_e32 v89, 10, v89
	v_lshl_add_u32 v90, v87, 4, v89
	v_add_u32_e32 v90, s36, v90
	v_cmp_gt_u32_e32 vcc, 0xb0, v226
	s_nop 1
	v_cndmask_b32_e32 v16, v21, v16, vcc
	v_cndmask_b32_e32 v91, v90, v91, vcc
	v_mov_b32_e32 v87, s35
	v_mov_b32_e32 v89, s34
	v_cndmask_b32_e32 v13, v87, v89, vcc
	v_mov_b32_e32 v87, s98
	v_mov_b32_e32 v89, s100
	v_cndmask_b32_e32 v8, v87, v89, vcc
	v_mov_b32_e32 v87, s99
	v_mov_b32_e32 v89, s101
	v_cndmask_b32_e32 v9, v87, v89, vcc
	v_add_co_u32_e32 v8, vcc, v8, v91
	s_nop 1
	v_addc_co_u32_e32 v9, vcc, 0, v9, vcc
	v_add_u32_e32 v92, 0x50, v226
	v_lshrrev_b32_e32 v17, 4, v92
	v_and_b32_e32 v87, 15, v92
	v_lshrrev_b32_e32 v89, 3, v87
	v_and_b32_e32 v87, 7, v87
	v_lshlrev_b32_e32 v89, 10, v89
	v_lshl_add_u32 v91, v87, 4, v89
	v_add_u32_e32 v91, s36, v91
	v_mov_b32_e32 v10, s98
	v_mov_b32_e32 v11, s99
	v_add_co_u32_e32 v10, vcc, v10, v91
	s_nop 1
	v_addc_co_u32_e32 v11, vcc, 0, v11, vcc
	v_mov_b32_e32 v14, s35
	s_add_u32 s30, s22, s29
	s_cmp_eq_u32 s20, 0
	s_cselect_b32 s30, s22, s30
	s_lshl_b32 s36, s19, 7
	s_lshl_b32 s37, s17, 5
	s_add_u32 s36, s36, s37
	s_cmp_eq_u32 s18, 2
	s_cbranch_scc1 .Lrw0_o_u2
	s_lshl_b32 s37, s20, 9
	s_add_u32 s36, s36, s37
	s_mul_i32 s98, s30, 0xa00
	s_mul_hi_u32 s99, s30, 0xa00
	s_add_u32 s98, s98, s36
	s_addc_u32 s99, s99, 0
	s_add_u32 s98, s8, s98
	s_addc_u32 s99, s9, s99
	s_movk_i32 s36, 0xa00
	s_mul_i32 s37, s36, -1
	s_cmp_eq_u32 s20, 0
	s_cselect_b32 s35, s36, s37
	s_branch .Lrw0_o_done

.Lrw0_loop:
	s_waitcnt vmcnt(0)
	ds_write_b128 v110, v[46:49] offset:26624
	ds_write_b128 v110, v[50:53] offset:30720
	ds_write_b128 v110, v[54:57] offset:34816
	s_waitcnt lgkmcnt(0)
	s_barrier
	s_add_u32 s30, s28, 32
	v_add_u32_e32 v87, s30, v15
	v_med3_i32 v87, v87, 0, s29
	v_mad_i64_i32 v[104:105], vcc, v87, v12, v[6:7]
	global_load_dwordx4 v[46:49], v[104:105], off
	v_add_u32_e32 v87, s30, v16
	v_med3_i32 v87, v87, 0, s29
	v_mad_i64_i32 v[104:105], vcc, v87, v13, v[8:9]
	global_load_dwordx4 v[50:53], v[104:105], off
	v_add_u32_e32 v87, s30, v17
	v_med3_i32 v87, v87, 0, s29
	v_mad_i64_i32 v[104:105], vcc, v87, v14, v[10:11]
	global_load_dwordx4 v[54:57], v[104:105], off
	s_cmp_eq_u32 s35, 0
	s_cbranch_scc1 .Lrw0_noout
	ds_read_b32 v89, v5 offset:24576
	ds_read_b32 v90, v5 offset:25600
	s_sub_u32 s98, s28, 16
	v_add_u32_e32 v87, s98, v127
	v_mad_i64_i32 v[104:105], vcc, v87, v20, v[18:19]
	s_waitcnt lgkmcnt(0)
	v_cvt_pk_bf16_f32 v89, v89, v90
	global_store_short v[104:105], v89, off
	global_store_short_d16_hi v[104:105], v89, off offset:32
.Lrw0_noout:
	ds_read_b128 v[30:33], v93 offset:46080
	ds_read_b128 v[34:37], v93 offset:46096
	ds_read_b128 v[38:41], v93 offset:46112
	ds_read_b128 v[42:45], v93 offset:46128
	ds_read_b64 v[70:71], v1 offset:27008
	ds_read_b64 v[72:73], v1 offset:26624
	ds_read_b64 v[74:75], v1 offset:27392
	ds_read_b64 v[76:77], v1 offset:27136
	ds_read_b64 v[78:79], v1 offset:26752
	ds_read_b64 v[80:81], v1 offset:27520
	ds_read_b64 v[82:83], v1 offset:27264
	ds_read_b64 v[84:85], v1 offset:26880
	ds_read_b64 v[96:97], v1 offset:27648
	ds_read_b64 v[128:129], v2 offset:33536
	ds_read_b64 v[130:131], v2 offset:33664
	v_add_u32_e32 v87, s28, v127
	v_cmp_ne_u32_e32 vcc, 0, v87
	s_nop 1
	v_cndmask_b32_e64 v98, 0, 0.5, vcc
	v_cmp_ne_u32_e32 vcc, s29, v87
	s_nop 1
	v_cndmask_b32_e64 v100, 0, 0.5, vcc
	s_waitcnt lgkmcnt(8)
	v_lshlrev_b32_e32 v132, 16, v70
	v_and_b32_e32 v133, 0xffff0000, v70
	v_lshlrev_b32_e32 v134, 16, v71
	v_and_b32_e32 v135, 0xffff0000, v71
	v_lshlrev_b32_e32 v136, 16, v72
	v_and_b32_e32 v137, 0xffff0000, v72
	v_lshlrev_b32_e32 v138, 16, v73
	v_and_b32_e32 v139, 0xffff0000, v73
	v_lshlrev_b32_e32 v140, 16, v74
	v_and_b32_e32 v141, 0xffff0000, v74
	v_lshlrev_b32_e32 v142, 16, v75
	v_and_b32_e32 v143, 0xffff0000, v75
	v_pk_mul_f32 v[136:137], v[136:137], v[98:99] op_sel_hi:[1,0]
	v_pk_fma_f32 v[136:137], v[140:141], v[100:101], v[136:137] op_sel_hi:[1,0,1]
	v_pk_add_f32 v[136:137], v[136:137], v[132:133] neg_lo:[0,1] neg_hi:[0,1]
	v_pk_fma_f32 v[144:145], v[30:31], v[136:137], v[132:133]
	v_pk_mul_f32 v[138:139], v[138:139], v[98:99] op_sel_hi:[1,0]
	v_pk_fma_f32 v[138:139], v[142:143], v[100:101], v[138:139] op_sel_hi:[1,0,1]
	v_pk_add_f32 v[138:139], v[138:139], v[134:135] neg_lo:[0,1] neg_hi:[0,1]
	v_pk_fma_f32 v[146:147], v[32:33], v[138:139], v[134:135]
	ds_read_b128 v[30:33], v93 offset:46144
	s_waitcnt lgkmcnt(6)
	v_lshlrev_b32_e32 v132, 16, v76
	v_and_b32_e32 v133, 0xffff0000, v76
	v_lshlrev_b32_e32 v134, 16, v77
	v_and_b32_e32 v135, 0xffff0000, v77
	v_lshlrev_b32_e32 v136, 16, v78
	v_and_b32_e32 v137, 0xffff0000, v78
	v_lshlrev_b32_e32 v138, 16, v79
	v_and_b32_e32 v139, 0xffff0000, v79
	v_lshlrev_b32_e32 v140, 16, v80
	v_and_b32_e32 v141, 0xffff0000, v80
	v_lshlrev_b32_e32 v142, 16, v81
	v_and_b32_e32 v143, 0xffff0000, v81
	v_pk_mul_f32 v[136:137], v[136:137], v[98:99] op_sel_hi:[1,0]
	v_pk_fma_f32 v[136:137], v[140:141], v[100:101], v[136:137] op_sel_hi:[1,0,1]
	v_pk_add_f32 v[136:137], v[136:137], v[132:133] neg_lo:[0,1] neg_hi:[0,1]
	v_pk_fma_f32 v[102:103], v[34:35], v[136:137], v[132:133]
	v_pk_mul_f32 v[138:139], v[138:139], v[98:99] op_sel_hi:[1,0]
	v_pk_fma_f32 v[138:139], v[142:143], v[100:101], v[138:139] op_sel_hi:[1,0,1]
	v_pk_add_f32 v[138:139], v[138:139], v[134:135] neg_lo:[0,1] neg_hi:[0,1]
	v_pk_fma_f32 v[104:105], v[36:37], v[138:139], v[134:135]
	s_waitcnt lgkmcnt(3)
	v_lshlrev_b32_e32 v132, 16, v82
	v_and_b32_e32 v133, 0xffff0000, v82
	v_lshlrev_b32_e32 v134, 16, v83
	v_and_b32_e32 v135, 0xffff0000, v83
	v_lshlrev_b32_e32 v136, 16, v84
	v_and_b32_e32 v137, 0xffff0000, v84
	v_lshlrev_b32_e32 v138, 16, v85
	v_and_b32_e32 v139, 0xffff0000, v85
	v_lshlrev_b32_e32 v140, 16, v96
	v_and_b32_e32 v141, 0xffff0000, v96
	v_lshlrev_b32_e32 v142, 16, v97
	v_and_b32_e32 v143, 0xffff0000, v97
	v_pk_mul_f32 v[136:137], v[136:137], v[98:99] op_sel_hi:[1,0]
	v_pk_fma_f32 v[136:137], v[140:141], v[100:101], v[136:137] op_sel_hi:[1,0,1]
	v_pk_add_f32 v[136:137], v[136:137], v[132:133] neg_lo:[0,1] neg_hi:[0,1]
	v_pk_fma_f32 v[148:149], v[38:39], v[136:137], v[132:133]
	v_pk_mul_f32 v[138:139], v[138:139], v[98:99] op_sel_hi:[1,0]
	v_pk_fma_f32 v[138:139], v[142:143], v[100:101], v[138:139] op_sel_hi:[1,0,1]
	v_pk_add_f32 v[138:139], v[138:139], v[134:135] neg_lo:[0,1] neg_hi:[0,1]
	v_pk_fma_f32 v[150:151], v[40:41], v[138:139], v[134:135]
	s_waitcnt lgkmcnt(0)
	v_lshlrev_b32_e32 v132, 16, v128
	v_and_b32_e32 v133, 0xffff0000, v128
	v_lshlrev_b32_e32 v134, 16, v129
	v_and_b32_e32 v135, 0xffff0000, v129
	v_lshlrev_b32_e32 v136, 16, v130
	v_and_b32_e32 v137, 0xffff0000, v130
	v_lshlrev_b32_e32 v138, 16, v131
	v_and_b32_e32 v139, 0xffff0000, v131
	s_mov_b32 s98, 0xbf60028b
	v_mul_f32_e32 v132, s98, v132
	v_mul_f32_e32 v133, s98, v133
	v_mul_f32_e32 v134, s98, v134
	v_mul_f32_e32 v135, s98, v135
	v_exp_f32_e32 v132, v132
	v_exp_f32_e32 v133, v133
	v_exp_f32_e32 v134, v134
	v_exp_f32_e32 v135, v135
	v_pk_mul_f32 v[140:141], v[102:103], v[42:43]
	v_pk_mul_f32 v[142:143], v[104:105], v[44:45]
	v_pk_mul_f32 v[106:107], v[140:141], v[140:141]
	v_pk_fma_f32 v[106:107], v[142:143], v[142:143], v[106:107]
	v_add_f32_e32 v106, v106, v107
	s_nop 1
	v_add_f32_dpp v106, v106, v106 row_ror:8 row_mask:0xf bank_mask:0xf bound_ctrl:1
	s_nop 1
	v_add_f32_dpp v106, v106, v106 row_ror:4 row_mask:0xf bank_mask:0xf bound_ctrl:1
	s_nop 1
	v_add_f32_dpp v106, v106, v106 row_ror:2 row_mask:0xf bank_mask:0xf bound_ctrl:1
	s_nop 1
	v_add_f32_dpp v106, v106, v106 row_ror:1 row_mask:0xf bank_mask:0xf bound_ctrl:1
	v_add_f32_e32 v106, 0x2b8cbccc, v106
	v_rsq_f32_e32 v106, v106
	v_pk_mul_f32 v[148:149], v[148:149], s[40:41] op_sel_hi:[1,0]
	v_pk_mul_f32 v[150:151], v[150:151], s[40:41] op_sel_hi:[1,0]
	v_pk_mul_f32 v[140:141], v[140:141], v[106:107] op_sel_hi:[1,0]
	v_pk_mul_f32 v[142:143], v[142:143], v[106:107] op_sel_hi:[1,0]
	v_pk_add_f32 v[70:71], v[136:137], -1.0 op_sel_hi:[1,0]
	v_pk_add_f32 v[72:73], v[138:139], -1.0 op_sel_hi:[1,0]
	v_pk_fma_f32 v[70:71], v[30:31], v[70:71], 1.0 op_sel_hi:[1,1,0]
	v_pk_fma_f32 v[72:73], v[32:33], v[72:73], 1.0 op_sel_hi:[1,1,0]
	v_pk_mul_f32 v[70:71], v[102:103], v[70:71]
	v_pk_mul_f32 v[72:73], v[104:105], v[72:73]
	v_pk_mul_f32 v[74:75], v[140:141], v[136:137]
	v_pk_mul_f32 v[76:77], v[142:143], v[138:139]
	ds_write_b128 v3, v[140:143] offset:0
	ds_write_b128 v3, v[132:135] offset:4096
	ds_write_b128 v3, v[74:77] offset:8192
	ds_write_b128 v3, v[70:73] offset:12288
	ds_write_b128 v3, v[144:147] offset:16384
	ds_write_b128 v4, v[148:151]
	s_waitcnt lgkmcnt(0)
	s_barrier
	s_cmp_eq_u32 s18, 2
	s_cbranch_scc1 .Lrw0_u2s0
	ds_read_b128 v[30:33], v112 offset:0
	ds_read_b128 v[34:37], v112 offset:16
	ds_read_b128 v[78:81], v112 offset:12288
	ds_read_b128 v[82:85], v112 offset:12304
	ds_read_b32 v104, v108 offset:20480
	ds_read_b128 v[38:41], v112 offset:4096
	ds_read_b128 v[42:45], v112 offset:4112
	ds_read_b128 v[70:73], v112 offset:8192
	ds_read_b128 v[74:77], v112 offset:8208
	s_waitcnt lgkmcnt(7)
	v_pk_mul_f32 v[136:137], v[22:23], v[30:31]
	v_pk_fma_f32 v[136:137], v[24:25], v[32:33], v[136:137]
	v_pk_fma_f32 v[136:137], v[26:27], v[34:35], v[136:137]
	v_pk_fma_f32 v[136:137], v[28:29], v[36:37], v[136:137]
	ds_read_b128 v[30:33], v112 offset:256
	ds_read_b128 v[34:37], v112 offset:272
	ds_read_b128 v[96:99], v112 offset:16384
	ds_read_b128 v[100:103], v112 offset:16400
	v_add_f32_e32 v140, v136, v137
	s_waitcnt lgkmcnt(8)
	v_pk_mul_f32 v[128:129], v[78:79], v[104:105] op_sel_hi:[1,0]
	v_add_f32_dpp v140, v140, v140 row_half_mirror row_mask:0xf bank_mask:0xf
	v_pk_mul_f32 v[130:131], v[80:81], v[104:105] op_sel_hi:[1,0]
	v_pk_mul_f32 v[132:133], v[82:83], v[104:105] op_sel_hi:[1,0]
	v_pk_mul_f32 v[134:135], v[84:85], v[104:105] op_sel_hi:[1,0]
	ds_read_b128 v[78:81], v112 offset:12544
	ds_read_b128 v[82:85], v112 offset:12560
	ds_read_b32 v104, v108 offset:20608
	v_add_f32_dpp v140, v140, v140 quad_perm:[1,0,3,2] row_mask:0xf bank_mask:0xf
	s_waitcnt lgkmcnt(9)
	v_pk_fma_f32 v[128:129], v[22:23], v[38:39], v[128:129]
	v_pk_fma_f32 v[130:131], v[24:25], v[40:41], v[130:131]
	v_pk_fma_f32 v[132:133], v[26:27], v[42:43], v[132:133]
	v_add_f32_dpp v140, v140, v140 quad_perm:[2,3,0,1] row_mask:0xf bank_mask:0xf
	v_pk_fma_f32 v[134:135], v[28:29], v[44:45], v[134:135]
	ds_read_b128 v[38:41], v112 offset:4352
	ds_read_b128 v[42:45], v112 offset:4368
	s_waitcnt lgkmcnt(9)
	v_pk_fma_f32 v[22:23], v[140:141], v[70:71], v[128:129] op_sel_hi:[0,1,1] neg_lo:[1,0,0] neg_hi:[1,0,0]
	v_pk_fma_f32 v[24:25], v[140:141], v[72:73], v[130:131] op_sel_hi:[0,1,1] neg_lo:[1,0,0] neg_hi:[1,0,0]
	v_pk_fma_f32 v[26:27], v[140:141], v[74:75], v[132:133] op_sel_hi:[0,1,1] neg_lo:[1,0,0] neg_hi:[1,0,0]
	v_pk_fma_f32 v[28:29], v[140:141], v[76:77], v[134:135] op_sel_hi:[0,1,1] neg_lo:[1,0,0] neg_hi:[1,0,0]
	ds_read_b128 v[70:73], v112 offset:8448
	ds_read_b128 v[74:77], v112 offset:8464
	s_waitcnt lgkmcnt(7)
	v_pk_mul_f32 v[136:137], v[22:23], v[30:31]
	v_pk_mul_f32 v[138:139], v[22:23], v[96:97]
	v_pk_fma_f32 v[136:137], v[24:25], v[32:33], v[136:137]
	v_pk_fma_f32 v[138:139], v[24:25], v[98:99], v[138:139]
	v_pk_fma_f32 v[136:137], v[26:27], v[34:35], v[136:137]
	v_pk_fma_f32 v[138:139], v[26:27], v[100:101], v[138:139]
	v_pk_fma_f32 v[136:137], v[28:29], v[36:37], v[136:137]
	v_pk_fma_f32 v[138:139], v[28:29], v[102:103], v[138:139]
	ds_read_b128 v[30:33], v112 offset:512
	ds_read_b128 v[34:37], v112 offset:528
	ds_read_b128 v[96:99], v112 offset:16640
	ds_read_b128 v[100:103], v112 offset:16656
	v_add_f32_e32 v140, v136, v137
	v_add_f32_e32 v144, v138, v139
	s_waitcnt lgkmcnt(8)
	v_pk_mul_f32 v[128:129], v[78:79], v[104:105] op_sel_hi:[1,0]
	v_add_f32_dpp v140, v140, v140 row_half_mirror row_mask:0xf bank_mask:0xf
	v_add_f32_dpp v144, v144, v144 row_half_mirror row_mask:0xf bank_mask:0xf
	v_pk_mul_f32 v[130:131], v[80:81], v[104:105] op_sel_hi:[1,0]
	v_pk_mul_f32 v[132:133], v[82:83], v[104:105] op_sel_hi:[1,0]
	v_add_f32_dpp v140, v140, v140 quad_perm:[1,0,3,2] row_mask:0xf bank_mask:0xf
	v_add_f32_dpp v144, v144, v144 quad_perm:[1,0,3,2] row_mask:0xf bank_mask:0xf
	v_pk_mul_f32 v[134:135], v[84:85], v[104:105] op_sel_hi:[1,0]
	ds_read_b128 v[78:81], v112 offset:12800
	ds_read_b128 v[82:85], v112 offset:12816
	ds_read_b32 v104, v108 offset:20736
	s_waitcnt lgkmcnt(9)
	v_pk_fma_f32 v[128:129], v[22:23], v[38:39], v[128:129]
	v_add_f32_dpp v140, v140, v140 quad_perm:[2,3,0,1] row_mask:0xf bank_mask:0xf
	v_add_f32_dpp v144, v144, v144 quad_perm:[2,3,0,1] row_mask:0xf bank_mask:0xf
	v_pk_fma_f32 v[130:131], v[24:25], v[40:41], v[130:131]
	v_pk_fma_f32 v[132:133], v[26:27], v[42:43], v[132:133]
	v_pk_fma_f32 v[134:135], v[28:29], v[44:45], v[134:135]
	ds_read_b128 v[38:41], v112 offset:4608
	ds_read_b128 v[42:45], v112 offset:4624
	s_waitcnt lgkmcnt(9)
	v_pk_fma_f32 v[22:23], v[140:141], v[70:71], v[128:129] op_sel_hi:[0,1,1] neg_lo:[1,0,0] neg_hi:[1,0,0]
	v_pk_fma_f32 v[24:25], v[140:141], v[72:73], v[130:131] op_sel_hi:[0,1,1] neg_lo:[1,0,0] neg_hi:[1,0,0]
	v_pk_fma_f32 v[26:27], v[140:141], v[74:75], v[132:133] op_sel_hi:[0,1,1] neg_lo:[1,0,0] neg_hi:[1,0,0]
	v_pk_fma_f32 v[28:29], v[140:141], v[76:77], v[134:135] op_sel_hi:[0,1,1] neg_lo:[1,0,0] neg_hi:[1,0,0]
	ds_read_b128 v[70:73], v112 offset:8704
	ds_read_b128 v[74:77], v112 offset:8720
	s_waitcnt lgkmcnt(7)
	v_pk_mul_f32 v[136:137], v[22:23], v[30:31]
	v_pk_mul_f32 v[138:139], v[22:23], v[96:97]
	v_pk_fma_f32 v[136:137], v[24:25], v[32:33], v[136:137]
	v_pk_fma_f32 v[138:139], v[24:25], v[98:99], v[138:139]
	v_pk_fma_f32 v[136:137], v[26:27], v[34:35], v[136:137]
	v_pk_fma_f32 v[138:139], v[26:27], v[100:101], v[138:139]
	v_pk_fma_f32 v[136:137], v[28:29], v[36:37], v[136:137]
	v_pk_fma_f32 v[138:139], v[28:29], v[102:103], v[138:139]
	ds_read_b128 v[30:33], v112 offset:768
	ds_read_b128 v[34:37], v112 offset:784
	ds_read_b128 v[96:99], v112 offset:16896
	ds_read_b128 v[100:103], v112 offset:16912
	v_add_f32_e32 v140, v136, v137
	v_add_f32_e32 v145, v138, v139
	s_waitcnt lgkmcnt(8)
	v_pk_mul_f32 v[128:129], v[78:79], v[104:105] op_sel_hi:[1,0]
	v_add_f32_dpp v140, v140, v140 row_half_mirror row_mask:0xf bank_mask:0xf
	v_add_f32_dpp v145, v145, v145 row_half_mirror row_mask:0xf bank_mask:0xf
	v_pk_mul_f32 v[130:131], v[80:81], v[104:105] op_sel_hi:[1,0]
	v_pk_mul_f32 v[132:133], v[82:83], v[104:105] op_sel_hi:[1,0]
	v_add_f32_dpp v140, v140, v140 quad_perm:[1,0,3,2] row_mask:0xf bank_mask:0xf
	v_add_f32_dpp v145, v145, v145 quad_perm:[1,0,3,2] row_mask:0xf bank_mask:0xf
	v_pk_mul_f32 v[134:135], v[84:85], v[104:105] op_sel_hi:[1,0]
	ds_read_b128 v[78:81], v112 offset:13056
	ds_read_b128 v[82:85], v112 offset:13072
	ds_read_b32 v104, v108 offset:20864
	s_waitcnt lgkmcnt(9)
	v_pk_fma_f32 v[128:129], v[22:23], v[38:39], v[128:129]
	v_add_f32_dpp v140, v140, v140 quad_perm:[2,3,0,1] row_mask:0xf bank_mask:0xf
	v_add_f32_dpp v145, v145, v145 quad_perm:[2,3,0,1] row_mask:0xf bank_mask:0xf
	v_pk_fma_f32 v[130:131], v[24:25], v[40:41], v[130:131]
	v_pk_fma_f32 v[132:133], v[26:27], v[42:43], v[132:133]
	v_pk_fma_f32 v[134:135], v[28:29], v[44:45], v[134:135]
	ds_read_b128 v[38:41], v112 offset:4864
	ds_read_b128 v[42:45], v112 offset:4880
	s_waitcnt lgkmcnt(9)
	v_pk_fma_f32 v[22:23], v[140:141], v[70:71], v[128:129] op_sel_hi:[0,1,1] neg_lo:[1,0,0] neg_hi:[1,0,0]
	v_pk_fma_f32 v[24:25], v[140:141], v[72:73], v[130:131] op_sel_hi:[0,1,1] neg_lo:[1,0,0] neg_hi:[1,0,0]
	v_pk_fma_f32 v[26:27], v[140:141], v[74:75], v[132:133] op_sel_hi:[0,1,1] neg_lo:[1,0,0] neg_hi:[1,0,0]
	v_pk_fma_f32 v[28:29], v[140:141], v[76:77], v[134:135] op_sel_hi:[0,1,1] neg_lo:[1,0,0] neg_hi:[1,0,0]
	ds_read_b128 v[70:73], v112 offset:8960
	ds_read_b128 v[74:77], v112 offset:8976
	s_waitcnt lgkmcnt(7)
	v_pk_mul_f32 v[136:137], v[22:23], v[30:31]
	v_pk_mul_f32 v[138:139], v[22:23], v[96:97]
	v_pk_fma_f32 v[136:137], v[24:25], v[32:33], v[136:137]
	v_pk_fma_f32 v[138:139], v[24:25], v[98:99], v[138:139]
	v_pk_fma_f32 v[136:137], v[26:27], v[34:35], v[136:137]
	v_pk_fma_f32 v[138:139], v[26:27], v[100:101], v[138:139]
	v_pk_fma_f32 v[136:137], v[28:29], v[36:37], v[136:137]
	v_pk_fma_f32 v[138:139], v[28:29], v[102:103], v[138:139]
	ds_read_b128 v[30:33], v112 offset:1024
	ds_read_b128 v[34:37], v112 offset:1040
	ds_read_b128 v[96:99], v112 offset:17152
	ds_read_b128 v[100:103], v112 offset:17168
	v_add_f32_e32 v140, v136, v137
	v_add_f32_e32 v146, v138, v139
	s_waitcnt lgkmcnt(8)
	v_pk_mul_f32 v[128:129], v[78:79], v[104:105] op_sel_hi:[1,0]
	v_add_f32_dpp v140, v140, v140 row_half_mirror row_mask:0xf bank_mask:0xf
	v_add_f32_dpp v146, v146, v146 row_half_mirror row_mask:0xf bank_mask:0xf
	v_pk_mul_f32 v[130:131], v[80:81], v[104:105] op_sel_hi:[1,0]
	v_pk_mul_f32 v[132:133], v[82:83], v[104:105] op_sel_hi:[1,0]
	v_add_f32_dpp v140, v140, v140 quad_perm:[1,0,3,2] row_mask:0xf bank_mask:0xf
	v_add_f32_dpp v146, v146, v146 quad_perm:[1,0,3,2] row_mask:0xf bank_mask:0xf
	v_pk_mul_f32 v[134:135], v[84:85], v[104:105] op_sel_hi:[1,0]
	ds_read_b128 v[78:81], v112 offset:13312
	ds_read_b128 v[82:85], v112 offset:13328
	ds_read_b32 v104, v108 offset:20992
	s_waitcnt lgkmcnt(9)
	v_pk_fma_f32 v[128:129], v[22:23], v[38:39], v[128:129]
	v_add_f32_dpp v140, v140, v140 quad_perm:[2,3,0,1] row_mask:0xf bank_mask:0xf
	v_add_f32_dpp v146, v146, v146 quad_perm:[2,3,0,1] row_mask:0xf bank_mask:0xf
	v_pk_fma_f32 v[130:131], v[24:25], v[40:41], v[130:131]
	v_pk_fma_f32 v[132:133], v[26:27], v[42:43], v[132:133]
	v_pk_fma_f32 v[134:135], v[28:29], v[44:45], v[134:135]
	ds_read_b128 v[38:41], v112 offset:5120
	ds_read_b128 v[42:45], v112 offset:5136
	s_waitcnt lgkmcnt(9)
	v_pk_fma_f32 v[22:23], v[140:141], v[70:71], v[128:129] op_sel_hi:[0,1,1] neg_lo:[1,0,0] neg_hi:[1,0,0]
	v_pk_fma_f32 v[24:25], v[140:141], v[72:73], v[130:131] op_sel_hi:[0,1,1] neg_lo:[1,0,0] neg_hi:[1,0,0]
	v_pk_fma_f32 v[26:27], v[140:141], v[74:75], v[132:133] op_sel_hi:[0,1,1] neg_lo:[1,0,0] neg_hi:[1,0,0]
	v_pk_fma_f32 v[28:29], v[140:141], v[76:77], v[134:135] op_sel_hi:[0,1,1] neg_lo:[1,0,0] neg_hi:[1,0,0]
	ds_read_b128 v[70:73], v112 offset:9216
	ds_read_b128 v[74:77], v112 offset:9232
	s_waitcnt lgkmcnt(7)
	v_pk_mul_f32 v[136:137], v[22:23], v[30:31]
	v_pk_mul_f32 v[138:139], v[22:23], v[96:97]
	v_pk_fma_f32 v[136:137], v[24:25], v[32:33], v[136:137]
	v_pk_fma_f32 v[138:139], v[24:25], v[98:99], v[138:139]
	v_pk_fma_f32 v[136:137], v[26:27], v[34:35], v[136:137]
	v_pk_fma_f32 v[138:139], v[26:27], v[100:101], v[138:139]
	v_pk_fma_f32 v[136:137], v[28:29], v[36:37], v[136:137]
	v_pk_fma_f32 v[138:139], v[28:29], v[102:103], v[138:139]
	ds_read_b128 v[30:33], v112 offset:1280
	ds_read_b128 v[34:37], v112 offset:1296
	ds_read_b128 v[96:99], v112 offset:17408
	ds_read_b128 v[100:103], v112 offset:17424
	v_add_f32_e32 v140, v136, v137
	v_add_f32_e32 v147, v138, v139
	s_waitcnt lgkmcnt(8)
	v_pk_mul_f32 v[128:129], v[78:79], v[104:105] op_sel_hi:[1,0]
	v_add_f32_dpp v140, v140, v140 row_half_mirror row_mask:0xf bank_mask:0xf
	v_add_f32_dpp v147, v147, v147 row_half_mirror row_mask:0xf bank_mask:0xf
	v_pk_mul_f32 v[130:131], v[80:81], v[104:105] op_sel_hi:[1,0]
	v_pk_mul_f32 v[132:133], v[82:83], v[104:105] op_sel_hi:[1,0]
	v_add_f32_dpp v140, v140, v140 quad_perm:[1,0,3,2] row_mask:0xf bank_mask:0xf
	v_add_f32_dpp v147, v147, v147 quad_perm:[1,0,3,2] row_mask:0xf bank_mask:0xf
	v_pk_mul_f32 v[134:135], v[84:85], v[104:105] op_sel_hi:[1,0]
	ds_read_b128 v[78:81], v112 offset:13568
	ds_read_b128 v[82:85], v112 offset:13584
	ds_read_b32 v104, v108 offset:21120
	s_waitcnt lgkmcnt(9)
	v_pk_fma_f32 v[128:129], v[22:23], v[38:39], v[128:129]
	v_add_f32_dpp v140, v140, v140 quad_perm:[2,3,0,1] row_mask:0xf bank_mask:0xf
	v_add_f32_dpp v147, v147, v147 quad_perm:[2,3,0,1] row_mask:0xf bank_mask:0xf
	v_pk_fma_f32 v[130:131], v[24:25], v[40:41], v[130:131]
	v_pk_fma_f32 v[132:133], v[26:27], v[42:43], v[132:133]
	v_pk_fma_f32 v[134:135], v[28:29], v[44:45], v[134:135]
	ds_read_b128 v[38:41], v112 offset:5376
	ds_read_b128 v[42:45], v112 offset:5392
	s_waitcnt lgkmcnt(9)
	v_pk_fma_f32 v[22:23], v[140:141], v[70:71], v[128:129] op_sel_hi:[0,1,1] neg_lo:[1,0,0] neg_hi:[1,0,0]
	v_pk_fma_f32 v[24:25], v[140:141], v[72:73], v[130:131] op_sel_hi:[0,1,1] neg_lo:[1,0,0] neg_hi:[1,0,0]
	v_pk_fma_f32 v[26:27], v[140:141], v[74:75], v[132:133] op_sel_hi:[0,1,1] neg_lo:[1,0,0] neg_hi:[1,0,0]
	v_pk_fma_f32 v[28:29], v[140:141], v[76:77], v[134:135] op_sel_hi:[0,1,1] neg_lo:[1,0,0] neg_hi:[1,0,0]
	ds_read_b128 v[70:73], v112 offset:9472
	ds_read_b128 v[74:77], v112 offset:9488
	ds_write_b128 v113, v[144:147] offset:22528
	s_waitcnt lgkmcnt(8)
	v_pk_mul_f32 v[136:137], v[22:23], v[30:31]
	v_pk_mul_f32 v[138:139], v[22:23], v[96:97]
	v_pk_fma_f32 v[136:137], v[24:25], v[32:33], v[136:137]
	v_pk_fma_f32 v[138:139], v[24:25], v[98:99], v[138:139]
	v_pk_fma_f32 v[136:137], v[26:27], v[34:35], v[136:137]
	v_pk_fma_f32 v[138:139], v[26:27], v[100:101], v[138:139]
	v_pk_fma_f32 v[136:137], v[28:29], v[36:37], v[136:137]
	v_pk_fma_f32 v[138:139], v[28:29], v[102:103], v[138:139]
	ds_read_b128 v[30:33], v112 offset:1536
	ds_read_b128 v[34:37], v112 offset:1552
	ds_read_b128 v[96:99], v112 offset:17664
	ds_read_b128 v[100:103], v112 offset:17680
	v_add_f32_e32 v140, v136, v137
	v_add_f32_e32 v144, v138, v139
	s_waitcnt lgkmcnt(9)
	v_pk_mul_f32 v[128:129], v[78:79], v[104:105] op_sel_hi:[1,0]
	v_add_f32_dpp v140, v140, v140 row_half_mirror row_mask:0xf bank_mask:0xf
	v_add_f32_dpp v144, v144, v144 row_half_mirror row_mask:0xf bank_mask:0xf
	v_pk_mul_f32 v[130:131], v[80:81], v[104:105] op_sel_hi:[1,0]
	v_pk_mul_f32 v[132:133], v[82:83], v[104:105] op_sel_hi:[1,0]
	v_add_f32_dpp v140, v140, v140 quad_perm:[1,0,3,2] row_mask:0xf bank_mask:0xf
	v_add_f32_dpp v144, v144, v144 quad_perm:[1,0,3,2] row_mask:0xf bank_mask:0xf
	v_pk_mul_f32 v[134:135], v[84:85], v[104:105] op_sel_hi:[1,0]
	ds_read_b128 v[78:81], v112 offset:13824
	ds_read_b128 v[82:85], v112 offset:13840
	ds_read_b32 v104, v108 offset:21248
	s_waitcnt lgkmcnt(10)
	v_pk_fma_f32 v[128:129], v[22:23], v[38:39], v[128:129]
	v_add_f32_dpp v140, v140, v140 quad_perm:[2,3,0,1] row_mask:0xf bank_mask:0xf
	v_add_f32_dpp v144, v144, v144 quad_perm:[2,3,0,1] row_mask:0xf bank_mask:0xf
	v_pk_fma_f32 v[130:131], v[24:25], v[40:41], v[130:131]
	v_pk_fma_f32 v[132:133], v[26:27], v[42:43], v[132:133]
	v_pk_fma_f32 v[134:135], v[28:29], v[44:45], v[134:135]
	ds_read_b128 v[38:41], v112 offset:5632
	ds_read_b128 v[42:45], v112 offset:5648
	s_waitcnt lgkmcnt(10)
	v_pk_fma_f32 v[22:23], v[140:141], v[70:71], v[128:129] op_sel_hi:[0,1,1] neg_lo:[1,0,0] neg_hi:[1,0,0]
	v_pk_fma_f32 v[24:25], v[140:141], v[72:73], v[130:131] op_sel_hi:[0,1,1] neg_lo:[1,0,0] neg_hi:[1,0,0]
	v_pk_fma_f32 v[26:27], v[140:141], v[74:75], v[132:133] op_sel_hi:[0,1,1] neg_lo:[1,0,0] neg_hi:[1,0,0]
	v_pk_fma_f32 v[28:29], v[140:141], v[76:77], v[134:135] op_sel_hi:[0,1,1] neg_lo:[1,0,0] neg_hi:[1,0,0]
	ds_read_b128 v[70:73], v112 offset:9728
	ds_read_b128 v[74:77], v112 offset:9744
	s_waitcnt lgkmcnt(7)
	v_pk_mul_f32 v[136:137], v[22:23], v[30:31]
	v_pk_mul_f32 v[138:139], v[22:23], v[96:97]
	v_pk_fma_f32 v[136:137], v[24:25], v[32:33], v[136:137]
	v_pk_fma_f32 v[138:139], v[24:25], v[98:99], v[138:139]
	v_pk_fma_f32 v[136:137], v[26:27], v[34:35], v[136:137]
	v_pk_fma_f32 v[138:139], v[26:27], v[100:101], v[138:139]
	v_pk_fma_f32 v[136:137], v[28:29], v[36:37], v[136:137]
	v_pk_fma_f32 v[138:139], v[28:29], v[102:103], v[138:139]
	ds_read_b128 v[30:33], v112 offset:1792
	ds_read_b128 v[34:37], v112 offset:1808
	ds_read_b128 v[96:99], v112 offset:17920
	ds_read_b128 v[100:103], v112 offset:17936
	v_add_f32_e32 v140, v136, v137
	v_add_f32_e32 v145, v138, v139
	s_waitcnt lgkmcnt(8)
	v_pk_mul_f32 v[128:129], v[78:79], v[104:105] op_sel_hi:[1,0]
	v_add_f32_dpp v140, v140, v140 row_half_mirror row_mask:0xf bank_mask:0xf
	v_add_f32_dpp v145, v145, v145 row_half_mirror row_mask:0xf bank_mask:0xf
	v_pk_mul_f32 v[130:131], v[80:81], v[104:105] op_sel_hi:[1,0]
	v_pk_mul_f32 v[132:133], v[82:83], v[104:105] op_sel_hi:[1,0]
	v_add_f32_dpp v140, v140, v140 quad_perm:[1,0,3,2] row_mask:0xf bank_mask:0xf
	v_add_f32_dpp v145, v145, v145 quad_perm:[1,0,3,2] row_mask:0xf bank_mask:0xf
	v_pk_mul_f32 v[134:135], v[84:85], v[104:105] op_sel_hi:[1,0]
	ds_read_b128 v[78:81], v112 offset:14080
	ds_read_b128 v[82:85], v112 offset:14096
	ds_read_b32 v104, v108 offset:21376
	s_waitcnt lgkmcnt(9)
	v_pk_fma_f32 v[128:129], v[22:23], v[38:39], v[128:129]
	v_add_f32_dpp v140, v140, v140 quad_perm:[2,3,0,1] row_mask:0xf bank_mask:0xf
	v_add_f32_dpp v145, v145, v145 quad_perm:[2,3,0,1] row_mask:0xf bank_mask:0xf
	v_pk_fma_f32 v[130:131], v[24:25], v[40:41], v[130:131]
	v_pk_fma_f32 v[132:133], v[26:27], v[42:43], v[132:133]
	v_pk_fma_f32 v[134:135], v[28:29], v[44:45], v[134:135]
	ds_read_b128 v[38:41], v112 offset:5888
	ds_read_b128 v[42:45], v112 offset:5904
	s_waitcnt lgkmcnt(9)
	v_pk_fma_f32 v[22:23], v[140:141], v[70:71], v[128:129] op_sel_hi:[0,1,1] neg_lo:[1,0,0] neg_hi:[1,0,0]
	v_pk_fma_f32 v[24:25], v[140:141], v[72:73], v[130:131] op_sel_hi:[0,1,1] neg_lo:[1,0,0] neg_hi:[1,0,0]
	v_pk_fma_f32 v[26:27], v[140:141], v[74:75], v[132:133] op_sel_hi:[0,1,1] neg_lo:[1,0,0] neg_hi:[1,0,0]
	v_pk_fma_f32 v[28:29], v[140:141], v[76:77], v[134:135] op_sel_hi:[0,1,1] neg_lo:[1,0,0] neg_hi:[1,0,0]
	ds_read_b128 v[70:73], v112 offset:9984
	ds_read_b128 v[74:77], v112 offset:10000
	s_waitcnt lgkmcnt(7)
	v_pk_mul_f32 v[136:137], v[22:23], v[30:31]
	v_pk_mul_f32 v[138:139], v[22:23], v[96:97]
	v_pk_fma_f32 v[136:137], v[24:25], v[32:33], v[136:137]
	v_pk_fma_f32 v[138:139], v[24:25], v[98:99], v[138:139]
	v_pk_fma_f32 v[136:137], v[26:27], v[34:35], v[136:137]
	v_pk_fma_f32 v[138:139], v[26:27], v[100:101], v[138:139]
	v_pk_fma_f32 v[136:137], v[28:29], v[36:37], v[136:137]
	v_pk_fma_f32 v[138:139], v[28:29], v[102:103], v[138:139]
	ds_read_b128 v[30:33], v112 offset:2048
	ds_read_b128 v[34:37], v112 offset:2064
	ds_read_b128 v[96:99], v112 offset:18176
	ds_read_b128 v[100:103], v112 offset:18192
	v_add_f32_e32 v140, v136, v137
	v_add_f32_e32 v146, v138, v139
	s_waitcnt lgkmcnt(8)
	v_pk_mul_f32 v[128:129], v[78:79], v[104:105] op_sel_hi:[1,0]
	v_add_f32_dpp v140, v140, v140 row_half_mirror row_mask:0xf bank_mask:0xf
	v_add_f32_dpp v146, v146, v146 row_half_mirror row_mask:0xf bank_mask:0xf
	v_pk_mul_f32 v[130:131], v[80:81], v[104:105] op_sel_hi:[1,0]
	v_pk_mul_f32 v[132:133], v[82:83], v[104:105] op_sel_hi:[1,0]
	v_add_f32_dpp v140, v140, v140 quad_perm:[1,0,3,2] row_mask:0xf bank_mask:0xf
	v_add_f32_dpp v146, v146, v146 quad_perm:[1,0,3,2] row_mask:0xf bank_mask:0xf
	v_pk_mul_f32 v[134:135], v[84:85], v[104:105] op_sel_hi:[1,0]
	ds_read_b128 v[78:81], v112 offset:14336
	ds_read_b128 v[82:85], v112 offset:14352
	ds_read_b32 v104, v108 offset:21504
	s_waitcnt lgkmcnt(9)
	v_pk_fma_f32 v[128:129], v[22:23], v[38:39], v[128:129]
	v_add_f32_dpp v140, v140, v140 quad_perm:[2,3,0,1] row_mask:0xf bank_mask:0xf
	v_add_f32_dpp v146, v146, v146 quad_perm:[2,3,0,1] row_mask:0xf bank_mask:0xf
	v_pk_fma_f32 v[130:131], v[24:25], v[40:41], v[130:131]
	v_pk_fma_f32 v[132:133], v[26:27], v[42:43], v[132:133]
	v_pk_fma_f32 v[134:135], v[28:29], v[44:45], v[134:135]
	ds_read_b128 v[38:41], v112 offset:6144
	ds_read_b128 v[42:45], v112 offset:6160
	s_waitcnt lgkmcnt(9)
	v_pk_fma_f32 v[22:23], v[140:141], v[70:71], v[128:129] op_sel_hi:[0,1,1] neg_lo:[1,0,0] neg_hi:[1,0,0]
	v_pk_fma_f32 v[24:25], v[140:141], v[72:73], v[130:131] op_sel_hi:[0,1,1] neg_lo:[1,0,0] neg_hi:[1,0,0]
	v_pk_fma_f32 v[26:27], v[140:141], v[74:75], v[132:133] op_sel_hi:[0,1,1] neg_lo:[1,0,0] neg_hi:[1,0,0]
	v_pk_fma_f32 v[28:29], v[140:141], v[76:77], v[134:135] op_sel_hi:[0,1,1] neg_lo:[1,0,0] neg_hi:[1,0,0]
	ds_read_b128 v[70:73], v112 offset:10240
	ds_read_b128 v[74:77], v112 offset:10256
	s_waitcnt lgkmcnt(7)
	v_pk_mul_f32 v[136:137], v[22:23], v[30:31]
	v_pk_mul_f32 v[138:139], v[22:23], v[96:97]
	v_pk_fma_f32 v[136:137], v[24:25], v[32:33], v[136:137]
	v_pk_fma_f32 v[138:139], v[24:25], v[98:99], v[138:139]
	v_pk_fma_f32 v[136:137], v[26:27], v[34:35], v[136:137]
	v_pk_fma_f32 v[138:139], v[26:27], v[100:101], v[138:139]
	v_pk_fma_f32 v[136:137], v[28:29], v[36:37], v[136:137]
	v_pk_fma_f32 v[138:139], v[28:29], v[102:103], v[138:139]
	ds_read_b128 v[30:33], v112 offset:2304
	ds_read_b128 v[34:37], v112 offset:2320
	ds_read_b128 v[96:99], v112 offset:18432
	ds_read_b128 v[100:103], v112 offset:18448
	v_add_f32_e32 v140, v136, v137
	v_add_f32_e32 v147, v138, v139
	s_waitcnt lgkmcnt(8)
	v_pk_mul_f32 v[128:129], v[78:79], v[104:105] op_sel_hi:[1,0]
	v_add_f32_dpp v140, v140, v140 row_half_mirror row_mask:0xf bank_mask:0xf
	v_add_f32_dpp v147, v147, v147 row_half_mirror row_mask:0xf bank_mask:0xf
	v_pk_mul_f32 v[130:131], v[80:81], v[104:105] op_sel_hi:[1,0]
	v_pk_mul_f32 v[132:133], v[82:83], v[104:105] op_sel_hi:[1,0]
	v_add_f32_dpp v140, v140, v140 quad_perm:[1,0,3,2] row_mask:0xf bank_mask:0xf
	v_add_f32_dpp v147, v147, v147 quad_perm:[1,0,3,2] row_mask:0xf bank_mask:0xf
	v_pk_mul_f32 v[134:135], v[84:85], v[104:105] op_sel_hi:[1,0]
	ds_read_b128 v[78:81], v112 offset:14592
	ds_read_b128 v[82:85], v112 offset:14608
	ds_read_b32 v104, v108 offset:21632
	s_waitcnt lgkmcnt(9)
	v_pk_fma_f32 v[128:129], v[22:23], v[38:39], v[128:129]
	v_add_f32_dpp v140, v140, v140 quad_perm:[2,3,0,1] row_mask:0xf bank_mask:0xf
	v_add_f32_dpp v147, v147, v147 quad_perm:[2,3,0,1] row_mask:0xf bank_mask:0xf
	v_pk_fma_f32 v[130:131], v[24:25], v[40:41], v[130:131]
	v_pk_fma_f32 v[132:133], v[26:27], v[42:43], v[132:133]
	v_pk_fma_f32 v[134:135], v[28:29], v[44:45], v[134:135]
	ds_read_b128 v[38:41], v112 offset:6400
	ds_read_b128 v[42:45], v112 offset:6416
	s_waitcnt lgkmcnt(9)
	v_pk_fma_f32 v[22:23], v[140:141], v[70:71], v[128:129] op_sel_hi:[0,1,1] neg_lo:[1,0,0] neg_hi:[1,0,0]
	v_pk_fma_f32 v[24:25], v[140:141], v[72:73], v[130:131] op_sel_hi:[0,1,1] neg_lo:[1,0,0] neg_hi:[1,0,0]
	v_pk_fma_f32 v[26:27], v[140:141], v[74:75], v[132:133] op_sel_hi:[0,1,1] neg_lo:[1,0,0] neg_hi:[1,0,0]
	v_pk_fma_f32 v[28:29], v[140:141], v[76:77], v[134:135] op_sel_hi:[0,1,1] neg_lo:[1,0,0] neg_hi:[1,0,0]
	ds_read_b128 v[70:73], v112 offset:10496
	ds_read_b128 v[74:77], v112 offset:10512
	ds_write_b128 v113, v[144:147] offset:22544
	s_waitcnt lgkmcnt(8)
	v_pk_mul_f32 v[136:137], v[22:23], v[30:31]
	v_pk_mul_f32 v[138:139], v[22:23], v[96:97]
	v_pk_fma_f32 v[136:137], v[24:25], v[32:33], v[136:137]
	v_pk_fma_f32 v[138:139], v[24:25], v[98:99], v[138:139]
	v_pk_fma_f32 v[136:137], v[26:27], v[34:35], v[136:137]
	v_pk_fma_f32 v[138:139], v[26:27], v[100:101], v[138:139]
	v_pk_fma_f32 v[136:137], v[28:29], v[36:37], v[136:137]
	v_pk_fma_f32 v[138:139], v[28:29], v[102:103], v[138:139]
	ds_read_b128 v[30:33], v112 offset:2560
	ds_read_b128 v[34:37], v112 offset:2576
	ds_read_b128 v[96:99], v112 offset:18688
	ds_read_b128 v[100:103], v112 offset:18704
	v_add_f32_e32 v140, v136, v137
	v_add_f32_e32 v144, v138, v139
	s_waitcnt lgkmcnt(9)
	v_pk_mul_f32 v[128:129], v[78:79], v[104:105] op_sel_hi:[1,0]
	v_add_f32_dpp v140, v140, v140 row_half_mirror row_mask:0xf bank_mask:0xf
	v_add_f32_dpp v144, v144, v144 row_half_mirror row_mask:0xf bank_mask:0xf
	v_pk_mul_f32 v[130:131], v[80:81], v[104:105] op_sel_hi:[1,0]
	v_pk_mul_f32 v[132:133], v[82:83], v[104:105] op_sel_hi:[1,0]
	v_add_f32_dpp v140, v140, v140 quad_perm:[1,0,3,2] row_mask:0xf bank_mask:0xf
	v_add_f32_dpp v144, v144, v144 quad_perm:[1,0,3,2] row_mask:0xf bank_mask:0xf
	v_pk_mul_f32 v[134:135], v[84:85], v[104:105] op_sel_hi:[1,0]
	ds_read_b128 v[78:81], v112 offset:14848
	ds_read_b128 v[82:85], v112 offset:14864
	ds_read_b32 v104, v108 offset:21760
	s_waitcnt lgkmcnt(10)
	v_pk_fma_f32 v[128:129], v[22:23], v[38:39], v[128:129]
	v_add_f32_dpp v140, v140, v140 quad_perm:[2,3,0,1] row_mask:0xf bank_mask:0xf
	v_add_f32_dpp v144, v144, v144 quad_perm:[2,3,0,1] row_mask:0xf bank_mask:0xf
	v_pk_fma_f32 v[130:131], v[24:25], v[40:41], v[130:131]
	v_pk_fma_f32 v[132:133], v[26:27], v[42:43], v[132:133]
	v_pk_fma_f32 v[134:135], v[28:29], v[44:45], v[134:135]
	ds_read_b128 v[38:41], v112 offset:6656
	ds_read_b128 v[42:45], v112 offset:6672
	s_waitcnt lgkmcnt(10)
	v_pk_fma_f32 v[22:23], v[140:141], v[70:71], v[128:129] op_sel_hi:[0,1,1] neg_lo:[1,0,0] neg_hi:[1,0,0]
	v_pk_fma_f32 v[24:25], v[140:141], v[72:73], v[130:131] op_sel_hi:[0,1,1] neg_lo:[1,0,0] neg_hi:[1,0,0]
	v_pk_fma_f32 v[26:27], v[140:141], v[74:75], v[132:133] op_sel_hi:[0,1,1] neg_lo:[1,0,0] neg_hi:[1,0,0]
	v_pk_fma_f32 v[28:29], v[140:141], v[76:77], v[134:135] op_sel_hi:[0,1,1] neg_lo:[1,0,0] neg_hi:[1,0,0]
	ds_read_b128 v[70:73], v112 offset:10752
	ds_read_b128 v[74:77], v112 offset:10768
	s_waitcnt lgkmcnt(7)
	v_pk_mul_f32 v[136:137], v[22:23], v[30:31]
	v_pk_mul_f32 v[138:139], v[22:23], v[96:97]
	v_pk_fma_f32 v[136:137], v[24:25], v[32:33], v[136:137]
	v_pk_fma_f32 v[138:139], v[24:25], v[98:99], v[138:139]
	v_pk_fma_f32 v[136:137], v[26:27], v[34:35], v[136:137]
	v_pk_fma_f32 v[138:139], v[26:27], v[100:101], v[138:139]
	v_pk_fma_f32 v[136:137], v[28:29], v[36:37], v[136:137]
	v_pk_fma_f32 v[138:139], v[28:29], v[102:103], v[138:139]
	ds_read_b128 v[30:33], v112 offset:2816
	ds_read_b128 v[34:37], v112 offset:2832
	ds_read_b128 v[96:99], v112 offset:18944
	ds_read_b128 v[100:103], v112 offset:18960
	v_add_f32_e32 v140, v136, v137
	v_add_f32_e32 v145, v138, v139
	s_waitcnt lgkmcnt(8)
	v_pk_mul_f32 v[128:129], v[78:79], v[104:105] op_sel_hi:[1,0]
	v_add_f32_dpp v140, v140, v140 row_half_mirror row_mask:0xf bank_mask:0xf
	v_add_f32_dpp v145, v145, v145 row_half_mirror row_mask:0xf bank_mask:0xf
	v_pk_mul_f32 v[130:131], v[80:81], v[104:105] op_sel_hi:[1,0]
	v_pk_mul_f32 v[132:133], v[82:83], v[104:105] op_sel_hi:[1,0]
	v_add_f32_dpp v140, v140, v140 quad_perm:[1,0,3,2] row_mask:0xf bank_mask:0xf
	v_add_f32_dpp v145, v145, v145 quad_perm:[1,0,3,2] row_mask:0xf bank_mask:0xf
	v_pk_mul_f32 v[134:135], v[84:85], v[104:105] op_sel_hi:[1,0]
	ds_read_b128 v[78:81], v112 offset:15104
	ds_read_b128 v[82:85], v112 offset:15120
	ds_read_b32 v104, v108 offset:21888
	s_waitcnt lgkmcnt(9)
	v_pk_fma_f32 v[128:129], v[22:23], v[38:39], v[128:129]
	v_add_f32_dpp v140, v140, v140 quad_perm:[2,3,0,1] row_mask:0xf bank_mask:0xf
	v_add_f32_dpp v145, v145, v145 quad_perm:[2,3,0,1] row_mask:0xf bank_mask:0xf
	v_pk_fma_f32 v[130:131], v[24:25], v[40:41], v[130:131]
	v_pk_fma_f32 v[132:133], v[26:27], v[42:43], v[132:133]
	v_pk_fma_f32 v[134:135], v[28:29], v[44:45], v[134:135]
	ds_read_b128 v[38:41], v112 offset:6912
	ds_read_b128 v[42:45], v112 offset:6928
	s_waitcnt lgkmcnt(9)
	v_pk_fma_f32 v[22:23], v[140:141], v[70:71], v[128:129] op_sel_hi:[0,1,1] neg_lo:[1,0,0] neg_hi:[1,0,0]
	v_pk_fma_f32 v[24:25], v[140:141], v[72:73], v[130:131] op_sel_hi:[0,1,1] neg_lo:[1,0,0] neg_hi:[1,0,0]
	v_pk_fma_f32 v[26:27], v[140:141], v[74:75], v[132:133] op_sel_hi:[0,1,1] neg_lo:[1,0,0] neg_hi:[1,0,0]
	v_pk_fma_f32 v[28:29], v[140:141], v[76:77], v[134:135] op_sel_hi:[0,1,1] neg_lo:[1,0,0] neg_hi:[1,0,0]
	ds_read_b128 v[70:73], v112 offset:11008
	ds_read_b128 v[74:77], v112 offset:11024
	s_waitcnt lgkmcnt(7)
	v_pk_mul_f32 v[136:137], v[22:23], v[30:31]
	v_pk_mul_f32 v[138:139], v[22:23], v[96:97]
	v_pk_fma_f32 v[136:137], v[24:25], v[32:33], v[136:137]
	v_pk_fma_f32 v[138:139], v[24:25], v[98:99], v[138:139]
	v_pk_fma_f32 v[136:137], v[26:27], v[34:35], v[136:137]
	v_pk_fma_f32 v[138:139], v[26:27], v[100:101], v[138:139]
	v_pk_fma_f32 v[136:137], v[28:29], v[36:37], v[136:137]
	v_pk_fma_f32 v[138:139], v[28:29], v[102:103], v[138:139]
	ds_read_b128 v[30:33], v112 offset:3072
	ds_read_b128 v[34:37], v112 offset:3088
	ds_read_b128 v[96:99], v112 offset:19200
	ds_read_b128 v[100:103], v112 offset:19216
	v_add_f32_e32 v140, v136, v137
	v_add_f32_e32 v146, v138, v139
	s_waitcnt lgkmcnt(8)
	v_pk_mul_f32 v[128:129], v[78:79], v[104:105] op_sel_hi:[1,0]
	v_add_f32_dpp v140, v140, v140 row_half_mirror row_mask:0xf bank_mask:0xf
	v_add_f32_dpp v146, v146, v146 row_half_mirror row_mask:0xf bank_mask:0xf
	v_pk_mul_f32 v[130:131], v[80:81], v[104:105] op_sel_hi:[1,0]
	v_pk_mul_f32 v[132:133], v[82:83], v[104:105] op_sel_hi:[1,0]
	v_add_f32_dpp v140, v140, v140 quad_perm:[1,0,3,2] row_mask:0xf bank_mask:0xf
	v_add_f32_dpp v146, v146, v146 quad_perm:[1,0,3,2] row_mask:0xf bank_mask:0xf
	v_pk_mul_f32 v[134:135], v[84:85], v[104:105] op_sel_hi:[1,0]
	ds_read_b128 v[78:81], v112 offset:15360
	ds_read_b128 v[82:85], v112 offset:15376
	ds_read_b32 v104, v108 offset:22016
	s_waitcnt lgkmcnt(9)
	v_pk_fma_f32 v[128:129], v[22:23], v[38:39], v[128:129]
	v_add_f32_dpp v140, v140, v140 quad_perm:[2,3,0,1] row_mask:0xf bank_mask:0xf
	v_add_f32_dpp v146, v146, v146 quad_perm:[2,3,0,1] row_mask:0xf bank_mask:0xf
	v_pk_fma_f32 v[130:131], v[24:25], v[40:41], v[130:131]
	v_pk_fma_f32 v[132:133], v[26:27], v[42:43], v[132:133]
	v_pk_fma_f32 v[134:135], v[28:29], v[44:45], v[134:135]
	ds_read_b128 v[38:41], v112 offset:7168
	ds_read_b128 v[42:45], v112 offset:7184
	s_waitcnt lgkmcnt(9)
	v_pk_fma_f32 v[22:23], v[140:141], v[70:71], v[128:129] op_sel_hi:[0,1,1] neg_lo:[1,0,0] neg_hi:[1,0,0]
	v_pk_fma_f32 v[24:25], v[140:141], v[72:73], v[130:131] op_sel_hi:[0,1,1] neg_lo:[1,0,0] neg_hi:[1,0,0]
	v_pk_fma_f32 v[26:27], v[140:141], v[74:75], v[132:133] op_sel_hi:[0,1,1] neg_lo:[1,0,0] neg_hi:[1,0,0]
	v_pk_fma_f32 v[28:29], v[140:141], v[76:77], v[134:135] op_sel_hi:[0,1,1] neg_lo:[1,0,0] neg_hi:[1,0,0]
	ds_read_b128 v[70:73], v112 offset:11264
	ds_read_b128 v[74:77], v112 offset:11280
	s_waitcnt lgkmcnt(7)
	v_pk_mul_f32 v[136:137], v[22:23], v[30:31]
	v_pk_mul_f32 v[138:139], v[22:23], v[96:97]
	v_pk_fma_f32 v[136:137], v[24:25], v[32:33], v[136:137]
	v_pk_fma_f32 v[138:139], v[24:25], v[98:99], v[138:139]
	v_pk_fma_f32 v[136:137], v[26:27], v[34:35], v[136:137]
	v_pk_fma_f32 v[138:139], v[26:27], v[100:101], v[138:139]
	v_pk_fma_f32 v[136:137], v[28:29], v[36:37], v[136:137]
	v_pk_fma_f32 v[138:139], v[28:29], v[102:103], v[138:139]
	ds_read_b128 v[30:33], v112 offset:3328
	ds_read_b128 v[34:37], v112 offset:3344
	ds_read_b128 v[96:99], v112 offset:19456
	ds_read_b128 v[100:103], v112 offset:19472
	v_add_f32_e32 v140, v136, v137
	v_add_f32_e32 v147, v138, v139
	s_waitcnt lgkmcnt(8)
	v_pk_mul_f32 v[128:129], v[78:79], v[104:105] op_sel_hi:[1,0]
	v_add_f32_dpp v140, v140, v140 row_half_mirror row_mask:0xf bank_mask:0xf
	v_add_f32_dpp v147, v147, v147 row_half_mirror row_mask:0xf bank_mask:0xf
	v_pk_mul_f32 v[130:131], v[80:81], v[104:105] op_sel_hi:[1,0]
	v_pk_mul_f32 v[132:133], v[82:83], v[104:105] op_sel_hi:[1,0]
	v_add_f32_dpp v140, v140, v140 quad_perm:[1,0,3,2] row_mask:0xf bank_mask:0xf
	v_add_f32_dpp v147, v147, v147 quad_perm:[1,0,3,2] row_mask:0xf bank_mask:0xf
	v_pk_mul_f32 v[134:135], v[84:85], v[104:105] op_sel_hi:[1,0]
	ds_read_b128 v[78:81], v112 offset:15616
	ds_read_b128 v[82:85], v112 offset:15632
	ds_read_b32 v104, v108 offset:22144
	s_waitcnt lgkmcnt(9)
	v_pk_fma_f32 v[128:129], v[22:23], v[38:39], v[128:129]
	v_add_f32_dpp v140, v140, v140 quad_perm:[2,3,0,1] row_mask:0xf bank_mask:0xf
	v_add_f32_dpp v147, v147, v147 quad_perm:[2,3,0,1] row_mask:0xf bank_mask:0xf
	v_pk_fma_f32 v[130:131], v[24:25], v[40:41], v[130:131]
	v_pk_fma_f32 v[132:133], v[26:27], v[42:43], v[132:133]
	v_pk_fma_f32 v[134:135], v[28:29], v[44:45], v[134:135]
	ds_read_b128 v[38:41], v112 offset:7424
	ds_read_b128 v[42:45], v112 offset:7440
	s_waitcnt lgkmcnt(9)
	v_pk_fma_f32 v[22:23], v[140:141], v[70:71], v[128:129] op_sel_hi:[0,1,1] neg_lo:[1,0,0] neg_hi:[1,0,0]
	v_pk_fma_f32 v[24:25], v[140:141], v[72:73], v[130:131] op_sel_hi:[0,1,1] neg_lo:[1,0,0] neg_hi:[1,0,0]
	v_pk_fma_f32 v[26:27], v[140:141], v[74:75], v[132:133] op_sel_hi:[0,1,1] neg_lo:[1,0,0] neg_hi:[1,0,0]
	v_pk_fma_f32 v[28:29], v[140:141], v[76:77], v[134:135] op_sel_hi:[0,1,1] neg_lo:[1,0,0] neg_hi:[1,0,0]
	ds_read_b128 v[70:73], v112 offset:11520
	ds_read_b128 v[74:77], v112 offset:11536
	ds_write_b128 v113, v[144:147] offset:22560
	s_waitcnt lgkmcnt(8)
	v_pk_mul_f32 v[136:137], v[22:23], v[30:31]
	v_pk_mul_f32 v[138:139], v[22:23], v[96:97]
	v_pk_fma_f32 v[136:137], v[24:25], v[32:33], v[136:137]
	v_pk_fma_f32 v[138:139], v[24:25], v[98:99], v[138:139]
	v_pk_fma_f32 v[136:137], v[26:27], v[34:35], v[136:137]
	v_pk_fma_f32 v[138:139], v[26:27], v[100:101], v[138:139]
	v_pk_fma_f32 v[136:137], v[28:29], v[36:37], v[136:137]
	v_pk_fma_f32 v[138:139], v[28:29], v[102:103], v[138:139]
	ds_read_b128 v[30:33], v112 offset:3584
	ds_read_b128 v[34:37], v112 offset:3600
	ds_read_b128 v[96:99], v112 offset:19712
	ds_read_b128 v[100:103], v112 offset:19728
	v_add_f32_e32 v140, v136, v137
	v_add_f32_e32 v144, v138, v139
	s_waitcnt lgkmcnt(9)
	v_pk_mul_f32 v[128:129], v[78:79], v[104:105] op_sel_hi:[1,0]
	v_add_f32_dpp v140, v140, v140 row_half_mirror row_mask:0xf bank_mask:0xf
	v_add_f32_dpp v144, v144, v144 row_half_mirror row_mask:0xf bank_mask:0xf
	v_pk_mul_f32 v[130:131], v[80:81], v[104:105] op_sel_hi:[1,0]
	v_pk_mul_f32 v[132:133], v[82:83], v[104:105] op_sel_hi:[1,0]
	v_add_f32_dpp v140, v140, v140 quad_perm:[1,0,3,2] row_mask:0xf bank_mask:0xf
	v_add_f32_dpp v144, v144, v144 quad_perm:[1,0,3,2] row_mask:0xf bank_mask:0xf
	v_pk_mul_f32 v[134:135], v[84:85], v[104:105] op_sel_hi:[1,0]
	ds_read_b128 v[78:81], v112 offset:15872
	ds_read_b128 v[82:85], v112 offset:15888
	ds_read_b32 v104, v108 offset:22272
	s_waitcnt lgkmcnt(10)
	v_pk_fma_f32 v[128:129], v[22:23], v[38:39], v[128:129]
	v_add_f32_dpp v140, v140, v140 quad_perm:[2,3,0,1] row_mask:0xf bank_mask:0xf
	v_add_f32_dpp v144, v144, v144 quad_perm:[2,3,0,1] row_mask:0xf bank_mask:0xf
	v_pk_fma_f32 v[130:131], v[24:25], v[40:41], v[130:131]
	v_pk_fma_f32 v[132:133], v[26:27], v[42:43], v[132:133]
	v_pk_fma_f32 v[134:135], v[28:29], v[44:45], v[134:135]
	ds_read_b128 v[38:41], v112 offset:7680
	ds_read_b128 v[42:45], v112 offset:7696
	s_waitcnt lgkmcnt(10)
	v_pk_fma_f32 v[22:23], v[140:141], v[70:71], v[128:129] op_sel_hi:[0,1,1] neg_lo:[1,0,0] neg_hi:[1,0,0]
	v_pk_fma_f32 v[24:25], v[140:141], v[72:73], v[130:131] op_sel_hi:[0,1,1] neg_lo:[1,0,0] neg_hi:[1,0,0]
	v_pk_fma_f32 v[26:27], v[140:141], v[74:75], v[132:133] op_sel_hi:[0,1,1] neg_lo:[1,0,0] neg_hi:[1,0,0]
	v_pk_fma_f32 v[28:29], v[140:141], v[76:77], v[134:135] op_sel_hi:[0,1,1] neg_lo:[1,0,0] neg_hi:[1,0,0]
	ds_read_b128 v[70:73], v112 offset:11776
	ds_read_b128 v[74:77], v112 offset:11792
	s_waitcnt lgkmcnt(7)
	v_pk_mul_f32 v[136:137], v[22:23], v[30:31]
	v_pk_mul_f32 v[138:139], v[22:23], v[96:97]
	v_pk_fma_f32 v[136:137], v[24:25], v[32:33], v[136:137]
	v_pk_fma_f32 v[138:139], v[24:25], v[98:99], v[138:139]
	v_pk_fma_f32 v[136:137], v[26:27], v[34:35], v[136:137]
	v_pk_fma_f32 v[138:139], v[26:27], v[100:101], v[138:139]
	v_pk_fma_f32 v[136:137], v[28:29], v[36:37], v[136:137]
	v_pk_fma_f32 v[138:139], v[28:29], v[102:103], v[138:139]
	ds_read_b128 v[30:33], v112 offset:3840
	ds_read_b128 v[34:37], v112 offset:3856
	ds_read_b128 v[96:99], v112 offset:19968
	ds_read_b128 v[100:103], v112 offset:19984
	v_add_f32_e32 v140, v136, v137
	v_add_f32_e32 v145, v138, v139
	s_waitcnt lgkmcnt(8)
	v_pk_mul_f32 v[128:129], v[78:79], v[104:105] op_sel_hi:[1,0]
	v_add_f32_dpp v140, v140, v140 row_half_mirror row_mask:0xf bank_mask:0xf
	v_add_f32_dpp v145, v145, v145 row_half_mirror row_mask:0xf bank_mask:0xf
	v_pk_mul_f32 v[130:131], v[80:81], v[104:105] op_sel_hi:[1,0]
	v_pk_mul_f32 v[132:133], v[82:83], v[104:105] op_sel_hi:[1,0]
	v_add_f32_dpp v140, v140, v140 quad_perm:[1,0,3,2] row_mask:0xf bank_mask:0xf
	v_add_f32_dpp v145, v145, v145 quad_perm:[1,0,3,2] row_mask:0xf bank_mask:0xf
	v_pk_mul_f32 v[134:135], v[84:85], v[104:105] op_sel_hi:[1,0]
	ds_read_b128 v[78:81], v112 offset:16128
	ds_read_b128 v[82:85], v112 offset:16144
	ds_read_b32 v104, v108 offset:22400
	s_waitcnt lgkmcnt(9)
	v_pk_fma_f32 v[128:129], v[22:23], v[38:39], v[128:129]
	v_add_f32_dpp v140, v140, v140 quad_perm:[2,3,0,1] row_mask:0xf bank_mask:0xf
	v_add_f32_dpp v145, v145, v145 quad_perm:[2,3,0,1] row_mask:0xf bank_mask:0xf
	v_pk_fma_f32 v[130:131], v[24:25], v[40:41], v[130:131]
	v_pk_fma_f32 v[132:133], v[26:27], v[42:43], v[132:133]
	v_pk_fma_f32 v[134:135], v[28:29], v[44:45], v[134:135]
	ds_read_b128 v[38:41], v112 offset:7936
	ds_read_b128 v[42:45], v112 offset:7952
	s_waitcnt lgkmcnt(9)
	v_pk_fma_f32 v[22:23], v[140:141], v[70:71], v[128:129] op_sel_hi:[0,1,1] neg_lo:[1,0,0] neg_hi:[1,0,0]
	v_pk_fma_f32 v[24:25], v[140:141], v[72:73], v[130:131] op_sel_hi:[0,1,1] neg_lo:[1,0,0] neg_hi:[1,0,0]
	v_pk_fma_f32 v[26:27], v[140:141], v[74:75], v[132:133] op_sel_hi:[0,1,1] neg_lo:[1,0,0] neg_hi:[1,0,0]
	v_pk_fma_f32 v[28:29], v[140:141], v[76:77], v[134:135] op_sel_hi:[0,1,1] neg_lo:[1,0,0] neg_hi:[1,0,0]
	ds_read_b128 v[70:73], v112 offset:12032
	ds_read_b128 v[74:77], v112 offset:12048
	s_waitcnt lgkmcnt(7)
	v_pk_mul_f32 v[136:137], v[22:23], v[30:31]
	v_pk_mul_f32 v[138:139], v[22:23], v[96:97]
	v_pk_fma_f32 v[136:137], v[24:25], v[32:33], v[136:137]
	v_pk_fma_f32 v[138:139], v[24:25], v[98:99], v[138:139]
	v_pk_fma_f32 v[136:137], v[26:27], v[34:35], v[136:137]
	v_pk_fma_f32 v[138:139], v[26:27], v[100:101], v[138:139]
	v_pk_fma_f32 v[136:137], v[28:29], v[36:37], v[136:137]
	v_pk_fma_f32 v[138:139], v[28:29], v[102:103], v[138:139]
	ds_read_b128 v[96:99], v112 offset:20224
	ds_read_b128 v[100:103], v112 offset:20240
	v_add_f32_e32 v140, v136, v137
	v_add_f32_e32 v146, v138, v139
	s_waitcnt lgkmcnt(6)
	v_pk_mul_f32 v[128:129], v[78:79], v[104:105] op_sel_hi:[1,0]
	v_add_f32_dpp v140, v140, v140 row_half_mirror row_mask:0xf bank_mask:0xf
	v_add_f32_dpp v146, v146, v146 row_half_mirror row_mask:0xf bank_mask:0xf
	v_pk_mul_f32 v[130:131], v[80:81], v[104:105] op_sel_hi:[1,0]
	v_pk_mul_f32 v[132:133], v[82:83], v[104:105] op_sel_hi:[1,0]
	v_add_f32_dpp v140, v140, v140 quad_perm:[1,0,3,2] row_mask:0xf bank_mask:0xf
	v_add_f32_dpp v146, v146, v146 quad_perm:[1,0,3,2] row_mask:0xf bank_mask:0xf
	v_pk_mul_f32 v[134:135], v[84:85], v[104:105] op_sel_hi:[1,0]
	s_waitcnt lgkmcnt(4)
	v_pk_fma_f32 v[128:129], v[22:23], v[38:39], v[128:129]
	v_add_f32_dpp v140, v140, v140 quad_perm:[2,3,0,1] row_mask:0xf bank_mask:0xf
	v_add_f32_dpp v146, v146, v146 quad_perm:[2,3,0,1] row_mask:0xf bank_mask:0xf
	v_pk_fma_f32 v[130:131], v[24:25], v[40:41], v[130:131]
	v_pk_fma_f32 v[132:133], v[26:27], v[42:43], v[132:133]
	v_pk_fma_f32 v[134:135], v[28:29], v[44:45], v[134:135]
	s_waitcnt lgkmcnt(2)
	v_pk_fma_f32 v[22:23], v[140:141], v[70:71], v[128:129] op_sel_hi:[0,1,1] neg_lo:[1,0,0] neg_hi:[1,0,0]
	v_pk_fma_f32 v[24:25], v[140:141], v[72:73], v[130:131] op_sel_hi:[0,1,1] neg_lo:[1,0,0] neg_hi:[1,0,0]
	v_pk_fma_f32 v[26:27], v[140:141], v[74:75], v[132:133] op_sel_hi:[0,1,1] neg_lo:[1,0,0] neg_hi:[1,0,0]
	v_pk_fma_f32 v[28:29], v[140:141], v[76:77], v[134:135] op_sel_hi:[0,1,1] neg_lo:[1,0,0] neg_hi:[1,0,0]
	s_waitcnt lgkmcnt(0)
	v_pk_mul_f32 v[138:139], v[22:23], v[96:97]
	v_pk_fma_f32 v[138:139], v[24:25], v[98:99], v[138:139]
	v_pk_fma_f32 v[138:139], v[26:27], v[100:101], v[138:139]
	v_pk_fma_f32 v[138:139], v[28:29], v[102:103], v[138:139]
	v_add_f32_e32 v147, v138, v139
	s_nop 1
	v_add_f32_dpp v147, v147, v147 row_half_mirror row_mask:0xf bank_mask:0xf
	s_nop 1
	v_add_f32_dpp v147, v147, v147 quad_perm:[1,0,3,2] row_mask:0xf bank_mask:0xf
	s_nop 1
	v_add_f32_dpp v147, v147, v147 quad_perm:[2,3,0,1] row_mask:0xf bank_mask:0xf
	ds_write_b128 v113, v[144:147] offset:22576
	s_branch .Lrw0_u2e0
.Lrw0_u2s0:
	ds_read_b128 v[30:33], v112 offset:0
	ds_read_b128 v[34:37], v112 offset:16
	ds_read_b128 v[38:41], v112 offset:4096
	ds_read_b128 v[42:45], v112 offset:4112
	ds_read_b128 v[70:73], v112 offset:8192
	ds_read_b128 v[74:77], v112 offset:8208
	s_waitcnt lgkmcnt(4)
	v_pk_mul_f32 v[136:137], v[22:23], v[30:31]
	v_pk_fma_f32 v[136:137], v[24:25], v[32:33], v[136:137]
	v_pk_fma_f32 v[136:137], v[26:27], v[34:35], v[136:137]
	v_pk_fma_f32 v[136:137], v[28:29], v[36:37], v[136:137]
	ds_read_b128 v[30:33], v112 offset:256
	ds_read_b128 v[34:37], v112 offset:272
	ds_read_b128 v[96:99], v112 offset:16384
	ds_read_b128 v[100:103], v112 offset:16400
	v_add_f32_e32 v140, v136, v137
	s_waitcnt lgkmcnt(6)
	v_pk_mul_f32 v[128:129], v[22:23], v[38:39]
	v_add_f32_dpp v140, v140, v140 row_half_mirror row_mask:0xf bank_mask:0xf
	v_pk_mul_f32 v[130:131], v[24:25], v[40:41]
	v_pk_mul_f32 v[132:133], v[26:27], v[42:43]
	v_pk_mul_f32 v[134:135], v[28:29], v[44:45]
	ds_read_b128 v[38:41], v112 offset:4352
	ds_read_b128 v[42:45], v112 offset:4368
	v_add_f32_dpp v140, v140, v140 quad_perm:[1,0,3,2] row_mask:0xf bank_mask:0xf
	s_nop 1
	v_add_f32_dpp v140, v140, v140 quad_perm:[2,3,0,1] row_mask:0xf bank_mask:0xf
	s_waitcnt lgkmcnt(6)
	v_pk_fma_f32 v[22:23], v[140:141], v[70:71], v[128:129] op_sel_hi:[0,1,1] neg_lo:[1,0,0] neg_hi:[1,0,0]
	v_pk_fma_f32 v[24:25], v[140:141], v[72:73], v[130:131] op_sel_hi:[0,1,1] neg_lo:[1,0,0] neg_hi:[1,0,0]
	v_pk_fma_f32 v[26:27], v[140:141], v[74:75], v[132:133] op_sel_hi:[0,1,1] neg_lo:[1,0,0] neg_hi:[1,0,0]
	v_pk_fma_f32 v[28:29], v[140:141], v[76:77], v[134:135] op_sel_hi:[0,1,1] neg_lo:[1,0,0] neg_hi:[1,0,0]
	ds_read_b128 v[70:73], v112 offset:8448
	ds_read_b128 v[74:77], v112 offset:8464
	s_waitcnt lgkmcnt(4)
	v_pk_mul_f32 v[136:137], v[22:23], v[30:31]
	v_pk_mul_f32 v[138:139], v[22:23], v[96:97]
	v_pk_fma_f32 v[136:137], v[24:25], v[32:33], v[136:137]
	v_pk_fma_f32 v[138:139], v[24:25], v[98:99], v[138:139]
	v_pk_fma_f32 v[136:137], v[26:27], v[34:35], v[136:137]
	v_pk_fma_f32 v[138:139], v[26:27], v[100:101], v[138:139]
	v_pk_fma_f32 v[136:137], v[28:29], v[36:37], v[136:137]
	v_pk_fma_f32 v[138:139], v[28:29], v[102:103], v[138:139]
	ds_read_b128 v[30:33], v112 offset:512
	ds_read_b128 v[34:37], v112 offset:528
	ds_read_b128 v[96:99], v112 offset:16640
	ds_read_b128 v[100:103], v112 offset:16656
	v_add_f32_e32 v140, v136, v137
	v_add_f32_e32 v144, v138, v139
	s_waitcnt lgkmcnt(6)
	v_pk_mul_f32 v[128:129], v[22:23], v[38:39]
	v_add_f32_dpp v140, v140, v140 row_half_mirror row_mask:0xf bank_mask:0xf
	v_add_f32_dpp v144, v144, v144 row_half_mirror row_mask:0xf bank_mask:0xf
	v_pk_mul_f32 v[130:131], v[24:25], v[40:41]
	v_pk_mul_f32 v[132:133], v[26:27], v[42:43]
	v_add_f32_dpp v140, v140, v140 quad_perm:[1,0,3,2] row_mask:0xf bank_mask:0xf
	v_add_f32_dpp v144, v144, v144 quad_perm:[1,0,3,2] row_mask:0xf bank_mask:0xf
	v_pk_mul_f32 v[134:135], v[28:29], v[44:45]
	ds_read_b128 v[38:41], v112 offset:4608
	ds_read_b128 v[42:45], v112 offset:4624
	v_add_f32_dpp v140, v140, v140 quad_perm:[2,3,0,1] row_mask:0xf bank_mask:0xf
	v_add_f32_dpp v144, v144, v144 quad_perm:[2,3,0,1] row_mask:0xf bank_mask:0xf
	s_waitcnt lgkmcnt(6)
	v_pk_fma_f32 v[22:23], v[140:141], v[70:71], v[128:129] op_sel_hi:[0,1,1] neg_lo:[1,0,0] neg_hi:[1,0,0]
	v_pk_fma_f32 v[24:25], v[140:141], v[72:73], v[130:131] op_sel_hi:[0,1,1] neg_lo:[1,0,0] neg_hi:[1,0,0]
	v_pk_fma_f32 v[26:27], v[140:141], v[74:75], v[132:133] op_sel_hi:[0,1,1] neg_lo:[1,0,0] neg_hi:[1,0,0]
	v_pk_fma_f32 v[28:29], v[140:141], v[76:77], v[134:135] op_sel_hi:[0,1,1] neg_lo:[1,0,0] neg_hi:[1,0,0]
	ds_read_b128 v[70:73], v112 offset:8704
	ds_read_b128 v[74:77], v112 offset:8720
	s_waitcnt lgkmcnt(4)
	v_pk_mul_f32 v[136:137], v[22:23], v[30:31]
	v_pk_mul_f32 v[138:139], v[22:23], v[96:97]
	v_pk_fma_f32 v[136:137], v[24:25], v[32:33], v[136:137]
	v_pk_fma_f32 v[138:139], v[24:25], v[98:99], v[138:139]
	v_pk_fma_f32 v[136:137], v[26:27], v[34:35], v[136:137]
	v_pk_fma_f32 v[138:139], v[26:27], v[100:101], v[138:139]
	v_pk_fma_f32 v[136:137], v[28:29], v[36:37], v[136:137]
	v_pk_fma_f32 v[138:139], v[28:29], v[102:103], v[138:139]
	ds_read_b128 v[30:33], v112 offset:768
	ds_read_b128 v[34:37], v112 offset:784
	ds_read_b128 v[96:99], v112 offset:16896
	ds_read_b128 v[100:103], v112 offset:16912
	v_add_f32_e32 v140, v136, v137
	v_add_f32_e32 v145, v138, v139
	s_waitcnt lgkmcnt(6)
	v_pk_mul_f32 v[128:129], v[22:23], v[38:39]
	v_add_f32_dpp v140, v140, v140 row_half_mirror row_mask:0xf bank_mask:0xf
	v_add_f32_dpp v145, v145, v145 row_half_mirror row_mask:0xf bank_mask:0xf
	v_pk_mul_f32 v[130:131], v[24:25], v[40:41]
	v_pk_mul_f32 v[132:133], v[26:27], v[42:43]
	v_add_f32_dpp v140, v140, v140 quad_perm:[1,0,3,2] row_mask:0xf bank_mask:0xf
	v_add_f32_dpp v145, v145, v145 quad_perm:[1,0,3,2] row_mask:0xf bank_mask:0xf
	v_pk_mul_f32 v[134:135], v[28:29], v[44:45]
	ds_read_b128 v[38:41], v112 offset:4864
	ds_read_b128 v[42:45], v112 offset:4880
	v_add_f32_dpp v140, v140, v140 quad_perm:[2,3,0,1] row_mask:0xf bank_mask:0xf
	v_add_f32_dpp v145, v145, v145 quad_perm:[2,3,0,1] row_mask:0xf bank_mask:0xf
	s_waitcnt lgkmcnt(6)
	v_pk_fma_f32 v[22:23], v[140:141], v[70:71], v[128:129] op_sel_hi:[0,1,1] neg_lo:[1,0,0] neg_hi:[1,0,0]
	v_pk_fma_f32 v[24:25], v[140:141], v[72:73], v[130:131] op_sel_hi:[0,1,1] neg_lo:[1,0,0] neg_hi:[1,0,0]
	v_pk_fma_f32 v[26:27], v[140:141], v[74:75], v[132:133] op_sel_hi:[0,1,1] neg_lo:[1,0,0] neg_hi:[1,0,0]
	v_pk_fma_f32 v[28:29], v[140:141], v[76:77], v[134:135] op_sel_hi:[0,1,1] neg_lo:[1,0,0] neg_hi:[1,0,0]
	ds_read_b128 v[70:73], v112 offset:8960
	ds_read_b128 v[74:77], v112 offset:8976
	s_waitcnt lgkmcnt(4)
	v_pk_mul_f32 v[136:137], v[22:23], v[30:31]
	v_pk_mul_f32 v[138:139], v[22:23], v[96:97]
	v_pk_fma_f32 v[136:137], v[24:25], v[32:33], v[136:137]
	v_pk_fma_f32 v[138:139], v[24:25], v[98:99], v[138:139]
	v_pk_fma_f32 v[136:137], v[26:27], v[34:35], v[136:137]
	v_pk_fma_f32 v[138:139], v[26:27], v[100:101], v[138:139]
	v_pk_fma_f32 v[136:137], v[28:29], v[36:37], v[136:137]
	v_pk_fma_f32 v[138:139], v[28:29], v[102:103], v[138:139]
	ds_read_b128 v[30:33], v112 offset:1024
	ds_read_b128 v[34:37], v112 offset:1040
	ds_read_b128 v[96:99], v112 offset:17152
	ds_read_b128 v[100:103], v112 offset:17168
	v_add_f32_e32 v140, v136, v137
	v_add_f32_e32 v146, v138, v139
	s_waitcnt lgkmcnt(6)
	v_pk_mul_f32 v[128:129], v[22:23], v[38:39]
	v_add_f32_dpp v140, v140, v140 row_half_mirror row_mask:0xf bank_mask:0xf
	v_add_f32_dpp v146, v146, v146 row_half_mirror row_mask:0xf bank_mask:0xf
	v_pk_mul_f32 v[130:131], v[24:25], v[40:41]
	v_pk_mul_f32 v[132:133], v[26:27], v[42:43]
	v_add_f32_dpp v140, v140, v140 quad_perm:[1,0,3,2] row_mask:0xf bank_mask:0xf
	v_add_f32_dpp v146, v146, v146 quad_perm:[1,0,3,2] row_mask:0xf bank_mask:0xf
	v_pk_mul_f32 v[134:135], v[28:29], v[44:45]
	ds_read_b128 v[38:41], v112 offset:5120
	ds_read_b128 v[42:45], v112 offset:5136
	v_add_f32_dpp v140, v140, v140 quad_perm:[2,3,0,1] row_mask:0xf bank_mask:0xf
	v_add_f32_dpp v146, v146, v146 quad_perm:[2,3,0,1] row_mask:0xf bank_mask:0xf
	s_waitcnt lgkmcnt(6)
	v_pk_fma_f32 v[22:23], v[140:141], v[70:71], v[128:129] op_sel_hi:[0,1,1] neg_lo:[1,0,0] neg_hi:[1,0,0]
	v_pk_fma_f32 v[24:25], v[140:141], v[72:73], v[130:131] op_sel_hi:[0,1,1] neg_lo:[1,0,0] neg_hi:[1,0,0]
	v_pk_fma_f32 v[26:27], v[140:141], v[74:75], v[132:133] op_sel_hi:[0,1,1] neg_lo:[1,0,0] neg_hi:[1,0,0]
	v_pk_fma_f32 v[28:29], v[140:141], v[76:77], v[134:135] op_sel_hi:[0,1,1] neg_lo:[1,0,0] neg_hi:[1,0,0]
	ds_read_b128 v[70:73], v112 offset:9216
	ds_read_b128 v[74:77], v112 offset:9232
	s_waitcnt lgkmcnt(4)
	v_pk_mul_f32 v[136:137], v[22:23], v[30:31]
	v_pk_mul_f32 v[138:139], v[22:23], v[96:97]
	v_pk_fma_f32 v[136:137], v[24:25], v[32:33], v[136:137]
	v_pk_fma_f32 v[138:139], v[24:25], v[98:99], v[138:139]
	v_pk_fma_f32 v[136:137], v[26:27], v[34:35], v[136:137]
	v_pk_fma_f32 v[138:139], v[26:27], v[100:101], v[138:139]
	v_pk_fma_f32 v[136:137], v[28:29], v[36:37], v[136:137]
	v_pk_fma_f32 v[138:139], v[28:29], v[102:103], v[138:139]
	ds_read_b128 v[30:33], v112 offset:1280
	ds_read_b128 v[34:37], v112 offset:1296
	ds_read_b128 v[96:99], v112 offset:17408
	ds_read_b128 v[100:103], v112 offset:17424
	v_add_f32_e32 v140, v136, v137
	v_add_f32_e32 v147, v138, v139
	s_waitcnt lgkmcnt(6)
	v_pk_mul_f32 v[128:129], v[22:23], v[38:39]
	v_add_f32_dpp v140, v140, v140 row_half_mirror row_mask:0xf bank_mask:0xf
	v_add_f32_dpp v147, v147, v147 row_half_mirror row_mask:0xf bank_mask:0xf
	v_pk_mul_f32 v[130:131], v[24:25], v[40:41]
	v_pk_mul_f32 v[132:133], v[26:27], v[42:43]
	v_add_f32_dpp v140, v140, v140 quad_perm:[1,0,3,2] row_mask:0xf bank_mask:0xf
	v_add_f32_dpp v147, v147, v147 quad_perm:[1,0,3,2] row_mask:0xf bank_mask:0xf
	v_pk_mul_f32 v[134:135], v[28:29], v[44:45]
	ds_read_b128 v[38:41], v112 offset:5376
	ds_read_b128 v[42:45], v112 offset:5392
	v_add_f32_dpp v140, v140, v140 quad_perm:[2,3,0,1] row_mask:0xf bank_mask:0xf
	v_add_f32_dpp v147, v147, v147 quad_perm:[2,3,0,1] row_mask:0xf bank_mask:0xf
	s_waitcnt lgkmcnt(6)
	v_pk_fma_f32 v[22:23], v[140:141], v[70:71], v[128:129] op_sel_hi:[0,1,1] neg_lo:[1,0,0] neg_hi:[1,0,0]
	v_pk_fma_f32 v[24:25], v[140:141], v[72:73], v[130:131] op_sel_hi:[0,1,1] neg_lo:[1,0,0] neg_hi:[1,0,0]
	v_pk_fma_f32 v[26:27], v[140:141], v[74:75], v[132:133] op_sel_hi:[0,1,1] neg_lo:[1,0,0] neg_hi:[1,0,0]
	v_pk_fma_f32 v[28:29], v[140:141], v[76:77], v[134:135] op_sel_hi:[0,1,1] neg_lo:[1,0,0] neg_hi:[1,0,0]
	ds_read_b128 v[70:73], v112 offset:9472
	ds_read_b128 v[74:77], v112 offset:9488
	ds_write_b128 v113, v[144:147] offset:22528
	s_waitcnt lgkmcnt(5)
	v_pk_mul_f32 v[136:137], v[22:23], v[30:31]
	v_pk_mul_f32 v[138:139], v[22:23], v[96:97]
	v_pk_fma_f32 v[136:137], v[24:25], v[32:33], v[136:137]
	v_pk_fma_f32 v[138:139], v[24:25], v[98:99], v[138:139]
	v_pk_fma_f32 v[136:137], v[26:27], v[34:35], v[136:137]
	v_pk_fma_f32 v[138:139], v[26:27], v[100:101], v[138:139]
	v_pk_fma_f32 v[136:137], v[28:29], v[36:37], v[136:137]
	v_pk_fma_f32 v[138:139], v[28:29], v[102:103], v[138:139]
	ds_read_b128 v[30:33], v112 offset:1536
	ds_read_b128 v[34:37], v112 offset:1552
	ds_read_b128 v[96:99], v112 offset:17664
	ds_read_b128 v[100:103], v112 offset:17680
	v_add_f32_e32 v140, v136, v137
	v_add_f32_e32 v144, v138, v139
	s_waitcnt lgkmcnt(7)
	v_pk_mul_f32 v[128:129], v[22:23], v[38:39]
	v_add_f32_dpp v140, v140, v140 row_half_mirror row_mask:0xf bank_mask:0xf
	v_add_f32_dpp v144, v144, v144 row_half_mirror row_mask:0xf bank_mask:0xf
	v_pk_mul_f32 v[130:131], v[24:25], v[40:41]
	v_pk_mul_f32 v[132:133], v[26:27], v[42:43]
	v_add_f32_dpp v140, v140, v140 quad_perm:[1,0,3,2] row_mask:0xf bank_mask:0xf
	v_add_f32_dpp v144, v144, v144 quad_perm:[1,0,3,2] row_mask:0xf bank_mask:0xf
	v_pk_mul_f32 v[134:135], v[28:29], v[44:45]
	ds_read_b128 v[38:41], v112 offset:5632
	ds_read_b128 v[42:45], v112 offset:5648
	v_add_f32_dpp v140, v140, v140 quad_perm:[2,3,0,1] row_mask:0xf bank_mask:0xf
	v_add_f32_dpp v144, v144, v144 quad_perm:[2,3,0,1] row_mask:0xf bank_mask:0xf
	s_waitcnt lgkmcnt(7)
	v_pk_fma_f32 v[22:23], v[140:141], v[70:71], v[128:129] op_sel_hi:[0,1,1] neg_lo:[1,0,0] neg_hi:[1,0,0]
	v_pk_fma_f32 v[24:25], v[140:141], v[72:73], v[130:131] op_sel_hi:[0,1,1] neg_lo:[1,0,0] neg_hi:[1,0,0]
	v_pk_fma_f32 v[26:27], v[140:141], v[74:75], v[132:133] op_sel_hi:[0,1,1] neg_lo:[1,0,0] neg_hi:[1,0,0]
	v_pk_fma_f32 v[28:29], v[140:141], v[76:77], v[134:135] op_sel_hi:[0,1,1] neg_lo:[1,0,0] neg_hi:[1,0,0]
	ds_read_b128 v[70:73], v112 offset:9728
	ds_read_b128 v[74:77], v112 offset:9744
	s_waitcnt lgkmcnt(4)
	v_pk_mul_f32 v[136:137], v[22:23], v[30:31]
	v_pk_mul_f32 v[138:139], v[22:23], v[96:97]
	v_pk_fma_f32 v[136:137], v[24:25], v[32:33], v[136:137]
	v_pk_fma_f32 v[138:139], v[24:25], v[98:99], v[138:139]
	v_pk_fma_f32 v[136:137], v[26:27], v[34:35], v[136:137]
	v_pk_fma_f32 v[138:139], v[26:27], v[100:101], v[138:139]
	v_pk_fma_f32 v[136:137], v[28:29], v[36:37], v[136:137]
	v_pk_fma_f32 v[138:139], v[28:29], v[102:103], v[138:139]
	ds_read_b128 v[30:33], v112 offset:1792
	ds_read_b128 v[34:37], v112 offset:1808
	ds_read_b128 v[96:99], v112 offset:17920
	ds_read_b128 v[100:103], v112 offset:17936
	v_add_f32_e32 v140, v136, v137
	v_add_f32_e32 v145, v138, v139
	s_waitcnt lgkmcnt(6)
	v_pk_mul_f32 v[128:129], v[22:23], v[38:39]
	v_add_f32_dpp v140, v140, v140 row_half_mirror row_mask:0xf bank_mask:0xf
	v_add_f32_dpp v145, v145, v145 row_half_mirror row_mask:0xf bank_mask:0xf
	v_pk_mul_f32 v[130:131], v[24:25], v[40:41]
	v_pk_mul_f32 v[132:133], v[26:27], v[42:43]
	v_add_f32_dpp v140, v140, v140 quad_perm:[1,0,3,2] row_mask:0xf bank_mask:0xf
	v_add_f32_dpp v145, v145, v145 quad_perm:[1,0,3,2] row_mask:0xf bank_mask:0xf
	v_pk_mul_f32 v[134:135], v[28:29], v[44:45]
	ds_read_b128 v[38:41], v112 offset:5888
	ds_read_b128 v[42:45], v112 offset:5904
	v_add_f32_dpp v140, v140, v140 quad_perm:[2,3,0,1] row_mask:0xf bank_mask:0xf
	v_add_f32_dpp v145, v145, v145 quad_perm:[2,3,0,1] row_mask:0xf bank_mask:0xf
	s_waitcnt lgkmcnt(6)
	v_pk_fma_f32 v[22:23], v[140:141], v[70:71], v[128:129] op_sel_hi:[0,1,1] neg_lo:[1,0,0] neg_hi:[1,0,0]
	v_pk_fma_f32 v[24:25], v[140:141], v[72:73], v[130:131] op_sel_hi:[0,1,1] neg_lo:[1,0,0] neg_hi:[1,0,0]
	v_pk_fma_f32 v[26:27], v[140:141], v[74:75], v[132:133] op_sel_hi:[0,1,1] neg_lo:[1,0,0] neg_hi:[1,0,0]
	v_pk_fma_f32 v[28:29], v[140:141], v[76:77], v[134:135] op_sel_hi:[0,1,1] neg_lo:[1,0,0] neg_hi:[1,0,0]
	ds_read_b128 v[70:73], v112 offset:9984
	ds_read_b128 v[74:77], v112 offset:10000
	s_waitcnt lgkmcnt(4)
	v_pk_mul_f32 v[136:137], v[22:23], v[30:31]
	v_pk_mul_f32 v[138:139], v[22:23], v[96:97]
	v_pk_fma_f32 v[136:137], v[24:25], v[32:33], v[136:137]
	v_pk_fma_f32 v[138:139], v[24:25], v[98:99], v[138:139]
	v_pk_fma_f32 v[136:137], v[26:27], v[34:35], v[136:137]
	v_pk_fma_f32 v[138:139], v[26:27], v[100:101], v[138:139]
	v_pk_fma_f32 v[136:137], v[28:29], v[36:37], v[136:137]
	v_pk_fma_f32 v[138:139], v[28:29], v[102:103], v[138:139]
	ds_read_b128 v[30:33], v112 offset:2048
	ds_read_b128 v[34:37], v112 offset:2064
	ds_read_b128 v[96:99], v112 offset:18176
	ds_read_b128 v[100:103], v112 offset:18192
	v_add_f32_e32 v140, v136, v137
	v_add_f32_e32 v146, v138, v139
	s_waitcnt lgkmcnt(6)
	v_pk_mul_f32 v[128:129], v[22:23], v[38:39]
	v_add_f32_dpp v140, v140, v140 row_half_mirror row_mask:0xf bank_mask:0xf
	v_add_f32_dpp v146, v146, v146 row_half_mirror row_mask:0xf bank_mask:0xf
	v_pk_mul_f32 v[130:131], v[24:25], v[40:41]
	v_pk_mul_f32 v[132:133], v[26:27], v[42:43]
	v_add_f32_dpp v140, v140, v140 quad_perm:[1,0,3,2] row_mask:0xf bank_mask:0xf
	v_add_f32_dpp v146, v146, v146 quad_perm:[1,0,3,2] row_mask:0xf bank_mask:0xf
	v_pk_mul_f32 v[134:135], v[28:29], v[44:45]
	ds_read_b128 v[38:41], v112 offset:6144
	ds_read_b128 v[42:45], v112 offset:6160
	v_add_f32_dpp v140, v140, v140 quad_perm:[2,3,0,1] row_mask:0xf bank_mask:0xf
	v_add_f32_dpp v146, v146, v146 quad_perm:[2,3,0,1] row_mask:0xf bank_mask:0xf
	s_waitcnt lgkmcnt(6)
	v_pk_fma_f32 v[22:23], v[140:141], v[70:71], v[128:129] op_sel_hi:[0,1,1] neg_lo:[1,0,0] neg_hi:[1,0,0]
	v_pk_fma_f32 v[24:25], v[140:141], v[72:73], v[130:131] op_sel_hi:[0,1,1] neg_lo:[1,0,0] neg_hi:[1,0,0]
	v_pk_fma_f32 v[26:27], v[140:141], v[74:75], v[132:133] op_sel_hi:[0,1,1] neg_lo:[1,0,0] neg_hi:[1,0,0]
	v_pk_fma_f32 v[28:29], v[140:141], v[76:77], v[134:135] op_sel_hi:[0,1,1] neg_lo:[1,0,0] neg_hi:[1,0,0]
	ds_read_b128 v[70:73], v112 offset:10240
	ds_read_b128 v[74:77], v112 offset:10256
	s_waitcnt lgkmcnt(4)
	v_pk_mul_f32 v[136:137], v[22:23], v[30:31]
	v_pk_mul_f32 v[138:139], v[22:23], v[96:97]
	v_pk_fma_f32 v[136:137], v[24:25], v[32:33], v[136:137]
	v_pk_fma_f32 v[138:139], v[24:25], v[98:99], v[138:139]
	v_pk_fma_f32 v[136:137], v[26:27], v[34:35], v[136:137]
	v_pk_fma_f32 v[138:139], v[26:27], v[100:101], v[138:139]
	v_pk_fma_f32 v[136:137], v[28:29], v[36:37], v[136:137]
	v_pk_fma_f32 v[138:139], v[28:29], v[102:103], v[138:139]
	ds_read_b128 v[30:33], v112 offset:2304
	ds_read_b128 v[34:37], v112 offset:2320
	ds_read_b128 v[96:99], v112 offset:18432
	ds_read_b128 v[100:103], v112 offset:18448
	v_add_f32_e32 v140, v136, v137
	v_add_f32_e32 v147, v138, v139
	s_waitcnt lgkmcnt(6)
	v_pk_mul_f32 v[128:129], v[22:23], v[38:39]
	v_add_f32_dpp v140, v140, v140 row_half_mirror row_mask:0xf bank_mask:0xf
	v_add_f32_dpp v147, v147, v147 row_half_mirror row_mask:0xf bank_mask:0xf
	v_pk_mul_f32 v[130:131], v[24:25], v[40:41]
	v_pk_mul_f32 v[132:133], v[26:27], v[42:43]
	v_add_f32_dpp v140, v140, v140 quad_perm:[1,0,3,2] row_mask:0xf bank_mask:0xf
	v_add_f32_dpp v147, v147, v147 quad_perm:[1,0,3,2] row_mask:0xf bank_mask:0xf
	v_pk_mul_f32 v[134:135], v[28:29], v[44:45]
	ds_read_b128 v[38:41], v112 offset:6400
	ds_read_b128 v[42:45], v112 offset:6416
	v_add_f32_dpp v140, v140, v140 quad_perm:[2,3,0,1] row_mask:0xf bank_mask:0xf
	v_add_f32_dpp v147, v147, v147 quad_perm:[2,3,0,1] row_mask:0xf bank_mask:0xf
	s_waitcnt lgkmcnt(6)
	v_pk_fma_f32 v[22:23], v[140:141], v[70:71], v[128:129] op_sel_hi:[0,1,1] neg_lo:[1,0,0] neg_hi:[1,0,0]
	v_pk_fma_f32 v[24:25], v[140:141], v[72:73], v[130:131] op_sel_hi:[0,1,1] neg_lo:[1,0,0] neg_hi:[1,0,0]
	v_pk_fma_f32 v[26:27], v[140:141], v[74:75], v[132:133] op_sel_hi:[0,1,1] neg_lo:[1,0,0] neg_hi:[1,0,0]
	v_pk_fma_f32 v[28:29], v[140:141], v[76:77], v[134:135] op_sel_hi:[0,1,1] neg_lo:[1,0,0] neg_hi:[1,0,0]
	ds_read_b128 v[70:73], v112 offset:10496
	ds_read_b128 v[74:77], v112 offset:10512
	ds_write_b128 v113, v[144:147] offset:22544
	s_waitcnt lgkmcnt(5)
	v_pk_mul_f32 v[136:137], v[22:23], v[30:31]
	v_pk_mul_f32 v[138:139], v[22:23], v[96:97]
	v_pk_fma_f32 v[136:137], v[24:25], v[32:33], v[136:137]
	v_pk_fma_f32 v[138:139], v[24:25], v[98:99], v[138:139]
	v_pk_fma_f32 v[136:137], v[26:27], v[34:35], v[136:137]
	v_pk_fma_f32 v[138:139], v[26:27], v[100:101], v[138:139]
	v_pk_fma_f32 v[136:137], v[28:29], v[36:37], v[136:137]
	v_pk_fma_f32 v[138:139], v[28:29], v[102:103], v[138:139]
	ds_read_b128 v[30:33], v112 offset:2560
	ds_read_b128 v[34:37], v112 offset:2576
	ds_read_b128 v[96:99], v112 offset:18688
	ds_read_b128 v[100:103], v112 offset:18704
	v_add_f32_e32 v140, v136, v137
	v_add_f32_e32 v144, v138, v139
	s_waitcnt lgkmcnt(7)
	v_pk_mul_f32 v[128:129], v[22:23], v[38:39]
	v_add_f32_dpp v140, v140, v140 row_half_mirror row_mask:0xf bank_mask:0xf
	v_add_f32_dpp v144, v144, v144 row_half_mirror row_mask:0xf bank_mask:0xf
	v_pk_mul_f32 v[130:131], v[24:25], v[40:41]
	v_pk_mul_f32 v[132:133], v[26:27], v[42:43]
	v_add_f32_dpp v140, v140, v140 quad_perm:[1,0,3,2] row_mask:0xf bank_mask:0xf
	v_add_f32_dpp v144, v144, v144 quad_perm:[1,0,3,2] row_mask:0xf bank_mask:0xf
	v_pk_mul_f32 v[134:135], v[28:29], v[44:45]
	ds_read_b128 v[38:41], v112 offset:6656
	ds_read_b128 v[42:45], v112 offset:6672
	v_add_f32_dpp v140, v140, v140 quad_perm:[2,3,0,1] row_mask:0xf bank_mask:0xf
	v_add_f32_dpp v144, v144, v144 quad_perm:[2,3,0,1] row_mask:0xf bank_mask:0xf
	s_waitcnt lgkmcnt(7)
	v_pk_fma_f32 v[22:23], v[140:141], v[70:71], v[128:129] op_sel_hi:[0,1,1] neg_lo:[1,0,0] neg_hi:[1,0,0]
	v_pk_fma_f32 v[24:25], v[140:141], v[72:73], v[130:131] op_sel_hi:[0,1,1] neg_lo:[1,0,0] neg_hi:[1,0,0]
	v_pk_fma_f32 v[26:27], v[140:141], v[74:75], v[132:133] op_sel_hi:[0,1,1] neg_lo:[1,0,0] neg_hi:[1,0,0]
	v_pk_fma_f32 v[28:29], v[140:141], v[76:77], v[134:135] op_sel_hi:[0,1,1] neg_lo:[1,0,0] neg_hi:[1,0,0]
	ds_read_b128 v[70:73], v112 offset:10752
	ds_read_b128 v[74:77], v112 offset:10768
	s_waitcnt lgkmcnt(4)
	v_pk_mul_f32 v[136:137], v[22:23], v[30:31]
	v_pk_mul_f32 v[138:139], v[22:23], v[96:97]
	v_pk_fma_f32 v[136:137], v[24:25], v[32:33], v[136:137]
	v_pk_fma_f32 v[138:139], v[24:25], v[98:99], v[138:139]
	v_pk_fma_f32 v[136:137], v[26:27], v[34:35], v[136:137]
	v_pk_fma_f32 v[138:139], v[26:27], v[100:101], v[138:139]
	v_pk_fma_f32 v[136:137], v[28:29], v[36:37], v[136:137]
	v_pk_fma_f32 v[138:139], v[28:29], v[102:103], v[138:139]
	ds_read_b128 v[30:33], v112 offset:2816
	ds_read_b128 v[34:37], v112 offset:2832
	ds_read_b128 v[96:99], v112 offset:18944
	ds_read_b128 v[100:103], v112 offset:18960
	v_add_f32_e32 v140, v136, v137
	v_add_f32_e32 v145, v138, v139
	s_waitcnt lgkmcnt(6)
	v_pk_mul_f32 v[128:129], v[22:23], v[38:39]
	v_add_f32_dpp v140, v140, v140 row_half_mirror row_mask:0xf bank_mask:0xf
	v_add_f32_dpp v145, v145, v145 row_half_mirror row_mask:0xf bank_mask:0xf
	v_pk_mul_f32 v[130:131], v[24:25], v[40:41]
	v_pk_mul_f32 v[132:133], v[26:27], v[42:43]
	v_add_f32_dpp v140, v140, v140 quad_perm:[1,0,3,2] row_mask:0xf bank_mask:0xf
	v_add_f32_dpp v145, v145, v145 quad_perm:[1,0,3,2] row_mask:0xf bank_mask:0xf
	v_pk_mul_f32 v[134:135], v[28:29], v[44:45]
	ds_read_b128 v[38:41], v112 offset:6912
	ds_read_b128 v[42:45], v112 offset:6928
	v_add_f32_dpp v140, v140, v140 quad_perm:[2,3,0,1] row_mask:0xf bank_mask:0xf
	v_add_f32_dpp v145, v145, v145 quad_perm:[2,3,0,1] row_mask:0xf bank_mask:0xf
	s_waitcnt lgkmcnt(6)
	v_pk_fma_f32 v[22:23], v[140:141], v[70:71], v[128:129] op_sel_hi:[0,1,1] neg_lo:[1,0,0] neg_hi:[1,0,0]
	v_pk_fma_f32 v[24:25], v[140:141], v[72:73], v[130:131] op_sel_hi:[0,1,1] neg_lo:[1,0,0] neg_hi:[1,0,0]
	v_pk_fma_f32 v[26:27], v[140:141], v[74:75], v[132:133] op_sel_hi:[0,1,1] neg_lo:[1,0,0] neg_hi:[1,0,0]
	v_pk_fma_f32 v[28:29], v[140:141], v[76:77], v[134:135] op_sel_hi:[0,1,1] neg_lo:[1,0,0] neg_hi:[1,0,0]
	ds_read_b128 v[70:73], v112 offset:11008
	ds_read_b128 v[74:77], v112 offset:11024
	s_waitcnt lgkmcnt(4)
	v_pk_mul_f32 v[136:137], v[22:23], v[30:31]
	v_pk_mul_f32 v[138:139], v[22:23], v[96:97]
	v_pk_fma_f32 v[136:137], v[24:25], v[32:33], v[136:137]
	v_pk_fma_f32 v[138:139], v[24:25], v[98:99], v[138:139]
	v_pk_fma_f32 v[136:137], v[26:27], v[34:35], v[136:137]
	v_pk_fma_f32 v[138:139], v[26:27], v[100:101], v[138:139]
	v_pk_fma_f32 v[136:137], v[28:29], v[36:37], v[136:137]
	v_pk_fma_f32 v[138:139], v[28:29], v[102:103], v[138:139]
	ds_read_b128 v[30:33], v112 offset:3072
	ds_read_b128 v[34:37], v112 offset:3088
	ds_read_b128 v[96:99], v112 offset:19200
	ds_read_b128 v[100:103], v112 offset:19216
	v_add_f32_e32 v140, v136, v137
	v_add_f32_e32 v146, v138, v139
	s_waitcnt lgkmcnt(6)
	v_pk_mul_f32 v[128:129], v[22:23], v[38:39]
	v_add_f32_dpp v140, v140, v140 row_half_mirror row_mask:0xf bank_mask:0xf
	v_add_f32_dpp v146, v146, v146 row_half_mirror row_mask:0xf bank_mask:0xf
	v_pk_mul_f32 v[130:131], v[24:25], v[40:41]
	v_pk_mul_f32 v[132:133], v[26:27], v[42:43]
	v_add_f32_dpp v140, v140, v140 quad_perm:[1,0,3,2] row_mask:0xf bank_mask:0xf
	v_add_f32_dpp v146, v146, v146 quad_perm:[1,0,3,2] row_mask:0xf bank_mask:0xf
	v_pk_mul_f32 v[134:135], v[28:29], v[44:45]
	ds_read_b128 v[38:41], v112 offset:7168
	ds_read_b128 v[42:45], v112 offset:7184
	v_add_f32_dpp v140, v140, v140 quad_perm:[2,3,0,1] row_mask:0xf bank_mask:0xf
	v_add_f32_dpp v146, v146, v146 quad_perm:[2,3,0,1] row_mask:0xf bank_mask:0xf
	s_waitcnt lgkmcnt(6)
	v_pk_fma_f32 v[22:23], v[140:141], v[70:71], v[128:129] op_sel_hi:[0,1,1] neg_lo:[1,0,0] neg_hi:[1,0,0]
	v_pk_fma_f32 v[24:25], v[140:141], v[72:73], v[130:131] op_sel_hi:[0,1,1] neg_lo:[1,0,0] neg_hi:[1,0,0]
	v_pk_fma_f32 v[26:27], v[140:141], v[74:75], v[132:133] op_sel_hi:[0,1,1] neg_lo:[1,0,0] neg_hi:[1,0,0]
	v_pk_fma_f32 v[28:29], v[140:141], v[76:77], v[134:135] op_sel_hi:[0,1,1] neg_lo:[1,0,0] neg_hi:[1,0,0]
	ds_read_b128 v[70:73], v112 offset:11264
	ds_read_b128 v[74:77], v112 offset:11280
	s_waitcnt lgkmcnt(4)
	v_pk_mul_f32 v[136:137], v[22:23], v[30:31]
	v_pk_mul_f32 v[138:139], v[22:23], v[96:97]
	v_pk_fma_f32 v[136:137], v[24:25], v[32:33], v[136:137]
	v_pk_fma_f32 v[138:139], v[24:25], v[98:99], v[138:139]
	v_pk_fma_f32 v[136:137], v[26:27], v[34:35], v[136:137]
	v_pk_fma_f32 v[138:139], v[26:27], v[100:101], v[138:139]
	v_pk_fma_f32 v[136:137], v[28:29], v[36:37], v[136:137]
	v_pk_fma_f32 v[138:139], v[28:29], v[102:103], v[138:139]
	ds_read_b128 v[30:33], v112 offset:3328
	ds_read_b128 v[34:37], v112 offset:3344
	ds_read_b128 v[96:99], v112 offset:19456
	ds_read_b128 v[100:103], v112 offset:19472
	v_add_f32_e32 v140, v136, v137
	v_add_f32_e32 v147, v138, v139
	s_waitcnt lgkmcnt(6)
	v_pk_mul_f32 v[128:129], v[22:23], v[38:39]
	v_add_f32_dpp v140, v140, v140 row_half_mirror row_mask:0xf bank_mask:0xf
	v_add_f32_dpp v147, v147, v147 row_half_mirror row_mask:0xf bank_mask:0xf
	v_pk_mul_f32 v[130:131], v[24:25], v[40:41]
	v_pk_mul_f32 v[132:133], v[26:27], v[42:43]
	v_add_f32_dpp v140, v140, v140 quad_perm:[1,0,3,2] row_mask:0xf bank_mask:0xf
	v_add_f32_dpp v147, v147, v147 quad_perm:[1,0,3,2] row_mask:0xf bank_mask:0xf
	v_pk_mul_f32 v[134:135], v[28:29], v[44:45]
	ds_read_b128 v[38:41], v112 offset:7424
	ds_read_b128 v[42:45], v112 offset:7440
	v_add_f32_dpp v140, v140, v140 quad_perm:[2,3,0,1] row_mask:0xf bank_mask:0xf
	v_add_f32_dpp v147, v147, v147 quad_perm:[2,3,0,1] row_mask:0xf bank_mask:0xf
	s_waitcnt lgkmcnt(6)
	v_pk_fma_f32 v[22:23], v[140:141], v[70:71], v[128:129] op_sel_hi:[0,1,1] neg_lo:[1,0,0] neg_hi:[1,0,0]
	v_pk_fma_f32 v[24:25], v[140:141], v[72:73], v[130:131] op_sel_hi:[0,1,1] neg_lo:[1,0,0] neg_hi:[1,0,0]
	v_pk_fma_f32 v[26:27], v[140:141], v[74:75], v[132:133] op_sel_hi:[0,1,1] neg_lo:[1,0,0] neg_hi:[1,0,0]
	v_pk_fma_f32 v[28:29], v[140:141], v[76:77], v[134:135] op_sel_hi:[0,1,1] neg_lo:[1,0,0] neg_hi:[1,0,0]
	ds_read_b128 v[70:73], v112 offset:11520
	ds_read_b128 v[74:77], v112 offset:11536
	ds_write_b128 v113, v[144:147] offset:22560
	s_waitcnt lgkmcnt(5)
	v_pk_mul_f32 v[136:137], v[22:23], v[30:31]
	v_pk_mul_f32 v[138:139], v[22:23], v[96:97]
	v_pk_fma_f32 v[136:137], v[24:25], v[32:33], v[136:137]
	v_pk_fma_f32 v[138:139], v[24:25], v[98:99], v[138:139]
	v_pk_fma_f32 v[136:137], v[26:27], v[34:35], v[136:137]
	v_pk_fma_f32 v[138:139], v[26:27], v[100:101], v[138:139]
	v_pk_fma_f32 v[136:137], v[28:29], v[36:37], v[136:137]
	v_pk_fma_f32 v[138:139], v[28:29], v[102:103], v[138:139]
	ds_read_b128 v[30:33], v112 offset:3584
	ds_read_b128 v[34:37], v112 offset:3600
	ds_read_b128 v[96:99], v112 offset:19712
	ds_read_b128 v[100:103], v112 offset:19728
	v_add_f32_e32 v140, v136, v137
	v_add_f32_e32 v144, v138, v139
	s_waitcnt lgkmcnt(7)
	v_pk_mul_f32 v[128:129], v[22:23], v[38:39]
	v_add_f32_dpp v140, v140, v140 row_half_mirror row_mask:0xf bank_mask:0xf
	v_add_f32_dpp v144, v144, v144 row_half_mirror row_mask:0xf bank_mask:0xf
	v_pk_mul_f32 v[130:131], v[24:25], v[40:41]
	v_pk_mul_f32 v[132:133], v[26:27], v[42:43]
	v_add_f32_dpp v140, v140, v140 quad_perm:[1,0,3,2] row_mask:0xf bank_mask:0xf
	v_add_f32_dpp v144, v144, v144 quad_perm:[1,0,3,2] row_mask:0xf bank_mask:0xf
	v_pk_mul_f32 v[134:135], v[28:29], v[44:45]
	ds_read_b128 v[38:41], v112 offset:7680
	ds_read_b128 v[42:45], v112 offset:7696
	v_add_f32_dpp v140, v140, v140 quad_perm:[2,3,0,1] row_mask:0xf bank_mask:0xf
	v_add_f32_dpp v144, v144, v144 quad_perm:[2,3,0,1] row_mask:0xf bank_mask:0xf
	s_waitcnt lgkmcnt(7)
	v_pk_fma_f32 v[22:23], v[140:141], v[70:71], v[128:129] op_sel_hi:[0,1,1] neg_lo:[1,0,0] neg_hi:[1,0,0]
	v_pk_fma_f32 v[24:25], v[140:141], v[72:73], v[130:131] op_sel_hi:[0,1,1] neg_lo:[1,0,0] neg_hi:[1,0,0]
	v_pk_fma_f32 v[26:27], v[140:141], v[74:75], v[132:133] op_sel_hi:[0,1,1] neg_lo:[1,0,0] neg_hi:[1,0,0]
	v_pk_fma_f32 v[28:29], v[140:141], v[76:77], v[134:135] op_sel_hi:[0,1,1] neg_lo:[1,0,0] neg_hi:[1,0,0]
	ds_read_b128 v[70:73], v112 offset:11776
	ds_read_b128 v[74:77], v112 offset:11792
	s_waitcnt lgkmcnt(4)
	v_pk_mul_f32 v[136:137], v[22:23], v[30:31]
	v_pk_mul_f32 v[138:139], v[22:23], v[96:97]
	v_pk_fma_f32 v[136:137], v[24:25], v[32:33], v[136:137]
	v_pk_fma_f32 v[138:139], v[24:25], v[98:99], v[138:139]
	v_pk_fma_f32 v[136:137], v[26:27], v[34:35], v[136:137]
	v_pk_fma_f32 v[138:139], v[26:27], v[100:101], v[138:139]
	v_pk_fma_f32 v[136:137], v[28:29], v[36:37], v[136:137]
	v_pk_fma_f32 v[138:139], v[28:29], v[102:103], v[138:139]
	ds_read_b128 v[30:33], v112 offset:3840
	ds_read_b128 v[34:37], v112 offset:3856
	ds_read_b128 v[96:99], v112 offset:19968
	ds_read_b128 v[100:103], v112 offset:19984
	v_add_f32_e32 v140, v136, v137
	v_add_f32_e32 v145, v138, v139
	s_waitcnt lgkmcnt(6)
	v_pk_mul_f32 v[128:129], v[22:23], v[38:39]
	v_add_f32_dpp v140, v140, v140 row_half_mirror row_mask:0xf bank_mask:0xf
	v_add_f32_dpp v145, v145, v145 row_half_mirror row_mask:0xf bank_mask:0xf
	v_pk_mul_f32 v[130:131], v[24:25], v[40:41]
	v_pk_mul_f32 v[132:133], v[26:27], v[42:43]
	v_add_f32_dpp v140, v140, v140 quad_perm:[1,0,3,2] row_mask:0xf bank_mask:0xf
	v_add_f32_dpp v145, v145, v145 quad_perm:[1,0,3,2] row_mask:0xf bank_mask:0xf
	v_pk_mul_f32 v[134:135], v[28:29], v[44:45]
	ds_read_b128 v[38:41], v112 offset:7936
	ds_read_b128 v[42:45], v112 offset:7952
	v_add_f32_dpp v140, v140, v140 quad_perm:[2,3,0,1] row_mask:0xf bank_mask:0xf
	v_add_f32_dpp v145, v145, v145 quad_perm:[2,3,0,1] row_mask:0xf bank_mask:0xf
	s_waitcnt lgkmcnt(6)
	v_pk_fma_f32 v[22:23], v[140:141], v[70:71], v[128:129] op_sel_hi:[0,1,1] neg_lo:[1,0,0] neg_hi:[1,0,0]
	v_pk_fma_f32 v[24:25], v[140:141], v[72:73], v[130:131] op_sel_hi:[0,1,1] neg_lo:[1,0,0] neg_hi:[1,0,0]
	v_pk_fma_f32 v[26:27], v[140:141], v[74:75], v[132:133] op_sel_hi:[0,1,1] neg_lo:[1,0,0] neg_hi:[1,0,0]
	v_pk_fma_f32 v[28:29], v[140:141], v[76:77], v[134:135] op_sel_hi:[0,1,1] neg_lo:[1,0,0] neg_hi:[1,0,0]
	ds_read_b128 v[70:73], v112 offset:12032
	ds_read_b128 v[74:77], v112 offset:12048
	s_waitcnt lgkmcnt(4)
	v_pk_mul_f32 v[136:137], v[22:23], v[30:31]
	v_pk_mul_f32 v[138:139], v[22:23], v[96:97]
	v_pk_fma_f32 v[136:137], v[24:25], v[32:33], v[136:137]
	v_pk_fma_f32 v[138:139], v[24:25], v[98:99], v[138:139]
	v_pk_fma_f32 v[136:137], v[26:27], v[34:35], v[136:137]
	v_pk_fma_f32 v[138:139], v[26:27], v[100:101], v[138:139]
	v_pk_fma_f32 v[136:137], v[28:29], v[36:37], v[136:137]
	v_pk_fma_f32 v[138:139], v[28:29], v[102:103], v[138:139]
	ds_read_b128 v[96:99], v112 offset:20224
	ds_read_b128 v[100:103], v112 offset:20240
	v_add_f32_e32 v140, v136, v137
	v_add_f32_e32 v146, v138, v139
	s_waitcnt lgkmcnt(4)
	v_pk_mul_f32 v[128:129], v[22:23], v[38:39]
	v_add_f32_dpp v140, v140, v140 row_half_mirror row_mask:0xf bank_mask:0xf
	v_add_f32_dpp v146, v146, v146 row_half_mirror row_mask:0xf bank_mask:0xf
	v_pk_mul_f32 v[130:131], v[24:25], v[40:41]
	v_pk_mul_f32 v[132:133], v[26:27], v[42:43]
	v_add_f32_dpp v140, v140, v140 quad_perm:[1,0,3,2] row_mask:0xf bank_mask:0xf
	v_add_f32_dpp v146, v146, v146 quad_perm:[1,0,3,2] row_mask:0xf bank_mask:0xf
	v_pk_mul_f32 v[134:135], v[28:29], v[44:45]
	v_add_f32_dpp v140, v140, v140 quad_perm:[2,3,0,1] row_mask:0xf bank_mask:0xf
	v_add_f32_dpp v146, v146, v146 quad_perm:[2,3,0,1] row_mask:0xf bank_mask:0xf
	s_waitcnt lgkmcnt(2)
	v_pk_fma_f32 v[22:23], v[140:141], v[70:71], v[128:129] op_sel_hi:[0,1,1] neg_lo:[1,0,0] neg_hi:[1,0,0]
	v_pk_fma_f32 v[24:25], v[140:141], v[72:73], v[130:131] op_sel_hi:[0,1,1] neg_lo:[1,0,0] neg_hi:[1,0,0]
	v_pk_fma_f32 v[26:27], v[140:141], v[74:75], v[132:133] op_sel_hi:[0,1,1] neg_lo:[1,0,0] neg_hi:[1,0,0]
	v_pk_fma_f32 v[28:29], v[140:141], v[76:77], v[134:135] op_sel_hi:[0,1,1] neg_lo:[1,0,0] neg_hi:[1,0,0]
	s_waitcnt lgkmcnt(0)
	v_pk_mul_f32 v[138:139], v[22:23], v[96:97]
	v_pk_fma_f32 v[138:139], v[24:25], v[98:99], v[138:139]
	v_pk_fma_f32 v[138:139], v[26:27], v[100:101], v[138:139]
	v_pk_fma_f32 v[138:139], v[28:29], v[102:103], v[138:139]
	v_add_f32_e32 v147, v138, v139
	s_nop 1
	v_add_f32_dpp v147, v147, v147 row_half_mirror row_mask:0xf bank_mask:0xf
	s_nop 1
	v_add_f32_dpp v147, v147, v147 quad_perm:[1,0,3,2] row_mask:0xf bank_mask:0xf
	s_nop 1
	v_add_f32_dpp v147, v147, v147 quad_perm:[2,3,0,1] row_mask:0xf bank_mask:0xf
	ds_write_b128 v113, v[144:147] offset:22576
.Lrw0_u2e0:
	s_add_u32 s28, s28, 16
	s_mov_b32 s35, 1
	s_waitcnt vmcnt(0)
	ds_write_b128 v110, v[58:61] offset:26624
	ds_write_b128 v110, v[62:65] offset:30720
	ds_write_b128 v110, v[66:69] offset:34816
	s_waitcnt lgkmcnt(0)
	s_barrier
	s_add_u32 s30, s28, 32
	v_add_u32_e32 v87, s30, v15
	v_med3_i32 v87, v87, 0, s29
	v_mad_i64_i32 v[104:105], vcc, v87, v12, v[6:7]
	global_load_dwordx4 v[58:61], v[104:105], off
	v_add_u32_e32 v87, s30, v16
	v_med3_i32 v87, v87, 0, s29
	v_mad_i64_i32 v[104:105], vcc, v87, v13, v[8:9]
	global_load_dwordx4 v[62:65], v[104:105], off
	v_add_u32_e32 v87, s30, v17
	v_med3_i32 v87, v87, 0, s29
	v_mad_i64_i32 v[104:105], vcc, v87, v14, v[10:11]
	global_load_dwordx4 v[66:69], v[104:105], off
	ds_read_b32 v89, v5 offset:22528
	ds_read_b32 v90, v5 offset:23552
	s_sub_u32 s98, s28, 16
	v_add_u32_e32 v87, s98, v127
	v_mad_i64_i32 v[104:105], vcc, v87, v20, v[18:19]
	s_waitcnt lgkmcnt(0)
	v_cvt_pk_bf16_f32 v89, v89, v90
	global_store_short v[104:105], v89, off
	global_store_short_d16_hi v[104:105], v89, off offset:32
	ds_read_b128 v[30:33], v93 offset:46080
	ds_read_b128 v[34:37], v93 offset:46096
	ds_read_b128 v[38:41], v93 offset:46112
	ds_read_b128 v[42:45], v93 offset:46128
	ds_read_b64 v[70:71], v1 offset:27008
	ds_read_b64 v[72:73], v1 offset:26624
	ds_read_b64 v[74:75], v1 offset:27392
	ds_read_b64 v[76:77], v1 offset:27136
	ds_read_b64 v[78:79], v1 offset:26752
	ds_read_b64 v[80:81], v1 offset:27520
	ds_read_b64 v[82:83], v1 offset:27264
	ds_read_b64 v[84:85], v1 offset:26880
	ds_read_b64 v[96:97], v1 offset:27648
	ds_read_b64 v[128:129], v2 offset:33536
	ds_read_b64 v[130:131], v2 offset:33664
	v_add_u32_e32 v87, s28, v127
	v_cmp_ne_u32_e32 vcc, 0, v87
	s_nop 1
	v_cndmask_b32_e64 v98, 0, 0.5, vcc
	v_cmp_ne_u32_e32 vcc, s29, v87
	s_nop 1
	v_cndmask_b32_e64 v100, 0, 0.5, vcc
	s_waitcnt lgkmcnt(8)
	v_lshlrev_b32_e32 v132, 16, v70
	v_and_b32_e32 v133, 0xffff0000, v70
	v_lshlrev_b32_e32 v134, 16, v71
	v_and_b32_e32 v135, 0xffff0000, v71
	v_lshlrev_b32_e32 v136, 16, v72
	v_and_b32_e32 v137, 0xffff0000, v72
	v_lshlrev_b32_e32 v138, 16, v73
	v_and_b32_e32 v139, 0xffff0000, v73
	v_lshlrev_b32_e32 v140, 16, v74
	v_and_b32_e32 v141, 0xffff0000, v74
	v_lshlrev_b32_e32 v142, 16, v75
	v_and_b32_e32 v143, 0xffff0000, v75
	v_pk_mul_f32 v[136:137], v[136:137], v[98:99] op_sel_hi:[1,0]
	v_pk_fma_f32 v[136:137], v[140:141], v[100:101], v[136:137] op_sel_hi:[1,0,1]
	v_pk_add_f32 v[136:137], v[136:137], v[132:133] neg_lo:[0,1] neg_hi:[0,1]
	v_pk_fma_f32 v[144:145], v[30:31], v[136:137], v[132:133]
	v_pk_mul_f32 v[138:139], v[138:139], v[98:99] op_sel_hi:[1,0]
	v_pk_fma_f32 v[138:139], v[142:143], v[100:101], v[138:139] op_sel_hi:[1,0,1]
	v_pk_add_f32 v[138:139], v[138:139], v[134:135] neg_lo:[0,1] neg_hi:[0,1]
	v_pk_fma_f32 v[146:147], v[32:33], v[138:139], v[134:135]
	ds_read_b128 v[30:33], v93 offset:46144
	s_waitcnt lgkmcnt(6)
	v_lshlrev_b32_e32 v132, 16, v76
	v_and_b32_e32 v133, 0xffff0000, v76
	v_lshlrev_b32_e32 v134, 16, v77
	v_and_b32_e32 v135, 0xffff0000, v77
	v_lshlrev_b32_e32 v136, 16, v78
	v_and_b32_e32 v137, 0xffff0000, v78
	v_lshlrev_b32_e32 v138, 16, v79
	v_and_b32_e32 v139, 0xffff0000, v79
	v_lshlrev_b32_e32 v140, 16, v80
	v_and_b32_e32 v141, 0xffff0000, v80
	v_lshlrev_b32_e32 v142, 16, v81
	v_and_b32_e32 v143, 0xffff0000, v81
	v_pk_mul_f32 v[136:137], v[136:137], v[98:99] op_sel_hi:[1,0]
	v_pk_fma_f32 v[136:137], v[140:141], v[100:101], v[136:137] op_sel_hi:[1,0,1]
	v_pk_add_f32 v[136:137], v[136:137], v[132:133] neg_lo:[0,1] neg_hi:[0,1]
	v_pk_fma_f32 v[102:103], v[34:35], v[136:137], v[132:133]
	v_pk_mul_f32 v[138:139], v[138:139], v[98:99] op_sel_hi:[1,0]
	v_pk_fma_f32 v[138:139], v[142:143], v[100:101], v[138:139] op_sel_hi:[1,0,1]
	v_pk_add_f32 v[138:139], v[138:139], v[134:135] neg_lo:[0,1] neg_hi:[0,1]
	v_pk_fma_f32 v[104:105], v[36:37], v[138:139], v[134:135]
	s_waitcnt lgkmcnt(3)
	v_lshlrev_b32_e32 v132, 16, v82
	v_and_b32_e32 v133, 0xffff0000, v82
	v_lshlrev_b32_e32 v134, 16, v83
	v_and_b32_e32 v135, 0xffff0000, v83
	v_lshlrev_b32_e32 v136, 16, v84
	v_and_b32_e32 v137, 0xffff0000, v84
	v_lshlrev_b32_e32 v138, 16, v85
	v_and_b32_e32 v139, 0xffff0000, v85
	v_lshlrev_b32_e32 v140, 16, v96
	v_and_b32_e32 v141, 0xffff0000, v96
	v_lshlrev_b32_e32 v142, 16, v97
	v_and_b32_e32 v143, 0xffff0000, v97
	v_pk_mul_f32 v[136:137], v[136:137], v[98:99] op_sel_hi:[1,0]
	v_pk_fma_f32 v[136:137], v[140:141], v[100:101], v[136:137] op_sel_hi:[1,0,1]
	v_pk_add_f32 v[136:137], v[136:137], v[132:133] neg_lo:[0,1] neg_hi:[0,1]
	v_pk_fma_f32 v[148:149], v[38:39], v[136:137], v[132:133]
	v_pk_mul_f32 v[138:139], v[138:139], v[98:99] op_sel_hi:[1,0]
	v_pk_fma_f32 v[138:139], v[142:143], v[100:101], v[138:139] op_sel_hi:[1,0,1]
	v_pk_add_f32 v[138:139], v[138:139], v[134:135] neg_lo:[0,1] neg_hi:[0,1]
	v_pk_fma_f32 v[150:151], v[40:41], v[138:139], v[134:135]
	s_waitcnt lgkmcnt(0)
	v_lshlrev_b32_e32 v132, 16, v128
	v_and_b32_e32 v133, 0xffff0000, v128
	v_lshlrev_b32_e32 v134, 16, v129
	v_and_b32_e32 v135, 0xffff0000, v129
	v_lshlrev_b32_e32 v136, 16, v130
	v_and_b32_e32 v137, 0xffff0000, v130
	v_lshlrev_b32_e32 v138, 16, v131
	v_and_b32_e32 v139, 0xffff0000, v131
	s_mov_b32 s98, 0xbf60028b
	v_mul_f32_e32 v132, s98, v132
	v_mul_f32_e32 v133, s98, v133
	v_mul_f32_e32 v134, s98, v134
	v_mul_f32_e32 v135, s98, v135
	v_exp_f32_e32 v132, v132
	v_exp_f32_e32 v133, v133
	v_exp_f32_e32 v134, v134
	v_exp_f32_e32 v135, v135
	v_pk_mul_f32 v[140:141], v[102:103], v[42:43]
	v_pk_mul_f32 v[142:143], v[104:105], v[44:45]
	v_pk_mul_f32 v[106:107], v[140:141], v[140:141]
	v_pk_fma_f32 v[106:107], v[142:143], v[142:143], v[106:107]
	v_add_f32_e32 v106, v106, v107
	s_nop 1
	v_add_f32_dpp v106, v106, v106 row_ror:8 row_mask:0xf bank_mask:0xf bound_ctrl:1
	s_nop 1
	v_add_f32_dpp v106, v106, v106 row_ror:4 row_mask:0xf bank_mask:0xf bound_ctrl:1
	s_nop 1
	v_add_f32_dpp v106, v106, v106 row_ror:2 row_mask:0xf bank_mask:0xf bound_ctrl:1
	s_nop 1
	v_add_f32_dpp v106, v106, v106 row_ror:1 row_mask:0xf bank_mask:0xf bound_ctrl:1
	v_add_f32_e32 v106, 0x2b8cbccc, v106
	v_rsq_f32_e32 v106, v106
	v_pk_mul_f32 v[148:149], v[148:149], s[40:41] op_sel_hi:[1,0]
	v_pk_mul_f32 v[150:151], v[150:151], s[40:41] op_sel_hi:[1,0]
	v_pk_mul_f32 v[140:141], v[140:141], v[106:107] op_sel_hi:[1,0]
	v_pk_mul_f32 v[142:143], v[142:143], v[106:107] op_sel_hi:[1,0]
	v_pk_add_f32 v[70:71], v[136:137], -1.0 op_sel_hi:[1,0]
	v_pk_add_f32 v[72:73], v[138:139], -1.0 op_sel_hi:[1,0]
	v_pk_fma_f32 v[70:71], v[30:31], v[70:71], 1.0 op_sel_hi:[1,1,0]
	v_pk_fma_f32 v[72:73], v[32:33], v[72:73], 1.0 op_sel_hi:[1,1,0]
	v_pk_mul_f32 v[70:71], v[102:103], v[70:71]
	v_pk_mul_f32 v[72:73], v[104:105], v[72:73]
	v_pk_mul_f32 v[74:75], v[140:141], v[136:137]
	v_pk_mul_f32 v[76:77], v[142:143], v[138:139]
	ds_write_b128 v3, v[140:143] offset:0
	ds_write_b128 v3, v[132:135] offset:4096
	ds_write_b128 v3, v[74:77] offset:8192
	ds_write_b128 v3, v[70:73] offset:12288
	ds_write_b128 v3, v[144:147] offset:16384
	ds_write_b128 v4, v[148:151]
	s_waitcnt lgkmcnt(0)
	s_barrier
	s_cmp_eq_u32 s18, 2
	s_cbranch_scc1 .Lrw0_u2s1
	ds_read_b128 v[30:33], v112 offset:0
	ds_read_b128 v[34:37], v112 offset:16
	ds_read_b128 v[78:81], v112 offset:12288
	ds_read_b128 v[82:85], v112 offset:12304
	ds_read_b32 v104, v108 offset:20480
	ds_read_b128 v[38:41], v112 offset:4096
	ds_read_b128 v[42:45], v112 offset:4112
	ds_read_b128 v[70:73], v112 offset:8192
	ds_read_b128 v[74:77], v112 offset:8208
	s_waitcnt lgkmcnt(7)
	v_pk_mul_f32 v[136:137], v[22:23], v[30:31]
	v_pk_fma_f32 v[136:137], v[24:25], v[32:33], v[136:137]
	v_pk_fma_f32 v[136:137], v[26:27], v[34:35], v[136:137]
	v_pk_fma_f32 v[136:137], v[28:29], v[36:37], v[136:137]
	ds_read_b128 v[30:33], v112 offset:256
	ds_read_b128 v[34:37], v112 offset:272
	ds_read_b128 v[96:99], v112 offset:16384
	ds_read_b128 v[100:103], v112 offset:16400
	v_add_f32_e32 v140, v136, v137
	s_waitcnt lgkmcnt(8)
	v_pk_mul_f32 v[128:129], v[78:79], v[104:105] op_sel_hi:[1,0]
	v_add_f32_dpp v140, v140, v140 row_half_mirror row_mask:0xf bank_mask:0xf
	v_pk_mul_f32 v[130:131], v[80:81], v[104:105] op_sel_hi:[1,0]
	v_pk_mul_f32 v[132:133], v[82:83], v[104:105] op_sel_hi:[1,0]
	v_pk_mul_f32 v[134:135], v[84:85], v[104:105] op_sel_hi:[1,0]
	ds_read_b128 v[78:81], v112 offset:12544
	ds_read_b128 v[82:85], v112 offset:12560
	ds_read_b32 v104, v108 offset:20608
	v_add_f32_dpp v140, v140, v140 quad_perm:[1,0,3,2] row_mask:0xf bank_mask:0xf
	s_waitcnt lgkmcnt(9)
	v_pk_fma_f32 v[128:129], v[22:23], v[38:39], v[128:129]
	v_pk_fma_f32 v[130:131], v[24:25], v[40:41], v[130:131]
	v_pk_fma_f32 v[132:133], v[26:27], v[42:43], v[132:133]
	v_add_f32_dpp v140, v140, v140 quad_perm:[2,3,0,1] row_mask:0xf bank_mask:0xf
	v_pk_fma_f32 v[134:135], v[28:29], v[44:45], v[134:135]
	ds_read_b128 v[38:41], v112 offset:4352
	ds_read_b128 v[42:45], v112 offset:4368
	s_waitcnt lgkmcnt(9)
	v_pk_fma_f32 v[22:23], v[140:141], v[70:71], v[128:129] op_sel_hi:[0,1,1] neg_lo:[1,0,0] neg_hi:[1,0,0]
	v_pk_fma_f32 v[24:25], v[140:141], v[72:73], v[130:131] op_sel_hi:[0,1,1] neg_lo:[1,0,0] neg_hi:[1,0,0]
	v_pk_fma_f32 v[26:27], v[140:141], v[74:75], v[132:133] op_sel_hi:[0,1,1] neg_lo:[1,0,0] neg_hi:[1,0,0]
	v_pk_fma_f32 v[28:29], v[140:141], v[76:77], v[134:135] op_sel_hi:[0,1,1] neg_lo:[1,0,0] neg_hi:[1,0,0]
	ds_read_b128 v[70:73], v112 offset:8448
	ds_read_b128 v[74:77], v112 offset:8464
	s_waitcnt lgkmcnt(7)
	v_pk_mul_f32 v[136:137], v[22:23], v[30:31]
	v_pk_mul_f32 v[138:139], v[22:23], v[96:97]
	v_pk_fma_f32 v[136:137], v[24:25], v[32:33], v[136:137]
	v_pk_fma_f32 v[138:139], v[24:25], v[98:99], v[138:139]
	v_pk_fma_f32 v[136:137], v[26:27], v[34:35], v[136:137]
	v_pk_fma_f32 v[138:139], v[26:27], v[100:101], v[138:139]
	v_pk_fma_f32 v[136:137], v[28:29], v[36:37], v[136:137]
	v_pk_fma_f32 v[138:139], v[28:29], v[102:103], v[138:139]
	ds_read_b128 v[30:33], v112 offset:512
	ds_read_b128 v[34:37], v112 offset:528
	ds_read_b128 v[96:99], v112 offset:16640
	ds_read_b128 v[100:103], v112 offset:16656
	v_add_f32_e32 v140, v136, v137
	v_add_f32_e32 v144, v138, v139
	s_waitcnt lgkmcnt(8)
	v_pk_mul_f32 v[128:129], v[78:79], v[104:105] op_sel_hi:[1,0]
	v_add_f32_dpp v140, v140, v140 row_half_mirror row_mask:0xf bank_mask:0xf
	v_add_f32_dpp v144, v144, v144 row_half_mirror row_mask:0xf bank_mask:0xf
	v_pk_mul_f32 v[130:131], v[80:81], v[104:105] op_sel_hi:[1,0]
	v_pk_mul_f32 v[132:133], v[82:83], v[104:105] op_sel_hi:[1,0]
	v_add_f32_dpp v140, v140, v140 quad_perm:[1,0,3,2] row_mask:0xf bank_mask:0xf
	v_add_f32_dpp v144, v144, v144 quad_perm:[1,0,3,2] row_mask:0xf bank_mask:0xf
	v_pk_mul_f32 v[134:135], v[84:85], v[104:105] op_sel_hi:[1,0]
	ds_read_b128 v[78:81], v112 offset:12800
	ds_read_b128 v[82:85], v112 offset:12816
	ds_read_b32 v104, v108 offset:20736
	s_waitcnt lgkmcnt(9)
	v_pk_fma_f32 v[128:129], v[22:23], v[38:39], v[128:129]
	v_add_f32_dpp v140, v140, v140 quad_perm:[2,3,0,1] row_mask:0xf bank_mask:0xf
	v_add_f32_dpp v144, v144, v144 quad_perm:[2,3,0,1] row_mask:0xf bank_mask:0xf
	v_pk_fma_f32 v[130:131], v[24:25], v[40:41], v[130:131]
	v_pk_fma_f32 v[132:133], v[26:27], v[42:43], v[132:133]
	v_pk_fma_f32 v[134:135], v[28:29], v[44:45], v[134:135]
	ds_read_b128 v[38:41], v112 offset:4608
	ds_read_b128 v[42:45], v112 offset:4624
	s_waitcnt lgkmcnt(9)
	v_pk_fma_f32 v[22:23], v[140:141], v[70:71], v[128:129] op_sel_hi:[0,1,1] neg_lo:[1,0,0] neg_hi:[1,0,0]
	v_pk_fma_f32 v[24:25], v[140:141], v[72:73], v[130:131] op_sel_hi:[0,1,1] neg_lo:[1,0,0] neg_hi:[1,0,0]
	v_pk_fma_f32 v[26:27], v[140:141], v[74:75], v[132:133] op_sel_hi:[0,1,1] neg_lo:[1,0,0] neg_hi:[1,0,0]
	v_pk_fma_f32 v[28:29], v[140:141], v[76:77], v[134:135] op_sel_hi:[0,1,1] neg_lo:[1,0,0] neg_hi:[1,0,0]
	ds_read_b128 v[70:73], v112 offset:8704
	ds_read_b128 v[74:77], v112 offset:8720
	s_waitcnt lgkmcnt(7)
	v_pk_mul_f32 v[136:137], v[22:23], v[30:31]
	v_pk_mul_f32 v[138:139], v[22:23], v[96:97]
	v_pk_fma_f32 v[136:137], v[24:25], v[32:33], v[136:137]
	v_pk_fma_f32 v[138:139], v[24:25], v[98:99], v[138:139]
	v_pk_fma_f32 v[136:137], v[26:27], v[34:35], v[136:137]
	v_pk_fma_f32 v[138:139], v[26:27], v[100:101], v[138:139]
	v_pk_fma_f32 v[136:137], v[28:29], v[36:37], v[136:137]
	v_pk_fma_f32 v[138:139], v[28:29], v[102:103], v[138:139]
	ds_read_b128 v[30:33], v112 offset:768
	ds_read_b128 v[34:37], v112 offset:784
	ds_read_b128 v[96:99], v112 offset:16896
	ds_read_b128 v[100:103], v112 offset:16912
	v_add_f32_e32 v140, v136, v137
	v_add_f32_e32 v145, v138, v139
	s_waitcnt lgkmcnt(8)
	v_pk_mul_f32 v[128:129], v[78:79], v[104:105] op_sel_hi:[1,0]
	v_add_f32_dpp v140, v140, v140 row_half_mirror row_mask:0xf bank_mask:0xf
	v_add_f32_dpp v145, v145, v145 row_half_mirror row_mask:0xf bank_mask:0xf
	v_pk_mul_f32 v[130:131], v[80:81], v[104:105] op_sel_hi:[1,0]
	v_pk_mul_f32 v[132:133], v[82:83], v[104:105] op_sel_hi:[1,0]
	v_add_f32_dpp v140, v140, v140 quad_perm:[1,0,3,2] row_mask:0xf bank_mask:0xf
	v_add_f32_dpp v145, v145, v145 quad_perm:[1,0,3,2] row_mask:0xf bank_mask:0xf
	v_pk_mul_f32 v[134:135], v[84:85], v[104:105] op_sel_hi:[1,0]
	ds_read_b128 v[78:81], v112 offset:13056
	ds_read_b128 v[82:85], v112 offset:13072
	ds_read_b32 v104, v108 offset:20864
	s_waitcnt lgkmcnt(9)
	v_pk_fma_f32 v[128:129], v[22:23], v[38:39], v[128:129]
	v_add_f32_dpp v140, v140, v140 quad_perm:[2,3,0,1] row_mask:0xf bank_mask:0xf
	v_add_f32_dpp v145, v145, v145 quad_perm:[2,3,0,1] row_mask:0xf bank_mask:0xf
	v_pk_fma_f32 v[130:131], v[24:25], v[40:41], v[130:131]
	v_pk_fma_f32 v[132:133], v[26:27], v[42:43], v[132:133]
	v_pk_fma_f32 v[134:135], v[28:29], v[44:45], v[134:135]
	ds_read_b128 v[38:41], v112 offset:4864
	ds_read_b128 v[42:45], v112 offset:4880
	s_waitcnt lgkmcnt(9)
	v_pk_fma_f32 v[22:23], v[140:141], v[70:71], v[128:129] op_sel_hi:[0,1,1] neg_lo:[1,0,0] neg_hi:[1,0,0]
	v_pk_fma_f32 v[24:25], v[140:141], v[72:73], v[130:131] op_sel_hi:[0,1,1] neg_lo:[1,0,0] neg_hi:[1,0,0]
	v_pk_fma_f32 v[26:27], v[140:141], v[74:75], v[132:133] op_sel_hi:[0,1,1] neg_lo:[1,0,0] neg_hi:[1,0,0]
	v_pk_fma_f32 v[28:29], v[140:141], v[76:77], v[134:135] op_sel_hi:[0,1,1] neg_lo:[1,0,0] neg_hi:[1,0,0]
	ds_read_b128 v[70:73], v112 offset:8960
	ds_read_b128 v[74:77], v112 offset:8976
	s_waitcnt lgkmcnt(7)
	v_pk_mul_f32 v[136:137], v[22:23], v[30:31]
	v_pk_mul_f32 v[138:139], v[22:23], v[96:97]
	v_pk_fma_f32 v[136:137], v[24:25], v[32:33], v[136:137]
	v_pk_fma_f32 v[138:139], v[24:25], v[98:99], v[138:139]
	v_pk_fma_f32 v[136:137], v[26:27], v[34:35], v[136:137]
	v_pk_fma_f32 v[138:139], v[26:27], v[100:101], v[138:139]
	v_pk_fma_f32 v[136:137], v[28:29], v[36:37], v[136:137]
	v_pk_fma_f32 v[138:139], v[28:29], v[102:103], v[138:139]
	ds_read_b128 v[30:33], v112 offset:1024
	ds_read_b128 v[34:37], v112 offset:1040
	ds_read_b128 v[96:99], v112 offset:17152
	ds_read_b128 v[100:103], v112 offset:17168
	v_add_f32_e32 v140, v136, v137
	v_add_f32_e32 v146, v138, v139
	s_waitcnt lgkmcnt(8)
	v_pk_mul_f32 v[128:129], v[78:79], v[104:105] op_sel_hi:[1,0]
	v_add_f32_dpp v140, v140, v140 row_half_mirror row_mask:0xf bank_mask:0xf
	v_add_f32_dpp v146, v146, v146 row_half_mirror row_mask:0xf bank_mask:0xf
	v_pk_mul_f32 v[130:131], v[80:81], v[104:105] op_sel_hi:[1,0]
	v_pk_mul_f32 v[132:133], v[82:83], v[104:105] op_sel_hi:[1,0]
	v_add_f32_dpp v140, v140, v140 quad_perm:[1,0,3,2] row_mask:0xf bank_mask:0xf
	v_add_f32_dpp v146, v146, v146 quad_perm:[1,0,3,2] row_mask:0xf bank_mask:0xf
	v_pk_mul_f32 v[134:135], v[84:85], v[104:105] op_sel_hi:[1,0]
	ds_read_b128 v[78:81], v112 offset:13312
	ds_read_b128 v[82:85], v112 offset:13328
	ds_read_b32 v104, v108 offset:20992
	s_waitcnt lgkmcnt(9)
	v_pk_fma_f32 v[128:129], v[22:23], v[38:39], v[128:129]
	v_add_f32_dpp v140, v140, v140 quad_perm:[2,3,0,1] row_mask:0xf bank_mask:0xf
	v_add_f32_dpp v146, v146, v146 quad_perm:[2,3,0,1] row_mask:0xf bank_mask:0xf
	v_pk_fma_f32 v[130:131], v[24:25], v[40:41], v[130:131]
	v_pk_fma_f32 v[132:133], v[26:27], v[42:43], v[132:133]
	v_pk_fma_f32 v[134:135], v[28:29], v[44:45], v[134:135]
	ds_read_b128 v[38:41], v112 offset:5120
	ds_read_b128 v[42:45], v112 offset:5136
	s_waitcnt lgkmcnt(9)
	v_pk_fma_f32 v[22:23], v[140:141], v[70:71], v[128:129] op_sel_hi:[0,1,1] neg_lo:[1,0,0] neg_hi:[1,0,0]
	v_pk_fma_f32 v[24:25], v[140:141], v[72:73], v[130:131] op_sel_hi:[0,1,1] neg_lo:[1,0,0] neg_hi:[1,0,0]
	v_pk_fma_f32 v[26:27], v[140:141], v[74:75], v[132:133] op_sel_hi:[0,1,1] neg_lo:[1,0,0] neg_hi:[1,0,0]
	v_pk_fma_f32 v[28:29], v[140:141], v[76:77], v[134:135] op_sel_hi:[0,1,1] neg_lo:[1,0,0] neg_hi:[1,0,0]
	ds_read_b128 v[70:73], v112 offset:9216
	ds_read_b128 v[74:77], v112 offset:9232
	s_waitcnt lgkmcnt(7)
	v_pk_mul_f32 v[136:137], v[22:23], v[30:31]
	v_pk_mul_f32 v[138:139], v[22:23], v[96:97]
	v_pk_fma_f32 v[136:137], v[24:25], v[32:33], v[136:137]
	v_pk_fma_f32 v[138:139], v[24:25], v[98:99], v[138:139]
	v_pk_fma_f32 v[136:137], v[26:27], v[34:35], v[136:137]
	v_pk_fma_f32 v[138:139], v[26:27], v[100:101], v[138:139]
	v_pk_fma_f32 v[136:137], v[28:29], v[36:37], v[136:137]
	v_pk_fma_f32 v[138:139], v[28:29], v[102:103], v[138:139]
	ds_read_b128 v[30:33], v112 offset:1280
	ds_read_b128 v[34:37], v112 offset:1296
	ds_read_b128 v[96:99], v112 offset:17408
	ds_read_b128 v[100:103], v112 offset:17424
	v_add_f32_e32 v140, v136, v137
	v_add_f32_e32 v147, v138, v139
	s_waitcnt lgkmcnt(8)
	v_pk_mul_f32 v[128:129], v[78:79], v[104:105] op_sel_hi:[1,0]
	v_add_f32_dpp v140, v140, v140 row_half_mirror row_mask:0xf bank_mask:0xf
	v_add_f32_dpp v147, v147, v147 row_half_mirror row_mask:0xf bank_mask:0xf
	v_pk_mul_f32 v[130:131], v[80:81], v[104:105] op_sel_hi:[1,0]
	v_pk_mul_f32 v[132:133], v[82:83], v[104:105] op_sel_hi:[1,0]
	v_add_f32_dpp v140, v140, v140 quad_perm:[1,0,3,2] row_mask:0xf bank_mask:0xf
	v_add_f32_dpp v147, v147, v147 quad_perm:[1,0,3,2] row_mask:0xf bank_mask:0xf
	v_pk_mul_f32 v[134:135], v[84:85], v[104:105] op_sel_hi:[1,0]
	ds_read_b128 v[78:81], v112 offset:13568
	ds_read_b128 v[82:85], v112 offset:13584
	ds_read_b32 v104, v108 offset:21120
	s_waitcnt lgkmcnt(9)
	v_pk_fma_f32 v[128:129], v[22:23], v[38:39], v[128:129]
	v_add_f32_dpp v140, v140, v140 quad_perm:[2,3,0,1] row_mask:0xf bank_mask:0xf
	v_add_f32_dpp v147, v147, v147 quad_perm:[2,3,0,1] row_mask:0xf bank_mask:0xf
	v_pk_fma_f32 v[130:131], v[24:25], v[40:41], v[130:131]
	v_pk_fma_f32 v[132:133], v[26:27], v[42:43], v[132:133]
	v_pk_fma_f32 v[134:135], v[28:29], v[44:45], v[134:135]
	ds_read_b128 v[38:41], v112 offset:5376
	ds_read_b128 v[42:45], v112 offset:5392
	s_waitcnt lgkmcnt(9)
	v_pk_fma_f32 v[22:23], v[140:141], v[70:71], v[128:129] op_sel_hi:[0,1,1] neg_lo:[1,0,0] neg_hi:[1,0,0]
	v_pk_fma_f32 v[24:25], v[140:141], v[72:73], v[130:131] op_sel_hi:[0,1,1] neg_lo:[1,0,0] neg_hi:[1,0,0]
	v_pk_fma_f32 v[26:27], v[140:141], v[74:75], v[132:133] op_sel_hi:[0,1,1] neg_lo:[1,0,0] neg_hi:[1,0,0]
	v_pk_fma_f32 v[28:29], v[140:141], v[76:77], v[134:135] op_sel_hi:[0,1,1] neg_lo:[1,0,0] neg_hi:[1,0,0]
	ds_read_b128 v[70:73], v112 offset:9472
	ds_read_b128 v[74:77], v112 offset:9488
	ds_write_b128 v113, v[144:147] offset:24576
	s_waitcnt lgkmcnt(8)
	v_pk_mul_f32 v[136:137], v[22:23], v[30:31]
	v_pk_mul_f32 v[138:139], v[22:23], v[96:97]
	v_pk_fma_f32 v[136:137], v[24:25], v[32:33], v[136:137]
	v_pk_fma_f32 v[138:139], v[24:25], v[98:99], v[138:139]
	v_pk_fma_f32 v[136:137], v[26:27], v[34:35], v[136:137]
	v_pk_fma_f32 v[138:139], v[26:27], v[100:101], v[138:139]
	v_pk_fma_f32 v[136:137], v[28:29], v[36:37], v[136:137]
	v_pk_fma_f32 v[138:139], v[28:29], v[102:103], v[138:139]
	ds_read_b128 v[30:33], v112 offset:1536
	ds_read_b128 v[34:37], v112 offset:1552
	ds_read_b128 v[96:99], v112 offset:17664
	ds_read_b128 v[100:103], v112 offset:17680
	v_add_f32_e32 v140, v136, v137
	v_add_f32_e32 v144, v138, v139
	s_waitcnt lgkmcnt(9)
	v_pk_mul_f32 v[128:129], v[78:79], v[104:105] op_sel_hi:[1,0]
	v_add_f32_dpp v140, v140, v140 row_half_mirror row_mask:0xf bank_mask:0xf
	v_add_f32_dpp v144, v144, v144 row_half_mirror row_mask:0xf bank_mask:0xf
	v_pk_mul_f32 v[130:131], v[80:81], v[104:105] op_sel_hi:[1,0]
	v_pk_mul_f32 v[132:133], v[82:83], v[104:105] op_sel_hi:[1,0]
	v_add_f32_dpp v140, v140, v140 quad_perm:[1,0,3,2] row_mask:0xf bank_mask:0xf
	v_add_f32_dpp v144, v144, v144 quad_perm:[1,0,3,2] row_mask:0xf bank_mask:0xf
	v_pk_mul_f32 v[134:135], v[84:85], v[104:105] op_sel_hi:[1,0]
	ds_read_b128 v[78:81], v112 offset:13824
	ds_read_b128 v[82:85], v112 offset:13840
	ds_read_b32 v104, v108 offset:21248
	s_waitcnt lgkmcnt(10)
	v_pk_fma_f32 v[128:129], v[22:23], v[38:39], v[128:129]
	v_add_f32_dpp v140, v140, v140 quad_perm:[2,3,0,1] row_mask:0xf bank_mask:0xf
	v_add_f32_dpp v144, v144, v144 quad_perm:[2,3,0,1] row_mask:0xf bank_mask:0xf
	v_pk_fma_f32 v[130:131], v[24:25], v[40:41], v[130:131]
	v_pk_fma_f32 v[132:133], v[26:27], v[42:43], v[132:133]
	v_pk_fma_f32 v[134:135], v[28:29], v[44:45], v[134:135]
	ds_read_b128 v[38:41], v112 offset:5632
	ds_read_b128 v[42:45], v112 offset:5648
	s_waitcnt lgkmcnt(10)
	v_pk_fma_f32 v[22:23], v[140:141], v[70:71], v[128:129] op_sel_hi:[0,1,1] neg_lo:[1,0,0] neg_hi:[1,0,0]
	v_pk_fma_f32 v[24:25], v[140:141], v[72:73], v[130:131] op_sel_hi:[0,1,1] neg_lo:[1,0,0] neg_hi:[1,0,0]
	v_pk_fma_f32 v[26:27], v[140:141], v[74:75], v[132:133] op_sel_hi:[0,1,1] neg_lo:[1,0,0] neg_hi:[1,0,0]
	v_pk_fma_f32 v[28:29], v[140:141], v[76:77], v[134:135] op_sel_hi:[0,1,1] neg_lo:[1,0,0] neg_hi:[1,0,0]
	ds_read_b128 v[70:73], v112 offset:9728
	ds_read_b128 v[74:77], v112 offset:9744
	s_waitcnt lgkmcnt(7)
	v_pk_mul_f32 v[136:137], v[22:23], v[30:31]
	v_pk_mul_f32 v[138:139], v[22:23], v[96:97]
	v_pk_fma_f32 v[136:137], v[24:25], v[32:33], v[136:137]
	v_pk_fma_f32 v[138:139], v[24:25], v[98:99], v[138:139]
	v_pk_fma_f32 v[136:137], v[26:27], v[34:35], v[136:137]
	v_pk_fma_f32 v[138:139], v[26:27], v[100:101], v[138:139]
	v_pk_fma_f32 v[136:137], v[28:29], v[36:37], v[136:137]
	v_pk_fma_f32 v[138:139], v[28:29], v[102:103], v[138:139]
	ds_read_b128 v[30:33], v112 offset:1792
	ds_read_b128 v[34:37], v112 offset:1808
	ds_read_b128 v[96:99], v112 offset:17920
	ds_read_b128 v[100:103], v112 offset:17936
	v_add_f32_e32 v140, v136, v137
	v_add_f32_e32 v145, v138, v139
	s_waitcnt lgkmcnt(8)
	v_pk_mul_f32 v[128:129], v[78:79], v[104:105] op_sel_hi:[1,0]
	v_add_f32_dpp v140, v140, v140 row_half_mirror row_mask:0xf bank_mask:0xf
	v_add_f32_dpp v145, v145, v145 row_half_mirror row_mask:0xf bank_mask:0xf
	v_pk_mul_f32 v[130:131], v[80:81], v[104:105] op_sel_hi:[1,0]
	v_pk_mul_f32 v[132:133], v[82:83], v[104:105] op_sel_hi:[1,0]
	v_add_f32_dpp v140, v140, v140 quad_perm:[1,0,3,2] row_mask:0xf bank_mask:0xf
	v_add_f32_dpp v145, v145, v145 quad_perm:[1,0,3,2] row_mask:0xf bank_mask:0xf
	v_pk_mul_f32 v[134:135], v[84:85], v[104:105] op_sel_hi:[1,0]
	ds_read_b128 v[78:81], v112 offset:14080
	ds_read_b128 v[82:85], v112 offset:14096
	ds_read_b32 v104, v108 offset:21376
	s_waitcnt lgkmcnt(9)
	v_pk_fma_f32 v[128:129], v[22:23], v[38:39], v[128:129]
	v_add_f32_dpp v140, v140, v140 quad_perm:[2,3,0,1] row_mask:0xf bank_mask:0xf
	v_add_f32_dpp v145, v145, v145 quad_perm:[2,3,0,1] row_mask:0xf bank_mask:0xf
	v_pk_fma_f32 v[130:131], v[24:25], v[40:41], v[130:131]
	v_pk_fma_f32 v[132:133], v[26:27], v[42:43], v[132:133]
	v_pk_fma_f32 v[134:135], v[28:29], v[44:45], v[134:135]
	ds_read_b128 v[38:41], v112 offset:5888
	ds_read_b128 v[42:45], v112 offset:5904
	s_waitcnt lgkmcnt(9)
	v_pk_fma_f32 v[22:23], v[140:141], v[70:71], v[128:129] op_sel_hi:[0,1,1] neg_lo:[1,0,0] neg_hi:[1,0,0]
	v_pk_fma_f32 v[24:25], v[140:141], v[72:73], v[130:131] op_sel_hi:[0,1,1] neg_lo:[1,0,0] neg_hi:[1,0,0]
	v_pk_fma_f32 v[26:27], v[140:141], v[74:75], v[132:133] op_sel_hi:[0,1,1] neg_lo:[1,0,0] neg_hi:[1,0,0]
	v_pk_fma_f32 v[28:29], v[140:141], v[76:77], v[134:135] op_sel_hi:[0,1,1] neg_lo:[1,0,0] neg_hi:[1,0,0]
	ds_read_b128 v[70:73], v112 offset:9984
	ds_read_b128 v[74:77], v112 offset:10000
	s_waitcnt lgkmcnt(7)
	v_pk_mul_f32 v[136:137], v[22:23], v[30:31]
	v_pk_mul_f32 v[138:139], v[22:23], v[96:97]
	v_pk_fma_f32 v[136:137], v[24:25], v[32:33], v[136:137]
	v_pk_fma_f32 v[138:139], v[24:25], v[98:99], v[138:139]
	v_pk_fma_f32 v[136:137], v[26:27], v[34:35], v[136:137]
	v_pk_fma_f32 v[138:139], v[26:27], v[100:101], v[138:139]
	v_pk_fma_f32 v[136:137], v[28:29], v[36:37], v[136:137]
	v_pk_fma_f32 v[138:139], v[28:29], v[102:103], v[138:139]
	ds_read_b128 v[30:33], v112 offset:2048
	ds_read_b128 v[34:37], v112 offset:2064
	ds_read_b128 v[96:99], v112 offset:18176
	ds_read_b128 v[100:103], v112 offset:18192
	v_add_f32_e32 v140, v136, v137
	v_add_f32_e32 v146, v138, v139
	s_waitcnt lgkmcnt(8)
	v_pk_mul_f32 v[128:129], v[78:79], v[104:105] op_sel_hi:[1,0]
	v_add_f32_dpp v140, v140, v140 row_half_mirror row_mask:0xf bank_mask:0xf
	v_add_f32_dpp v146, v146, v146 row_half_mirror row_mask:0xf bank_mask:0xf
	v_pk_mul_f32 v[130:131], v[80:81], v[104:105] op_sel_hi:[1,0]
	v_pk_mul_f32 v[132:133], v[82:83], v[104:105] op_sel_hi:[1,0]
	v_add_f32_dpp v140, v140, v140 quad_perm:[1,0,3,2] row_mask:0xf bank_mask:0xf
	v_add_f32_dpp v146, v146, v146 quad_perm:[1,0,3,2] row_mask:0xf bank_mask:0xf
	v_pk_mul_f32 v[134:135], v[84:85], v[104:105] op_sel_hi:[1,0]
	ds_read_b128 v[78:81], v112 offset:14336
	ds_read_b128 v[82:85], v112 offset:14352
	ds_read_b32 v104, v108 offset:21504
	s_waitcnt lgkmcnt(9)
	v_pk_fma_f32 v[128:129], v[22:23], v[38:39], v[128:129]
	v_add_f32_dpp v140, v140, v140 quad_perm:[2,3,0,1] row_mask:0xf bank_mask:0xf
	v_add_f32_dpp v146, v146, v146 quad_perm:[2,3,0,1] row_mask:0xf bank_mask:0xf
	v_pk_fma_f32 v[130:131], v[24:25], v[40:41], v[130:131]
	v_pk_fma_f32 v[132:133], v[26:27], v[42:43], v[132:133]
	v_pk_fma_f32 v[134:135], v[28:29], v[44:45], v[134:135]
	ds_read_b128 v[38:41], v112 offset:6144
	ds_read_b128 v[42:45], v112 offset:6160
	s_waitcnt lgkmcnt(9)
	v_pk_fma_f32 v[22:23], v[140:141], v[70:71], v[128:129] op_sel_hi:[0,1,1] neg_lo:[1,0,0] neg_hi:[1,0,0]
	v_pk_fma_f32 v[24:25], v[140:141], v[72:73], v[130:131] op_sel_hi:[0,1,1] neg_lo:[1,0,0] neg_hi:[1,0,0]
	v_pk_fma_f32 v[26:27], v[140:141], v[74:75], v[132:133] op_sel_hi:[0,1,1] neg_lo:[1,0,0] neg_hi:[1,0,0]
	v_pk_fma_f32 v[28:29], v[140:141], v[76:77], v[134:135] op_sel_hi:[0,1,1] neg_lo:[1,0,0] neg_hi:[1,0,0]
	ds_read_b128 v[70:73], v112 offset:10240
	ds_read_b128 v[74:77], v112 offset:10256
	s_waitcnt lgkmcnt(7)
	v_pk_mul_f32 v[136:137], v[22:23], v[30:31]
	v_pk_mul_f32 v[138:139], v[22:23], v[96:97]
	v_pk_fma_f32 v[136:137], v[24:25], v[32:33], v[136:137]
	v_pk_fma_f32 v[138:139], v[24:25], v[98:99], v[138:139]
	v_pk_fma_f32 v[136:137], v[26:27], v[34:35], v[136:137]
	v_pk_fma_f32 v[138:139], v[26:27], v[100:101], v[138:139]
	v_pk_fma_f32 v[136:137], v[28:29], v[36:37], v[136:137]
	v_pk_fma_f32 v[138:139], v[28:29], v[102:103], v[138:139]
	ds_read_b128 v[30:33], v112 offset:2304
	ds_read_b128 v[34:37], v112 offset:2320
	ds_read_b128 v[96:99], v112 offset:18432
	ds_read_b128 v[100:103], v112 offset:18448
	v_add_f32_e32 v140, v136, v137
	v_add_f32_e32 v147, v138, v139
	s_waitcnt lgkmcnt(8)
	v_pk_mul_f32 v[128:129], v[78:79], v[104:105] op_sel_hi:[1,0]
	v_add_f32_dpp v140, v140, v140 row_half_mirror row_mask:0xf bank_mask:0xf
	v_add_f32_dpp v147, v147, v147 row_half_mirror row_mask:0xf bank_mask:0xf
	v_pk_mul_f32 v[130:131], v[80:81], v[104:105] op_sel_hi:[1,0]
	v_pk_mul_f32 v[132:133], v[82:83], v[104:105] op_sel_hi:[1,0]
	v_add_f32_dpp v140, v140, v140 quad_perm:[1,0,3,2] row_mask:0xf bank_mask:0xf
	v_add_f32_dpp v147, v147, v147 quad_perm:[1,0,3,2] row_mask:0xf bank_mask:0xf
	v_pk_mul_f32 v[134:135], v[84:85], v[104:105] op_sel_hi:[1,0]
	ds_read_b128 v[78:81], v112 offset:14592
	ds_read_b128 v[82:85], v112 offset:14608
	ds_read_b32 v104, v108 offset:21632
	s_waitcnt lgkmcnt(9)
	v_pk_fma_f32 v[128:129], v[22:23], v[38:39], v[128:129]
	v_add_f32_dpp v140, v140, v140 quad_perm:[2,3,0,1] row_mask:0xf bank_mask:0xf
	v_add_f32_dpp v147, v147, v147 quad_perm:[2,3,0,1] row_mask:0xf bank_mask:0xf
	v_pk_fma_f32 v[130:131], v[24:25], v[40:41], v[130:131]
	v_pk_fma_f32 v[132:133], v[26:27], v[42:43], v[132:133]
	v_pk_fma_f32 v[134:135], v[28:29], v[44:45], v[134:135]
	ds_read_b128 v[38:41], v112 offset:6400
	ds_read_b128 v[42:45], v112 offset:6416
	s_waitcnt lgkmcnt(9)
	v_pk_fma_f32 v[22:23], v[140:141], v[70:71], v[128:129] op_sel_hi:[0,1,1] neg_lo:[1,0,0] neg_hi:[1,0,0]
	v_pk_fma_f32 v[24:25], v[140:141], v[72:73], v[130:131] op_sel_hi:[0,1,1] neg_lo:[1,0,0] neg_hi:[1,0,0]
	v_pk_fma_f32 v[26:27], v[140:141], v[74:75], v[132:133] op_sel_hi:[0,1,1] neg_lo:[1,0,0] neg_hi:[1,0,0]
	v_pk_fma_f32 v[28:29], v[140:141], v[76:77], v[134:135] op_sel_hi:[0,1,1] neg_lo:[1,0,0] neg_hi:[1,0,0]
	ds_read_b128 v[70:73], v112 offset:10496
	ds_read_b128 v[74:77], v112 offset:10512
	ds_write_b128 v113, v[144:147] offset:24592
	s_waitcnt lgkmcnt(8)
	v_pk_mul_f32 v[136:137], v[22:23], v[30:31]
	v_pk_mul_f32 v[138:139], v[22:23], v[96:97]
	v_pk_fma_f32 v[136:137], v[24:25], v[32:33], v[136:137]
	v_pk_fma_f32 v[138:139], v[24:25], v[98:99], v[138:139]
	v_pk_fma_f32 v[136:137], v[26:27], v[34:35], v[136:137]
	v_pk_fma_f32 v[138:139], v[26:27], v[100:101], v[138:139]
	v_pk_fma_f32 v[136:137], v[28:29], v[36:37], v[136:137]
	v_pk_fma_f32 v[138:139], v[28:29], v[102:103], v[138:139]
	ds_read_b128 v[30:33], v112 offset:2560
	ds_read_b128 v[34:37], v112 offset:2576
	ds_read_b128 v[96:99], v112 offset:18688
	ds_read_b128 v[100:103], v112 offset:18704
	v_add_f32_e32 v140, v136, v137
	v_add_f32_e32 v144, v138, v139
	s_waitcnt lgkmcnt(9)
	v_pk_mul_f32 v[128:129], v[78:79], v[104:105] op_sel_hi:[1,0]
	v_add_f32_dpp v140, v140, v140 row_half_mirror row_mask:0xf bank_mask:0xf
	v_add_f32_dpp v144, v144, v144 row_half_mirror row_mask:0xf bank_mask:0xf
	v_pk_mul_f32 v[130:131], v[80:81], v[104:105] op_sel_hi:[1,0]
	v_pk_mul_f32 v[132:133], v[82:83], v[104:105] op_sel_hi:[1,0]
	v_add_f32_dpp v140, v140, v140 quad_perm:[1,0,3,2] row_mask:0xf bank_mask:0xf
	v_add_f32_dpp v144, v144, v144 quad_perm:[1,0,3,2] row_mask:0xf bank_mask:0xf
	v_pk_mul_f32 v[134:135], v[84:85], v[104:105] op_sel_hi:[1,0]
	ds_read_b128 v[78:81], v112 offset:14848
	ds_read_b128 v[82:85], v112 offset:14864
	ds_read_b32 v104, v108 offset:21760
	s_waitcnt lgkmcnt(10)
	v_pk_fma_f32 v[128:129], v[22:23], v[38:39], v[128:129]
	v_add_f32_dpp v140, v140, v140 quad_perm:[2,3,0,1] row_mask:0xf bank_mask:0xf
	v_add_f32_dpp v144, v144, v144 quad_perm:[2,3,0,1] row_mask:0xf bank_mask:0xf
	v_pk_fma_f32 v[130:131], v[24:25], v[40:41], v[130:131]
	v_pk_fma_f32 v[132:133], v[26:27], v[42:43], v[132:133]
	v_pk_fma_f32 v[134:135], v[28:29], v[44:45], v[134:135]
	ds_read_b128 v[38:41], v112 offset:6656
	ds_read_b128 v[42:45], v112 offset:6672
	s_waitcnt lgkmcnt(10)
	v_pk_fma_f32 v[22:23], v[140:141], v[70:71], v[128:129] op_sel_hi:[0,1,1] neg_lo:[1,0,0] neg_hi:[1,0,0]
	v_pk_fma_f32 v[24:25], v[140:141], v[72:73], v[130:131] op_sel_hi:[0,1,1] neg_lo:[1,0,0] neg_hi:[1,0,0]
	v_pk_fma_f32 v[26:27], v[140:141], v[74:75], v[132:133] op_sel_hi:[0,1,1] neg_lo:[1,0,0] neg_hi:[1,0,0]
	v_pk_fma_f32 v[28:29], v[140:141], v[76:77], v[134:135] op_sel_hi:[0,1,1] neg_lo:[1,0,0] neg_hi:[1,0,0]
	ds_read_b128 v[70:73], v112 offset:10752
	ds_read_b128 v[74:77], v112 offset:10768
	s_waitcnt lgkmcnt(7)
	v_pk_mul_f32 v[136:137], v[22:23], v[30:31]
	v_pk_mul_f32 v[138:139], v[22:23], v[96:97]
	v_pk_fma_f32 v[136:137], v[24:25], v[32:33], v[136:137]
	v_pk_fma_f32 v[138:139], v[24:25], v[98:99], v[138:139]
	v_pk_fma_f32 v[136:137], v[26:27], v[34:35], v[136:137]
	v_pk_fma_f32 v[138:139], v[26:27], v[100:101], v[138:139]
	v_pk_fma_f32 v[136:137], v[28:29], v[36:37], v[136:137]
	v_pk_fma_f32 v[138:139], v[28:29], v[102:103], v[138:139]
	ds_read_b128 v[30:33], v112 offset:2816
	ds_read_b128 v[34:37], v112 offset:2832
	ds_read_b128 v[96:99], v112 offset:18944
	ds_read_b128 v[100:103], v112 offset:18960
	v_add_f32_e32 v140, v136, v137
	v_add_f32_e32 v145, v138, v139
	s_waitcnt lgkmcnt(8)
	v_pk_mul_f32 v[128:129], v[78:79], v[104:105] op_sel_hi:[1,0]
	v_add_f32_dpp v140, v140, v140 row_half_mirror row_mask:0xf bank_mask:0xf
	v_add_f32_dpp v145, v145, v145 row_half_mirror row_mask:0xf bank_mask:0xf
	v_pk_mul_f32 v[130:131], v[80:81], v[104:105] op_sel_hi:[1,0]
	v_pk_mul_f32 v[132:133], v[82:83], v[104:105] op_sel_hi:[1,0]
	v_add_f32_dpp v140, v140, v140 quad_perm:[1,0,3,2] row_mask:0xf bank_mask:0xf
	v_add_f32_dpp v145, v145, v145 quad_perm:[1,0,3,2] row_mask:0xf bank_mask:0xf
	v_pk_mul_f32 v[134:135], v[84:85], v[104:105] op_sel_hi:[1,0]
	ds_read_b128 v[78:81], v112 offset:15104
	ds_read_b128 v[82:85], v112 offset:15120
	ds_read_b32 v104, v108 offset:21888
	s_waitcnt lgkmcnt(9)
	v_pk_fma_f32 v[128:129], v[22:23], v[38:39], v[128:129]
	v_add_f32_dpp v140, v140, v140 quad_perm:[2,3,0,1] row_mask:0xf bank_mask:0xf
	v_add_f32_dpp v145, v145, v145 quad_perm:[2,3,0,1] row_mask:0xf bank_mask:0xf
	v_pk_fma_f32 v[130:131], v[24:25], v[40:41], v[130:131]
	v_pk_fma_f32 v[132:133], v[26:27], v[42:43], v[132:133]
	v_pk_fma_f32 v[134:135], v[28:29], v[44:45], v[134:135]
	ds_read_b128 v[38:41], v112 offset:6912
	ds_read_b128 v[42:45], v112 offset:6928
	s_waitcnt lgkmcnt(9)
	v_pk_fma_f32 v[22:23], v[140:141], v[70:71], v[128:129] op_sel_hi:[0,1,1] neg_lo:[1,0,0] neg_hi:[1,0,0]
	v_pk_fma_f32 v[24:25], v[140:141], v[72:73], v[130:131] op_sel_hi:[0,1,1] neg_lo:[1,0,0] neg_hi:[1,0,0]
	v_pk_fma_f32 v[26:27], v[140:141], v[74:75], v[132:133] op_sel_hi:[0,1,1] neg_lo:[1,0,0] neg_hi:[1,0,0]
	v_pk_fma_f32 v[28:29], v[140:141], v[76:77], v[134:135] op_sel_hi:[0,1,1] neg_lo:[1,0,0] neg_hi:[1,0,0]
	ds_read_b128 v[70:73], v112 offset:11008
	ds_read_b128 v[74:77], v112 offset:11024
	s_waitcnt lgkmcnt(7)
	v_pk_mul_f32 v[136:137], v[22:23], v[30:31]
	v_pk_mul_f32 v[138:139], v[22:23], v[96:97]
	v_pk_fma_f32 v[136:137], v[24:25], v[32:33], v[136:137]
	v_pk_fma_f32 v[138:139], v[24:25], v[98:99], v[138:139]
	v_pk_fma_f32 v[136:137], v[26:27], v[34:35], v[136:137]
	v_pk_fma_f32 v[138:139], v[26:27], v[100:101], v[138:139]
	v_pk_fma_f32 v[136:137], v[28:29], v[36:37], v[136:137]
	v_pk_fma_f32 v[138:139], v[28:29], v[102:103], v[138:139]
	ds_read_b128 v[30:33], v112 offset:3072
	ds_read_b128 v[34:37], v112 offset:3088
	ds_read_b128 v[96:99], v112 offset:19200
	ds_read_b128 v[100:103], v112 offset:19216
	v_add_f32_e32 v140, v136, v137
	v_add_f32_e32 v146, v138, v139
	s_waitcnt lgkmcnt(8)
	v_pk_mul_f32 v[128:129], v[78:79], v[104:105] op_sel_hi:[1,0]
	v_add_f32_dpp v140, v140, v140 row_half_mirror row_mask:0xf bank_mask:0xf
	v_add_f32_dpp v146, v146, v146 row_half_mirror row_mask:0xf bank_mask:0xf
	v_pk_mul_f32 v[130:131], v[80:81], v[104:105] op_sel_hi:[1,0]
	v_pk_mul_f32 v[132:133], v[82:83], v[104:105] op_sel_hi:[1,0]
	v_add_f32_dpp v140, v140, v140 quad_perm:[1,0,3,2] row_mask:0xf bank_mask:0xf
	v_add_f32_dpp v146, v146, v146 quad_perm:[1,0,3,2] row_mask:0xf bank_mask:0xf
	v_pk_mul_f32 v[134:135], v[84:85], v[104:105] op_sel_hi:[1,0]
	ds_read_b128 v[78:81], v112 offset:15360
	ds_read_b128 v[82:85], v112 offset:15376
	ds_read_b32 v104, v108 offset:22016
	s_waitcnt lgkmcnt(9)
	v_pk_fma_f32 v[128:129], v[22:23], v[38:39], v[128:129]
	v_add_f32_dpp v140, v140, v140 quad_perm:[2,3,0,1] row_mask:0xf bank_mask:0xf
	v_add_f32_dpp v146, v146, v146 quad_perm:[2,3,0,1] row_mask:0xf bank_mask:0xf
	v_pk_fma_f32 v[130:131], v[24:25], v[40:41], v[130:131]
	v_pk_fma_f32 v[132:133], v[26:27], v[42:43], v[132:133]
	v_pk_fma_f32 v[134:135], v[28:29], v[44:45], v[134:135]
	ds_read_b128 v[38:41], v112 offset:7168
	ds_read_b128 v[42:45], v112 offset:7184
	s_waitcnt lgkmcnt(9)
	v_pk_fma_f32 v[22:23], v[140:141], v[70:71], v[128:129] op_sel_hi:[0,1,1] neg_lo:[1,0,0] neg_hi:[1,0,0]
	v_pk_fma_f32 v[24:25], v[140:141], v[72:73], v[130:131] op_sel_hi:[0,1,1] neg_lo:[1,0,0] neg_hi:[1,0,0]
	v_pk_fma_f32 v[26:27], v[140:141], v[74:75], v[132:133] op_sel_hi:[0,1,1] neg_lo:[1,0,0] neg_hi:[1,0,0]
	v_pk_fma_f32 v[28:29], v[140:141], v[76:77], v[134:135] op_sel_hi:[0,1,1] neg_lo:[1,0,0] neg_hi:[1,0,0]
	ds_read_b128 v[70:73], v112 offset:11264
	ds_read_b128 v[74:77], v112 offset:11280
	s_waitcnt lgkmcnt(7)
	v_pk_mul_f32 v[136:137], v[22:23], v[30:31]
	v_pk_mul_f32 v[138:139], v[22:23], v[96:97]
	v_pk_fma_f32 v[136:137], v[24:25], v[32:33], v[136:137]
	v_pk_fma_f32 v[138:139], v[24:25], v[98:99], v[138:139]
	v_pk_fma_f32 v[136:137], v[26:27], v[34:35], v[136:137]
	v_pk_fma_f32 v[138:139], v[26:27], v[100:101], v[138:139]
	v_pk_fma_f32 v[136:137], v[28:29], v[36:37], v[136:137]
	v_pk_fma_f32 v[138:139], v[28:29], v[102:103], v[138:139]
	ds_read_b128 v[30:33], v112 offset:3328
	ds_read_b128 v[34:37], v112 offset:3344
	ds_read_b128 v[96:99], v112 offset:19456
	ds_read_b128 v[100:103], v112 offset:19472
	v_add_f32_e32 v140, v136, v137
	v_add_f32_e32 v147, v138, v139
	s_waitcnt lgkmcnt(8)
	v_pk_mul_f32 v[128:129], v[78:79], v[104:105] op_sel_hi:[1,0]
	v_add_f32_dpp v140, v140, v140 row_half_mirror row_mask:0xf bank_mask:0xf
	v_add_f32_dpp v147, v147, v147 row_half_mirror row_mask:0xf bank_mask:0xf
	v_pk_mul_f32 v[130:131], v[80:81], v[104:105] op_sel_hi:[1,0]
	v_pk_mul_f32 v[132:133], v[82:83], v[104:105] op_sel_hi:[1,0]
	v_add_f32_dpp v140, v140, v140 quad_perm:[1,0,3,2] row_mask:0xf bank_mask:0xf
	v_add_f32_dpp v147, v147, v147 quad_perm:[1,0,3,2] row_mask:0xf bank_mask:0xf
	v_pk_mul_f32 v[134:135], v[84:85], v[104:105] op_sel_hi:[1,0]
	ds_read_b128 v[78:81], v112 offset:15616
	ds_read_b128 v[82:85], v112 offset:15632
	ds_read_b32 v104, v108 offset:22144
	s_waitcnt lgkmcnt(9)
	v_pk_fma_f32 v[128:129], v[22:23], v[38:39], v[128:129]
	v_add_f32_dpp v140, v140, v140 quad_perm:[2,3,0,1] row_mask:0xf bank_mask:0xf
	v_add_f32_dpp v147, v147, v147 quad_perm:[2,3,0,1] row_mask:0xf bank_mask:0xf
	v_pk_fma_f32 v[130:131], v[24:25], v[40:41], v[130:131]
	v_pk_fma_f32 v[132:133], v[26:27], v[42:43], v[132:133]
	v_pk_fma_f32 v[134:135], v[28:29], v[44:45], v[134:135]
	ds_read_b128 v[38:41], v112 offset:7424
	ds_read_b128 v[42:45], v112 offset:7440
	s_waitcnt lgkmcnt(9)
	v_pk_fma_f32 v[22:23], v[140:141], v[70:71], v[128:129] op_sel_hi:[0,1,1] neg_lo:[1,0,0] neg_hi:[1,0,0]
	v_pk_fma_f32 v[24:25], v[140:141], v[72:73], v[130:131] op_sel_hi:[0,1,1] neg_lo:[1,0,0] neg_hi:[1,0,0]
	v_pk_fma_f32 v[26:27], v[140:141], v[74:75], v[132:133] op_sel_hi:[0,1,1] neg_lo:[1,0,0] neg_hi:[1,0,0]
	v_pk_fma_f32 v[28:29], v[140:141], v[76:77], v[134:135] op_sel_hi:[0,1,1] neg_lo:[1,0,0] neg_hi:[1,0,0]
	ds_read_b128 v[70:73], v112 offset:11520
	ds_read_b128 v[74:77], v112 offset:11536
	ds_write_b128 v113, v[144:147] offset:24608
	s_waitcnt lgkmcnt(8)
	v_pk_mul_f32 v[136:137], v[22:23], v[30:31]
	v_pk_mul_f32 v[138:139], v[22:23], v[96:97]
	v_pk_fma_f32 v[136:137], v[24:25], v[32:33], v[136:137]
	v_pk_fma_f32 v[138:139], v[24:25], v[98:99], v[138:139]
	v_pk_fma_f32 v[136:137], v[26:27], v[34:35], v[136:137]
	v_pk_fma_f32 v[138:139], v[26:27], v[100:101], v[138:139]
	v_pk_fma_f32 v[136:137], v[28:29], v[36:37], v[136:137]
	v_pk_fma_f32 v[138:139], v[28:29], v[102:103], v[138:139]
	ds_read_b128 v[30:33], v112 offset:3584
	ds_read_b128 v[34:37], v112 offset:3600
	ds_read_b128 v[96:99], v112 offset:19712
	ds_read_b128 v[100:103], v112 offset:19728
	v_add_f32_e32 v140, v136, v137
	v_add_f32_e32 v144, v138, v139
	s_waitcnt lgkmcnt(9)
	v_pk_mul_f32 v[128:129], v[78:79], v[104:105] op_sel_hi:[1,0]
	v_add_f32_dpp v140, v140, v140 row_half_mirror row_mask:0xf bank_mask:0xf
	v_add_f32_dpp v144, v144, v144 row_half_mirror row_mask:0xf bank_mask:0xf
	v_pk_mul_f32 v[130:131], v[80:81], v[104:105] op_sel_hi:[1,0]
	v_pk_mul_f32 v[132:133], v[82:83], v[104:105] op_sel_hi:[1,0]
	v_add_f32_dpp v140, v140, v140 quad_perm:[1,0,3,2] row_mask:0xf bank_mask:0xf
	v_add_f32_dpp v144, v144, v144 quad_perm:[1,0,3,2] row_mask:0xf bank_mask:0xf
	v_pk_mul_f32 v[134:135], v[84:85], v[104:105] op_sel_hi:[1,0]
	ds_read_b128 v[78:81], v112 offset:15872
	ds_read_b128 v[82:85], v112 offset:15888
	ds_read_b32 v104, v108 offset:22272
	s_waitcnt lgkmcnt(10)
	v_pk_fma_f32 v[128:129], v[22:23], v[38:39], v[128:129]
	v_add_f32_dpp v140, v140, v140 quad_perm:[2,3,0,1] row_mask:0xf bank_mask:0xf
	v_add_f32_dpp v144, v144, v144 quad_perm:[2,3,0,1] row_mask:0xf bank_mask:0xf
	v_pk_fma_f32 v[130:131], v[24:25], v[40:41], v[130:131]
	v_pk_fma_f32 v[132:133], v[26:27], v[42:43], v[132:133]
	v_pk_fma_f32 v[134:135], v[28:29], v[44:45], v[134:135]
	ds_read_b128 v[38:41], v112 offset:7680
	ds_read_b128 v[42:45], v112 offset:7696
	s_waitcnt lgkmcnt(10)
	v_pk_fma_f32 v[22:23], v[140:141], v[70:71], v[128:129] op_sel_hi:[0,1,1] neg_lo:[1,0,0] neg_hi:[1,0,0]
	v_pk_fma_f32 v[24:25], v[140:141], v[72:73], v[130:131] op_sel_hi:[0,1,1] neg_lo:[1,0,0] neg_hi:[1,0,0]
	v_pk_fma_f32 v[26:27], v[140:141], v[74:75], v[132:133] op_sel_hi:[0,1,1] neg_lo:[1,0,0] neg_hi:[1,0,0]
	v_pk_fma_f32 v[28:29], v[140:141], v[76:77], v[134:135] op_sel_hi:[0,1,1] neg_lo:[1,0,0] neg_hi:[1,0,0]
	ds_read_b128 v[70:73], v112 offset:11776
	ds_read_b128 v[74:77], v112 offset:11792
	s_waitcnt lgkmcnt(7)
	v_pk_mul_f32 v[136:137], v[22:23], v[30:31]
	v_pk_mul_f32 v[138:139], v[22:23], v[96:97]
	v_pk_fma_f32 v[136:137], v[24:25], v[32:33], v[136:137]
	v_pk_fma_f32 v[138:139], v[24:25], v[98:99], v[138:139]
	v_pk_fma_f32 v[136:137], v[26:27], v[34:35], v[136:137]
	v_pk_fma_f32 v[138:139], v[26:27], v[100:101], v[138:139]
	v_pk_fma_f32 v[136:137], v[28:29], v[36:37], v[136:137]
	v_pk_fma_f32 v[138:139], v[28:29], v[102:103], v[138:139]
	ds_read_b128 v[30:33], v112 offset:3840
	ds_read_b128 v[34:37], v112 offset:3856
	ds_read_b128 v[96:99], v112 offset:19968
	ds_read_b128 v[100:103], v112 offset:19984
	v_add_f32_e32 v140, v136, v137
	v_add_f32_e32 v145, v138, v139
	s_waitcnt lgkmcnt(8)
	v_pk_mul_f32 v[128:129], v[78:79], v[104:105] op_sel_hi:[1,0]
	v_add_f32_dpp v140, v140, v140 row_half_mirror row_mask:0xf bank_mask:0xf
	v_add_f32_dpp v145, v145, v145 row_half_mirror row_mask:0xf bank_mask:0xf
	v_pk_mul_f32 v[130:131], v[80:81], v[104:105] op_sel_hi:[1,0]
	v_pk_mul_f32 v[132:133], v[82:83], v[104:105] op_sel_hi:[1,0]
	v_add_f32_dpp v140, v140, v140 quad_perm:[1,0,3,2] row_mask:0xf bank_mask:0xf
	v_add_f32_dpp v145, v145, v145 quad_perm:[1,0,3,2] row_mask:0xf bank_mask:0xf
	v_pk_mul_f32 v[134:135], v[84:85], v[104:105] op_sel_hi:[1,0]
	ds_read_b128 v[78:81], v112 offset:16128
	ds_read_b128 v[82:85], v112 offset:16144
	ds_read_b32 v104, v108 offset:22400
	s_waitcnt lgkmcnt(9)
	v_pk_fma_f32 v[128:129], v[22:23], v[38:39], v[128:129]
	v_add_f32_dpp v140, v140, v140 quad_perm:[2,3,0,1] row_mask:0xf bank_mask:0xf
	v_add_f32_dpp v145, v145, v145 quad_perm:[2,3,0,1] row_mask:0xf bank_mask:0xf
	v_pk_fma_f32 v[130:131], v[24:25], v[40:41], v[130:131]
	v_pk_fma_f32 v[132:133], v[26:27], v[42:43], v[132:133]
	v_pk_fma_f32 v[134:135], v[28:29], v[44:45], v[134:135]
	ds_read_b128 v[38:41], v112 offset:7936
	ds_read_b128 v[42:45], v112 offset:7952
	s_waitcnt lgkmcnt(9)
	v_pk_fma_f32 v[22:23], v[140:141], v[70:71], v[128:129] op_sel_hi:[0,1,1] neg_lo:[1,0,0] neg_hi:[1,0,0]
	v_pk_fma_f32 v[24:25], v[140:141], v[72:73], v[130:131] op_sel_hi:[0,1,1] neg_lo:[1,0,0] neg_hi:[1,0,0]
	v_pk_fma_f32 v[26:27], v[140:141], v[74:75], v[132:133] op_sel_hi:[0,1,1] neg_lo:[1,0,0] neg_hi:[1,0,0]
	v_pk_fma_f32 v[28:29], v[140:141], v[76:77], v[134:135] op_sel_hi:[0,1,1] neg_lo:[1,0,0] neg_hi:[1,0,0]
	ds_read_b128 v[70:73], v112 offset:12032
	ds_read_b128 v[74:77], v112 offset:12048
	s_waitcnt lgkmcnt(7)
	v_pk_mul_f32 v[136:137], v[22:23], v[30:31]
	v_pk_mul_f32 v[138:139], v[22:23], v[96:97]
	v_pk_fma_f32 v[136:137], v[24:25], v[32:33], v[136:137]
	v_pk_fma_f32 v[138:139], v[24:25], v[98:99], v[138:139]
	v_pk_fma_f32 v[136:137], v[26:27], v[34:35], v[136:137]
	v_pk_fma_f32 v[138:139], v[26:27], v[100:101], v[138:139]
	v_pk_fma_f32 v[136:137], v[28:29], v[36:37], v[136:137]
	v_pk_fma_f32 v[138:139], v[28:29], v[102:103], v[138:139]
	ds_read_b128 v[96:99], v112 offset:20224
	ds_read_b128 v[100:103], v112 offset:20240
	v_add_f32_e32 v140, v136, v137
	v_add_f32_e32 v146, v138, v139
	s_waitcnt lgkmcnt(6)
	v_pk_mul_f32 v[128:129], v[78:79], v[104:105] op_sel_hi:[1,0]
	v_add_f32_dpp v140, v140, v140 row_half_mirror row_mask:0xf bank_mask:0xf
	v_add_f32_dpp v146, v146, v146 row_half_mirror row_mask:0xf bank_mask:0xf
	v_pk_mul_f32 v[130:131], v[80:81], v[104:105] op_sel_hi:[1,0]
	v_pk_mul_f32 v[132:133], v[82:83], v[104:105] op_sel_hi:[1,0]
	v_add_f32_dpp v140, v140, v140 quad_perm:[1,0,3,2] row_mask:0xf bank_mask:0xf
	v_add_f32_dpp v146, v146, v146 quad_perm:[1,0,3,2] row_mask:0xf bank_mask:0xf
	v_pk_mul_f32 v[134:135], v[84:85], v[104:105] op_sel_hi:[1,0]
	s_waitcnt lgkmcnt(4)
	v_pk_fma_f32 v[128:129], v[22:23], v[38:39], v[128:129]
	v_add_f32_dpp v140, v140, v140 quad_perm:[2,3,0,1] row_mask:0xf bank_mask:0xf
	v_add_f32_dpp v146, v146, v146 quad_perm:[2,3,0,1] row_mask:0xf bank_mask:0xf
	v_pk_fma_f32 v[130:131], v[24:25], v[40:41], v[130:131]
	v_pk_fma_f32 v[132:133], v[26:27], v[42:43], v[132:133]
	v_pk_fma_f32 v[134:135], v[28:29], v[44:45], v[134:135]
	s_waitcnt lgkmcnt(2)
	v_pk_fma_f32 v[22:23], v[140:141], v[70:71], v[128:129] op_sel_hi:[0,1,1] neg_lo:[1,0,0] neg_hi:[1,0,0]
	v_pk_fma_f32 v[24:25], v[140:141], v[72:73], v[130:131] op_sel_hi:[0,1,1] neg_lo:[1,0,0] neg_hi:[1,0,0]
	v_pk_fma_f32 v[26:27], v[140:141], v[74:75], v[132:133] op_sel_hi:[0,1,1] neg_lo:[1,0,0] neg_hi:[1,0,0]
	v_pk_fma_f32 v[28:29], v[140:141], v[76:77], v[134:135] op_sel_hi:[0,1,1] neg_lo:[1,0,0] neg_hi:[1,0,0]
	s_waitcnt lgkmcnt(0)
	v_pk_mul_f32 v[138:139], v[22:23], v[96:97]
	v_pk_fma_f32 v[138:139], v[24:25], v[98:99], v[138:139]
	v_pk_fma_f32 v[138:139], v[26:27], v[100:101], v[138:139]
	v_pk_fma_f32 v[138:139], v[28:29], v[102:103], v[138:139]
	v_add_f32_e32 v147, v138, v139
	s_nop 1
	v_add_f32_dpp v147, v147, v147 row_half_mirror row_mask:0xf bank_mask:0xf
	s_nop 1
	v_add_f32_dpp v147, v147, v147 quad_perm:[1,0,3,2] row_mask:0xf bank_mask:0xf
	s_nop 1
	v_add_f32_dpp v147, v147, v147 quad_perm:[2,3,0,1] row_mask:0xf bank_mask:0xf
	ds_write_b128 v113, v[144:147] offset:24624
	s_branch .Lrw0_u2e1
.Lrw0_u2s1:
	ds_read_b128 v[30:33], v112 offset:0
	ds_read_b128 v[34:37], v112 offset:16
	ds_read_b128 v[38:41], v112 offset:4096
	ds_read_b128 v[42:45], v112 offset:4112
	ds_read_b128 v[70:73], v112 offset:8192
	ds_read_b128 v[74:77], v112 offset:8208
	s_waitcnt lgkmcnt(4)
	v_pk_mul_f32 v[136:137], v[22:23], v[30:31]
	v_pk_fma_f32 v[136:137], v[24:25], v[32:33], v[136:137]
	v_pk_fma_f32 v[136:137], v[26:27], v[34:35], v[136:137]
	v_pk_fma_f32 v[136:137], v[28:29], v[36:37], v[136:137]
	ds_read_b128 v[30:33], v112 offset:256
	ds_read_b128 v[34:37], v112 offset:272
	ds_read_b128 v[96:99], v112 offset:16384
	ds_read_b128 v[100:103], v112 offset:16400
	v_add_f32_e32 v140, v136, v137
	s_waitcnt lgkmcnt(6)
	v_pk_mul_f32 v[128:129], v[22:23], v[38:39]
	v_add_f32_dpp v140, v140, v140 row_half_mirror row_mask:0xf bank_mask:0xf
	v_pk_mul_f32 v[130:131], v[24:25], v[40:41]
	v_pk_mul_f32 v[132:133], v[26:27], v[42:43]
	v_pk_mul_f32 v[134:135], v[28:29], v[44:45]
	ds_read_b128 v[38:41], v112 offset:4352
	ds_read_b128 v[42:45], v112 offset:4368
	v_add_f32_dpp v140, v140, v140 quad_perm:[1,0,3,2] row_mask:0xf bank_mask:0xf
	s_nop 1
	v_add_f32_dpp v140, v140, v140 quad_perm:[2,3,0,1] row_mask:0xf bank_mask:0xf
	s_waitcnt lgkmcnt(6)
	v_pk_fma_f32 v[22:23], v[140:141], v[70:71], v[128:129] op_sel_hi:[0,1,1] neg_lo:[1,0,0] neg_hi:[1,0,0]
	v_pk_fma_f32 v[24:25], v[140:141], v[72:73], v[130:131] op_sel_hi:[0,1,1] neg_lo:[1,0,0] neg_hi:[1,0,0]
	v_pk_fma_f32 v[26:27], v[140:141], v[74:75], v[132:133] op_sel_hi:[0,1,1] neg_lo:[1,0,0] neg_hi:[1,0,0]
	v_pk_fma_f32 v[28:29], v[140:141], v[76:77], v[134:135] op_sel_hi:[0,1,1] neg_lo:[1,0,0] neg_hi:[1,0,0]
	ds_read_b128 v[70:73], v112 offset:8448
	ds_read_b128 v[74:77], v112 offset:8464
	s_waitcnt lgkmcnt(4)
	v_pk_mul_f32 v[136:137], v[22:23], v[30:31]
	v_pk_mul_f32 v[138:139], v[22:23], v[96:97]
	v_pk_fma_f32 v[136:137], v[24:25], v[32:33], v[136:137]
	v_pk_fma_f32 v[138:139], v[24:25], v[98:99], v[138:139]
	v_pk_fma_f32 v[136:137], v[26:27], v[34:35], v[136:137]
	v_pk_fma_f32 v[138:139], v[26:27], v[100:101], v[138:139]
	v_pk_fma_f32 v[136:137], v[28:29], v[36:37], v[136:137]
	v_pk_fma_f32 v[138:139], v[28:29], v[102:103], v[138:139]
	ds_read_b128 v[30:33], v112 offset:512
	ds_read_b128 v[34:37], v112 offset:528
	ds_read_b128 v[96:99], v112 offset:16640
	ds_read_b128 v[100:103], v112 offset:16656
	v_add_f32_e32 v140, v136, v137
	v_add_f32_e32 v144, v138, v139
	s_waitcnt lgkmcnt(6)
	v_pk_mul_f32 v[128:129], v[22:23], v[38:39]
	v_add_f32_dpp v140, v140, v140 row_half_mirror row_mask:0xf bank_mask:0xf
	v_add_f32_dpp v144, v144, v144 row_half_mirror row_mask:0xf bank_mask:0xf
	v_pk_mul_f32 v[130:131], v[24:25], v[40:41]
	v_pk_mul_f32 v[132:133], v[26:27], v[42:43]
	v_add_f32_dpp v140, v140, v140 quad_perm:[1,0,3,2] row_mask:0xf bank_mask:0xf
	v_add_f32_dpp v144, v144, v144 quad_perm:[1,0,3,2] row_mask:0xf bank_mask:0xf
	v_pk_mul_f32 v[134:135], v[28:29], v[44:45]
	ds_read_b128 v[38:41], v112 offset:4608
	ds_read_b128 v[42:45], v112 offset:4624
	v_add_f32_dpp v140, v140, v140 quad_perm:[2,3,0,1] row_mask:0xf bank_mask:0xf
	v_add_f32_dpp v144, v144, v144 quad_perm:[2,3,0,1] row_mask:0xf bank_mask:0xf
	s_waitcnt lgkmcnt(6)
	v_pk_fma_f32 v[22:23], v[140:141], v[70:71], v[128:129] op_sel_hi:[0,1,1] neg_lo:[1,0,0] neg_hi:[1,0,0]
	v_pk_fma_f32 v[24:25], v[140:141], v[72:73], v[130:131] op_sel_hi:[0,1,1] neg_lo:[1,0,0] neg_hi:[1,0,0]
	v_pk_fma_f32 v[26:27], v[140:141], v[74:75], v[132:133] op_sel_hi:[0,1,1] neg_lo:[1,0,0] neg_hi:[1,0,0]
	v_pk_fma_f32 v[28:29], v[140:141], v[76:77], v[134:135] op_sel_hi:[0,1,1] neg_lo:[1,0,0] neg_hi:[1,0,0]
	ds_read_b128 v[70:73], v112 offset:8704
	ds_read_b128 v[74:77], v112 offset:8720
	s_waitcnt lgkmcnt(4)
	v_pk_mul_f32 v[136:137], v[22:23], v[30:31]
	v_pk_mul_f32 v[138:139], v[22:23], v[96:97]
	v_pk_fma_f32 v[136:137], v[24:25], v[32:33], v[136:137]
	v_pk_fma_f32 v[138:139], v[24:25], v[98:99], v[138:139]
	v_pk_fma_f32 v[136:137], v[26:27], v[34:35], v[136:137]
	v_pk_fma_f32 v[138:139], v[26:27], v[100:101], v[138:139]
	v_pk_fma_f32 v[136:137], v[28:29], v[36:37], v[136:137]
	v_pk_fma_f32 v[138:139], v[28:29], v[102:103], v[138:139]
	ds_read_b128 v[30:33], v112 offset:768
	ds_read_b128 v[34:37], v112 offset:784
	ds_read_b128 v[96:99], v112 offset:16896
	ds_read_b128 v[100:103], v112 offset:16912
	v_add_f32_e32 v140, v136, v137
	v_add_f32_e32 v145, v138, v139
	s_waitcnt lgkmcnt(6)
	v_pk_mul_f32 v[128:129], v[22:23], v[38:39]
	v_add_f32_dpp v140, v140, v140 row_half_mirror row_mask:0xf bank_mask:0xf
	v_add_f32_dpp v145, v145, v145 row_half_mirror row_mask:0xf bank_mask:0xf
	v_pk_mul_f32 v[130:131], v[24:25], v[40:41]
	v_pk_mul_f32 v[132:133], v[26:27], v[42:43]
	v_add_f32_dpp v140, v140, v140 quad_perm:[1,0,3,2] row_mask:0xf bank_mask:0xf
	v_add_f32_dpp v145, v145, v145 quad_perm:[1,0,3,2] row_mask:0xf bank_mask:0xf
	v_pk_mul_f32 v[134:135], v[28:29], v[44:45]
	ds_read_b128 v[38:41], v112 offset:4864
	ds_read_b128 v[42:45], v112 offset:4880
	v_add_f32_dpp v140, v140, v140 quad_perm:[2,3,0,1] row_mask:0xf bank_mask:0xf
	v_add_f32_dpp v145, v145, v145 quad_perm:[2,3,0,1] row_mask:0xf bank_mask:0xf
	s_waitcnt lgkmcnt(6)
	v_pk_fma_f32 v[22:23], v[140:141], v[70:71], v[128:129] op_sel_hi:[0,1,1] neg_lo:[1,0,0] neg_hi:[1,0,0]
	v_pk_fma_f32 v[24:25], v[140:141], v[72:73], v[130:131] op_sel_hi:[0,1,1] neg_lo:[1,0,0] neg_hi:[1,0,0]
	v_pk_fma_f32 v[26:27], v[140:141], v[74:75], v[132:133] op_sel_hi:[0,1,1] neg_lo:[1,0,0] neg_hi:[1,0,0]
	v_pk_fma_f32 v[28:29], v[140:141], v[76:77], v[134:135] op_sel_hi:[0,1,1] neg_lo:[1,0,0] neg_hi:[1,0,0]
	ds_read_b128 v[70:73], v112 offset:8960
	ds_read_b128 v[74:77], v112 offset:8976
	s_waitcnt lgkmcnt(4)
	v_pk_mul_f32 v[136:137], v[22:23], v[30:31]
	v_pk_mul_f32 v[138:139], v[22:23], v[96:97]
	v_pk_fma_f32 v[136:137], v[24:25], v[32:33], v[136:137]
	v_pk_fma_f32 v[138:139], v[24:25], v[98:99], v[138:139]
	v_pk_fma_f32 v[136:137], v[26:27], v[34:35], v[136:137]
	v_pk_fma_f32 v[138:139], v[26:27], v[100:101], v[138:139]
	v_pk_fma_f32 v[136:137], v[28:29], v[36:37], v[136:137]
	v_pk_fma_f32 v[138:139], v[28:29], v[102:103], v[138:139]
	ds_read_b128 v[30:33], v112 offset:1024
	ds_read_b128 v[34:37], v112 offset:1040
	ds_read_b128 v[96:99], v112 offset:17152
	ds_read_b128 v[100:103], v112 offset:17168
	v_add_f32_e32 v140, v136, v137
	v_add_f32_e32 v146, v138, v139
	s_waitcnt lgkmcnt(6)
	v_pk_mul_f32 v[128:129], v[22:23], v[38:39]
	v_add_f32_dpp v140, v140, v140 row_half_mirror row_mask:0xf bank_mask:0xf
	v_add_f32_dpp v146, v146, v146 row_half_mirror row_mask:0xf bank_mask:0xf
	v_pk_mul_f32 v[130:131], v[24:25], v[40:41]
	v_pk_mul_f32 v[132:133], v[26:27], v[42:43]
	v_add_f32_dpp v140, v140, v140 quad_perm:[1,0,3,2] row_mask:0xf bank_mask:0xf
	v_add_f32_dpp v146, v146, v146 quad_perm:[1,0,3,2] row_mask:0xf bank_mask:0xf
	v_pk_mul_f32 v[134:135], v[28:29], v[44:45]
	ds_read_b128 v[38:41], v112 offset:5120
	ds_read_b128 v[42:45], v112 offset:5136
	v_add_f32_dpp v140, v140, v140 quad_perm:[2,3,0,1] row_mask:0xf bank_mask:0xf
	v_add_f32_dpp v146, v146, v146 quad_perm:[2,3,0,1] row_mask:0xf bank_mask:0xf
	s_waitcnt lgkmcnt(6)
	v_pk_fma_f32 v[22:23], v[140:141], v[70:71], v[128:129] op_sel_hi:[0,1,1] neg_lo:[1,0,0] neg_hi:[1,0,0]
	v_pk_fma_f32 v[24:25], v[140:141], v[72:73], v[130:131] op_sel_hi:[0,1,1] neg_lo:[1,0,0] neg_hi:[1,0,0]
	v_pk_fma_f32 v[26:27], v[140:141], v[74:75], v[132:133] op_sel_hi:[0,1,1] neg_lo:[1,0,0] neg_hi:[1,0,0]
	v_pk_fma_f32 v[28:29], v[140:141], v[76:77], v[134:135] op_sel_hi:[0,1,1] neg_lo:[1,0,0] neg_hi:[1,0,0]
	ds_read_b128 v[70:73], v112 offset:9216
	ds_read_b128 v[74:77], v112 offset:9232
	s_waitcnt lgkmcnt(4)
	v_pk_mul_f32 v[136:137], v[22:23], v[30:31]
	v_pk_mul_f32 v[138:139], v[22:23], v[96:97]
	v_pk_fma_f32 v[136:137], v[24:25], v[32:33], v[136:137]
	v_pk_fma_f32 v[138:139], v[24:25], v[98:99], v[138:139]
	v_pk_fma_f32 v[136:137], v[26:27], v[34:35], v[136:137]
	v_pk_fma_f32 v[138:139], v[26:27], v[100:101], v[138:139]
	v_pk_fma_f32 v[136:137], v[28:29], v[36:37], v[136:137]
	v_pk_fma_f32 v[138:139], v[28:29], v[102:103], v[138:139]
	ds_read_b128 v[30:33], v112 offset:1280
	ds_read_b128 v[34:37], v112 offset:1296
	ds_read_b128 v[96:99], v112 offset:17408
	ds_read_b128 v[100:103], v112 offset:17424
	v_add_f32_e32 v140, v136, v137
	v_add_f32_e32 v147, v138, v139
	s_waitcnt lgkmcnt(6)
	v_pk_mul_f32 v[128:129], v[22:23], v[38:39]
	v_add_f32_dpp v140, v140, v140 row_half_mirror row_mask:0xf bank_mask:0xf
	v_add_f32_dpp v147, v147, v147 row_half_mirror row_mask:0xf bank_mask:0xf
	v_pk_mul_f32 v[130:131], v[24:25], v[40:41]
	v_pk_mul_f32 v[132:133], v[26:27], v[42:43]
	v_add_f32_dpp v140, v140, v140 quad_perm:[1,0,3,2] row_mask:0xf bank_mask:0xf
	v_add_f32_dpp v147, v147, v147 quad_perm:[1,0,3,2] row_mask:0xf bank_mask:0xf
	v_pk_mul_f32 v[134:135], v[28:29], v[44:45]
	ds_read_b128 v[38:41], v112 offset:5376
	ds_read_b128 v[42:45], v112 offset:5392
	v_add_f32_dpp v140, v140, v140 quad_perm:[2,3,0,1] row_mask:0xf bank_mask:0xf
	v_add_f32_dpp v147, v147, v147 quad_perm:[2,3,0,1] row_mask:0xf bank_mask:0xf
	s_waitcnt lgkmcnt(6)
	v_pk_fma_f32 v[22:23], v[140:141], v[70:71], v[128:129] op_sel_hi:[0,1,1] neg_lo:[1,0,0] neg_hi:[1,0,0]
	v_pk_fma_f32 v[24:25], v[140:141], v[72:73], v[130:131] op_sel_hi:[0,1,1] neg_lo:[1,0,0] neg_hi:[1,0,0]
	v_pk_fma_f32 v[26:27], v[140:141], v[74:75], v[132:133] op_sel_hi:[0,1,1] neg_lo:[1,0,0] neg_hi:[1,0,0]
	v_pk_fma_f32 v[28:29], v[140:141], v[76:77], v[134:135] op_sel_hi:[0,1,1] neg_lo:[1,0,0] neg_hi:[1,0,0]
	ds_read_b128 v[70:73], v112 offset:9472
	ds_read_b128 v[74:77], v112 offset:9488
	ds_write_b128 v113, v[144:147] offset:24576
	s_waitcnt lgkmcnt(5)
	v_pk_mul_f32 v[136:137], v[22:23], v[30:31]
	v_pk_mul_f32 v[138:139], v[22:23], v[96:97]
	v_pk_fma_f32 v[136:137], v[24:25], v[32:33], v[136:137]
	v_pk_fma_f32 v[138:139], v[24:25], v[98:99], v[138:139]
	v_pk_fma_f32 v[136:137], v[26:27], v[34:35], v[136:137]
	v_pk_fma_f32 v[138:139], v[26:27], v[100:101], v[138:139]
	v_pk_fma_f32 v[136:137], v[28:29], v[36:37], v[136:137]
	v_pk_fma_f32 v[138:139], v[28:29], v[102:103], v[138:139]
	ds_read_b128 v[30:33], v112 offset:1536
	ds_read_b128 v[34:37], v112 offset:1552
	ds_read_b128 v[96:99], v112 offset:17664
	ds_read_b128 v[100:103], v112 offset:17680
	v_add_f32_e32 v140, v136, v137
	v_add_f32_e32 v144, v138, v139
	s_waitcnt lgkmcnt(7)
	v_pk_mul_f32 v[128:129], v[22:23], v[38:39]
	v_add_f32_dpp v140, v140, v140 row_half_mirror row_mask:0xf bank_mask:0xf
	v_add_f32_dpp v144, v144, v144 row_half_mirror row_mask:0xf bank_mask:0xf
	v_pk_mul_f32 v[130:131], v[24:25], v[40:41]
	v_pk_mul_f32 v[132:133], v[26:27], v[42:43]
	v_add_f32_dpp v140, v140, v140 quad_perm:[1,0,3,2] row_mask:0xf bank_mask:0xf
	v_add_f32_dpp v144, v144, v144 quad_perm:[1,0,3,2] row_mask:0xf bank_mask:0xf
	v_pk_mul_f32 v[134:135], v[28:29], v[44:45]
	ds_read_b128 v[38:41], v112 offset:5632
	ds_read_b128 v[42:45], v112 offset:5648
	v_add_f32_dpp v140, v140, v140 quad_perm:[2,3,0,1] row_mask:0xf bank_mask:0xf
	v_add_f32_dpp v144, v144, v144 quad_perm:[2,3,0,1] row_mask:0xf bank_mask:0xf
	s_waitcnt lgkmcnt(7)
	v_pk_fma_f32 v[22:23], v[140:141], v[70:71], v[128:129] op_sel_hi:[0,1,1] neg_lo:[1,0,0] neg_hi:[1,0,0]
	v_pk_fma_f32 v[24:25], v[140:141], v[72:73], v[130:131] op_sel_hi:[0,1,1] neg_lo:[1,0,0] neg_hi:[1,0,0]
	v_pk_fma_f32 v[26:27], v[140:141], v[74:75], v[132:133] op_sel_hi:[0,1,1] neg_lo:[1,0,0] neg_hi:[1,0,0]
	v_pk_fma_f32 v[28:29], v[140:141], v[76:77], v[134:135] op_sel_hi:[0,1,1] neg_lo:[1,0,0] neg_hi:[1,0,0]
	ds_read_b128 v[70:73], v112 offset:9728
	ds_read_b128 v[74:77], v112 offset:9744
	s_waitcnt lgkmcnt(4)
	v_pk_mul_f32 v[136:137], v[22:23], v[30:31]
	v_pk_mul_f32 v[138:139], v[22:23], v[96:97]
	v_pk_fma_f32 v[136:137], v[24:25], v[32:33], v[136:137]
	v_pk_fma_f32 v[138:139], v[24:25], v[98:99], v[138:139]
	v_pk_fma_f32 v[136:137], v[26:27], v[34:35], v[136:137]
	v_pk_fma_f32 v[138:139], v[26:27], v[100:101], v[138:139]
	v_pk_fma_f32 v[136:137], v[28:29], v[36:37], v[136:137]
	v_pk_fma_f32 v[138:139], v[28:29], v[102:103], v[138:139]
	ds_read_b128 v[30:33], v112 offset:1792
	ds_read_b128 v[34:37], v112 offset:1808
	ds_read_b128 v[96:99], v112 offset:17920
	ds_read_b128 v[100:103], v112 offset:17936
	v_add_f32_e32 v140, v136, v137
	v_add_f32_e32 v145, v138, v139
	s_waitcnt lgkmcnt(6)
	v_pk_mul_f32 v[128:129], v[22:23], v[38:39]
	v_add_f32_dpp v140, v140, v140 row_half_mirror row_mask:0xf bank_mask:0xf
	v_add_f32_dpp v145, v145, v145 row_half_mirror row_mask:0xf bank_mask:0xf
	v_pk_mul_f32 v[130:131], v[24:25], v[40:41]
	v_pk_mul_f32 v[132:133], v[26:27], v[42:43]
	v_add_f32_dpp v140, v140, v140 quad_perm:[1,0,3,2] row_mask:0xf bank_mask:0xf
	v_add_f32_dpp v145, v145, v145 quad_perm:[1,0,3,2] row_mask:0xf bank_mask:0xf
	v_pk_mul_f32 v[134:135], v[28:29], v[44:45]
	ds_read_b128 v[38:41], v112 offset:5888
	ds_read_b128 v[42:45], v112 offset:5904
	v_add_f32_dpp v140, v140, v140 quad_perm:[2,3,0,1] row_mask:0xf bank_mask:0xf
	v_add_f32_dpp v145, v145, v145 quad_perm:[2,3,0,1] row_mask:0xf bank_mask:0xf
	s_waitcnt lgkmcnt(6)
	v_pk_fma_f32 v[22:23], v[140:141], v[70:71], v[128:129] op_sel_hi:[0,1,1] neg_lo:[1,0,0] neg_hi:[1,0,0]
	v_pk_fma_f32 v[24:25], v[140:141], v[72:73], v[130:131] op_sel_hi:[0,1,1] neg_lo:[1,0,0] neg_hi:[1,0,0]
	v_pk_fma_f32 v[26:27], v[140:141], v[74:75], v[132:133] op_sel_hi:[0,1,1] neg_lo:[1,0,0] neg_hi:[1,0,0]
	v_pk_fma_f32 v[28:29], v[140:141], v[76:77], v[134:135] op_sel_hi:[0,1,1] neg_lo:[1,0,0] neg_hi:[1,0,0]
	ds_read_b128 v[70:73], v112 offset:9984
	ds_read_b128 v[74:77], v112 offset:10000
	s_waitcnt lgkmcnt(4)
	v_pk_mul_f32 v[136:137], v[22:23], v[30:31]
	v_pk_mul_f32 v[138:139], v[22:23], v[96:97]
	v_pk_fma_f32 v[136:137], v[24:25], v[32:33], v[136:137]
	v_pk_fma_f32 v[138:139], v[24:25], v[98:99], v[138:139]
	v_pk_fma_f32 v[136:137], v[26:27], v[34:35], v[136:137]
	v_pk_fma_f32 v[138:139], v[26:27], v[100:101], v[138:139]
	v_pk_fma_f32 v[136:137], v[28:29], v[36:37], v[136:137]
	v_pk_fma_f32 v[138:139], v[28:29], v[102:103], v[138:139]
	ds_read_b128 v[30:33], v112 offset:2048
	ds_read_b128 v[34:37], v112 offset:2064
	ds_read_b128 v[96:99], v112 offset:18176
	ds_read_b128 v[100:103], v112 offset:18192
	v_add_f32_e32 v140, v136, v137
	v_add_f32_e32 v146, v138, v139
	s_waitcnt lgkmcnt(6)
	v_pk_mul_f32 v[128:129], v[22:23], v[38:39]
	v_add_f32_dpp v140, v140, v140 row_half_mirror row_mask:0xf bank_mask:0xf
	v_add_f32_dpp v146, v146, v146 row_half_mirror row_mask:0xf bank_mask:0xf
	v_pk_mul_f32 v[130:131], v[24:25], v[40:41]
	v_pk_mul_f32 v[132:133], v[26:27], v[42:43]
	v_add_f32_dpp v140, v140, v140 quad_perm:[1,0,3,2] row_mask:0xf bank_mask:0xf
	v_add_f32_dpp v146, v146, v146 quad_perm:[1,0,3,2] row_mask:0xf bank_mask:0xf
	v_pk_mul_f32 v[134:135], v[28:29], v[44:45]
	ds_read_b128 v[38:41], v112 offset:6144
	ds_read_b128 v[42:45], v112 offset:6160
	v_add_f32_dpp v140, v140, v140 quad_perm:[2,3,0,1] row_mask:0xf bank_mask:0xf
	v_add_f32_dpp v146, v146, v146 quad_perm:[2,3,0,1] row_mask:0xf bank_mask:0xf
	s_waitcnt lgkmcnt(6)
	v_pk_fma_f32 v[22:23], v[140:141], v[70:71], v[128:129] op_sel_hi:[0,1,1] neg_lo:[1,0,0] neg_hi:[1,0,0]
	v_pk_fma_f32 v[24:25], v[140:141], v[72:73], v[130:131] op_sel_hi:[0,1,1] neg_lo:[1,0,0] neg_hi:[1,0,0]
	v_pk_fma_f32 v[26:27], v[140:141], v[74:75], v[132:133] op_sel_hi:[0,1,1] neg_lo:[1,0,0] neg_hi:[1,0,0]
	v_pk_fma_f32 v[28:29], v[140:141], v[76:77], v[134:135] op_sel_hi:[0,1,1] neg_lo:[1,0,0] neg_hi:[1,0,0]
	ds_read_b128 v[70:73], v112 offset:10240
	ds_read_b128 v[74:77], v112 offset:10256
	s_waitcnt lgkmcnt(4)
	v_pk_mul_f32 v[136:137], v[22:23], v[30:31]
	v_pk_mul_f32 v[138:139], v[22:23], v[96:97]
	v_pk_fma_f32 v[136:137], v[24:25], v[32:33], v[136:137]
	v_pk_fma_f32 v[138:139], v[24:25], v[98:99], v[138:139]
	v_pk_fma_f32 v[136:137], v[26:27], v[34:35], v[136:137]
	v_pk_fma_f32 v[138:139], v[26:27], v[100:101], v[138:139]
	v_pk_fma_f32 v[136:137], v[28:29], v[36:37], v[136:137]
	v_pk_fma_f32 v[138:139], v[28:29], v[102:103], v[138:139]
	ds_read_b128 v[30:33], v112 offset:2304
	ds_read_b128 v[34:37], v112 offset:2320
	ds_read_b128 v[96:99], v112 offset:18432
	ds_read_b128 v[100:103], v112 offset:18448
	v_add_f32_e32 v140, v136, v137
	v_add_f32_e32 v147, v138, v139
	s_waitcnt lgkmcnt(6)
	v_pk_mul_f32 v[128:129], v[22:23], v[38:39]
	v_add_f32_dpp v140, v140, v140 row_half_mirror row_mask:0xf bank_mask:0xf
	v_add_f32_dpp v147, v147, v147 row_half_mirror row_mask:0xf bank_mask:0xf
	v_pk_mul_f32 v[130:131], v[24:25], v[40:41]
	v_pk_mul_f32 v[132:133], v[26:27], v[42:43]
	v_add_f32_dpp v140, v140, v140 quad_perm:[1,0,3,2] row_mask:0xf bank_mask:0xf
	v_add_f32_dpp v147, v147, v147 quad_perm:[1,0,3,2] row_mask:0xf bank_mask:0xf
	v_pk_mul_f32 v[134:135], v[28:29], v[44:45]
	ds_read_b128 v[38:41], v112 offset:6400
	ds_read_b128 v[42:45], v112 offset:6416
	v_add_f32_dpp v140, v140, v140 quad_perm:[2,3,0,1] row_mask:0xf bank_mask:0xf
	v_add_f32_dpp v147, v147, v147 quad_perm:[2,3,0,1] row_mask:0xf bank_mask:0xf
	s_waitcnt lgkmcnt(6)
	v_pk_fma_f32 v[22:23], v[140:141], v[70:71], v[128:129] op_sel_hi:[0,1,1] neg_lo:[1,0,0] neg_hi:[1,0,0]
	v_pk_fma_f32 v[24:25], v[140:141], v[72:73], v[130:131] op_sel_hi:[0,1,1] neg_lo:[1,0,0] neg_hi:[1,0,0]
	v_pk_fma_f32 v[26:27], v[140:141], v[74:75], v[132:133] op_sel_hi:[0,1,1] neg_lo:[1,0,0] neg_hi:[1,0,0]
	v_pk_fma_f32 v[28:29], v[140:141], v[76:77], v[134:135] op_sel_hi:[0,1,1] neg_lo:[1,0,0] neg_hi:[1,0,0]
	ds_read_b128 v[70:73], v112 offset:10496
	ds_read_b128 v[74:77], v112 offset:10512
	ds_write_b128 v113, v[144:147] offset:24592
	s_waitcnt lgkmcnt(5)
	v_pk_mul_f32 v[136:137], v[22:23], v[30:31]
	v_pk_mul_f32 v[138:139], v[22:23], v[96:97]
	v_pk_fma_f32 v[136:137], v[24:25], v[32:33], v[136:137]
	v_pk_fma_f32 v[138:139], v[24:25], v[98:99], v[138:139]
	v_pk_fma_f32 v[136:137], v[26:27], v[34:35], v[136:137]
	v_pk_fma_f32 v[138:139], v[26:27], v[100:101], v[138:139]
	v_pk_fma_f32 v[136:137], v[28:29], v[36:37], v[136:137]
	v_pk_fma_f32 v[138:139], v[28:29], v[102:103], v[138:139]
	ds_read_b128 v[30:33], v112 offset:2560
	ds_read_b128 v[34:37], v112 offset:2576
	ds_read_b128 v[96:99], v112 offset:18688
	ds_read_b128 v[100:103], v112 offset:18704
	v_add_f32_e32 v140, v136, v137
	v_add_f32_e32 v144, v138, v139
	s_waitcnt lgkmcnt(7)
	v_pk_mul_f32 v[128:129], v[22:23], v[38:39]
	v_add_f32_dpp v140, v140, v140 row_half_mirror row_mask:0xf bank_mask:0xf
	v_add_f32_dpp v144, v144, v144 row_half_mirror row_mask:0xf bank_mask:0xf
	v_pk_mul_f32 v[130:131], v[24:25], v[40:41]
	v_pk_mul_f32 v[132:133], v[26:27], v[42:43]
	v_add_f32_dpp v140, v140, v140 quad_perm:[1,0,3,2] row_mask:0xf bank_mask:0xf
	v_add_f32_dpp v144, v144, v144 quad_perm:[1,0,3,2] row_mask:0xf bank_mask:0xf
	v_pk_mul_f32 v[134:135], v[28:29], v[44:45]
	ds_read_b128 v[38:41], v112 offset:6656
	ds_read_b128 v[42:45], v112 offset:6672
	v_add_f32_dpp v140, v140, v140 quad_perm:[2,3,0,1] row_mask:0xf bank_mask:0xf
	v_add_f32_dpp v144, v144, v144 quad_perm:[2,3,0,1] row_mask:0xf bank_mask:0xf
	s_waitcnt lgkmcnt(7)
	v_pk_fma_f32 v[22:23], v[140:141], v[70:71], v[128:129] op_sel_hi:[0,1,1] neg_lo:[1,0,0] neg_hi:[1,0,0]
	v_pk_fma_f32 v[24:25], v[140:141], v[72:73], v[130:131] op_sel_hi:[0,1,1] neg_lo:[1,0,0] neg_hi:[1,0,0]
	v_pk_fma_f32 v[26:27], v[140:141], v[74:75], v[132:133] op_sel_hi:[0,1,1] neg_lo:[1,0,0] neg_hi:[1,0,0]
	v_pk_fma_f32 v[28:29], v[140:141], v[76:77], v[134:135] op_sel_hi:[0,1,1] neg_lo:[1,0,0] neg_hi:[1,0,0]
	ds_read_b128 v[70:73], v112 offset:10752
	ds_read_b128 v[74:77], v112 offset:10768
	s_waitcnt lgkmcnt(4)
	v_pk_mul_f32 v[136:137], v[22:23], v[30:31]
	v_pk_mul_f32 v[138:139], v[22:23], v[96:97]
	v_pk_fma_f32 v[136:137], v[24:25], v[32:33], v[136:137]
	v_pk_fma_f32 v[138:139], v[24:25], v[98:99], v[138:139]
	v_pk_fma_f32 v[136:137], v[26:27], v[34:35], v[136:137]
	v_pk_fma_f32 v[138:139], v[26:27], v[100:101], v[138:139]
	v_pk_fma_f32 v[136:137], v[28:29], v[36:37], v[136:137]
	v_pk_fma_f32 v[138:139], v[28:29], v[102:103], v[138:139]
	ds_read_b128 v[30:33], v112 offset:2816
	ds_read_b128 v[34:37], v112 offset:2832
	ds_read_b128 v[96:99], v112 offset:18944
	ds_read_b128 v[100:103], v112 offset:18960
	v_add_f32_e32 v140, v136, v137
	v_add_f32_e32 v145, v138, v139
	s_waitcnt lgkmcnt(6)
	v_pk_mul_f32 v[128:129], v[22:23], v[38:39]
	v_add_f32_dpp v140, v140, v140 row_half_mirror row_mask:0xf bank_mask:0xf
	v_add_f32_dpp v145, v145, v145 row_half_mirror row_mask:0xf bank_mask:0xf
	v_pk_mul_f32 v[130:131], v[24:25], v[40:41]
	v_pk_mul_f32 v[132:133], v[26:27], v[42:43]
	v_add_f32_dpp v140, v140, v140 quad_perm:[1,0,3,2] row_mask:0xf bank_mask:0xf
	v_add_f32_dpp v145, v145, v145 quad_perm:[1,0,3,2] row_mask:0xf bank_mask:0xf
	v_pk_mul_f32 v[134:135], v[28:29], v[44:45]
	ds_read_b128 v[38:41], v112 offset:6912
	ds_read_b128 v[42:45], v112 offset:6928
	v_add_f32_dpp v140, v140, v140 quad_perm:[2,3,0,1] row_mask:0xf bank_mask:0xf
	v_add_f32_dpp v145, v145, v145 quad_perm:[2,3,0,1] row_mask:0xf bank_mask:0xf
	s_waitcnt lgkmcnt(6)
	v_pk_fma_f32 v[22:23], v[140:141], v[70:71], v[128:129] op_sel_hi:[0,1,1] neg_lo:[1,0,0] neg_hi:[1,0,0]
	v_pk_fma_f32 v[24:25], v[140:141], v[72:73], v[130:131] op_sel_hi:[0,1,1] neg_lo:[1,0,0] neg_hi:[1,0,0]
	v_pk_fma_f32 v[26:27], v[140:141], v[74:75], v[132:133] op_sel_hi:[0,1,1] neg_lo:[1,0,0] neg_hi:[1,0,0]
	v_pk_fma_f32 v[28:29], v[140:141], v[76:77], v[134:135] op_sel_hi:[0,1,1] neg_lo:[1,0,0] neg_hi:[1,0,0]
	ds_read_b128 v[70:73], v112 offset:11008
	ds_read_b128 v[74:77], v112 offset:11024
	s_waitcnt lgkmcnt(4)
	v_pk_mul_f32 v[136:137], v[22:23], v[30:31]
	v_pk_mul_f32 v[138:139], v[22:23], v[96:97]
	v_pk_fma_f32 v[136:137], v[24:25], v[32:33], v[136:137]
	v_pk_fma_f32 v[138:139], v[24:25], v[98:99], v[138:139]
	v_pk_fma_f32 v[136:137], v[26:27], v[34:35], v[136:137]
	v_pk_fma_f32 v[138:139], v[26:27], v[100:101], v[138:139]
	v_pk_fma_f32 v[136:137], v[28:29], v[36:37], v[136:137]
	v_pk_fma_f32 v[138:139], v[28:29], v[102:103], v[138:139]
	ds_read_b128 v[30:33], v112 offset:3072
	ds_read_b128 v[34:37], v112 offset:3088
	ds_read_b128 v[96:99], v112 offset:19200
	ds_read_b128 v[100:103], v112 offset:19216
	v_add_f32_e32 v140, v136, v137
	v_add_f32_e32 v146, v138, v139
	s_waitcnt lgkmcnt(6)
	v_pk_mul_f32 v[128:129], v[22:23], v[38:39]
	v_add_f32_dpp v140, v140, v140 row_half_mirror row_mask:0xf bank_mask:0xf
	v_add_f32_dpp v146, v146, v146 row_half_mirror row_mask:0xf bank_mask:0xf
	v_pk_mul_f32 v[130:131], v[24:25], v[40:41]
	v_pk_mul_f32 v[132:133], v[26:27], v[42:43]
	v_add_f32_dpp v140, v140, v140 quad_perm:[1,0,3,2] row_mask:0xf bank_mask:0xf
	v_add_f32_dpp v146, v146, v146 quad_perm:[1,0,3,2] row_mask:0xf bank_mask:0xf
	v_pk_mul_f32 v[134:135], v[28:29], v[44:45]
	ds_read_b128 v[38:41], v112 offset:7168
	ds_read_b128 v[42:45], v112 offset:7184
	v_add_f32_dpp v140, v140, v140 quad_perm:[2,3,0,1] row_mask:0xf bank_mask:0xf
	v_add_f32_dpp v146, v146, v146 quad_perm:[2,3,0,1] row_mask:0xf bank_mask:0xf
	s_waitcnt lgkmcnt(6)
	v_pk_fma_f32 v[22:23], v[140:141], v[70:71], v[128:129] op_sel_hi:[0,1,1] neg_lo:[1,0,0] neg_hi:[1,0,0]
	v_pk_fma_f32 v[24:25], v[140:141], v[72:73], v[130:131] op_sel_hi:[0,1,1] neg_lo:[1,0,0] neg_hi:[1,0,0]
	v_pk_fma_f32 v[26:27], v[140:141], v[74:75], v[132:133] op_sel_hi:[0,1,1] neg_lo:[1,0,0] neg_hi:[1,0,0]
	v_pk_fma_f32 v[28:29], v[140:141], v[76:77], v[134:135] op_sel_hi:[0,1,1] neg_lo:[1,0,0] neg_hi:[1,0,0]
	ds_read_b128 v[70:73], v112 offset:11264
	ds_read_b128 v[74:77], v112 offset:11280
	s_waitcnt lgkmcnt(4)
	v_pk_mul_f32 v[136:137], v[22:23], v[30:31]
	v_pk_mul_f32 v[138:139], v[22:23], v[96:97]
	v_pk_fma_f32 v[136:137], v[24:25], v[32:33], v[136:137]
	v_pk_fma_f32 v[138:139], v[24:25], v[98:99], v[138:139]
	v_pk_fma_f32 v[136:137], v[26:27], v[34:35], v[136:137]
	v_pk_fma_f32 v[138:139], v[26:27], v[100:101], v[138:139]
	v_pk_fma_f32 v[136:137], v[28:29], v[36:37], v[136:137]
	v_pk_fma_f32 v[138:139], v[28:29], v[102:103], v[138:139]
	ds_read_b128 v[30:33], v112 offset:3328
	ds_read_b128 v[34:37], v112 offset:3344
	ds_read_b128 v[96:99], v112 offset:19456
	ds_read_b128 v[100:103], v112 offset:19472
	v_add_f32_e32 v140, v136, v137
	v_add_f32_e32 v147, v138, v139
	s_waitcnt lgkmcnt(6)
	v_pk_mul_f32 v[128:129], v[22:23], v[38:39]
	v_add_f32_dpp v140, v140, v140 row_half_mirror row_mask:0xf bank_mask:0xf
	v_add_f32_dpp v147, v147, v147 row_half_mirror row_mask:0xf bank_mask:0xf
	v_pk_mul_f32 v[130:131], v[24:25], v[40:41]
	v_pk_mul_f32 v[132:133], v[26:27], v[42:43]
	v_add_f32_dpp v140, v140, v140 quad_perm:[1,0,3,2] row_mask:0xf bank_mask:0xf
	v_add_f32_dpp v147, v147, v147 quad_perm:[1,0,3,2] row_mask:0xf bank_mask:0xf
	v_pk_mul_f32 v[134:135], v[28:29], v[44:45]
	ds_read_b128 v[38:41], v112 offset:7424
	ds_read_b128 v[42:45], v112 offset:7440
	v_add_f32_dpp v140, v140, v140 quad_perm:[2,3,0,1] row_mask:0xf bank_mask:0xf
	v_add_f32_dpp v147, v147, v147 quad_perm:[2,3,0,1] row_mask:0xf bank_mask:0xf
	s_waitcnt lgkmcnt(6)
	v_pk_fma_f32 v[22:23], v[140:141], v[70:71], v[128:129] op_sel_hi:[0,1,1] neg_lo:[1,0,0] neg_hi:[1,0,0]
	v_pk_fma_f32 v[24:25], v[140:141], v[72:73], v[130:131] op_sel_hi:[0,1,1] neg_lo:[1,0,0] neg_hi:[1,0,0]
	v_pk_fma_f32 v[26:27], v[140:141], v[74:75], v[132:133] op_sel_hi:[0,1,1] neg_lo:[1,0,0] neg_hi:[1,0,0]
	v_pk_fma_f32 v[28:29], v[140:141], v[76:77], v[134:135] op_sel_hi:[0,1,1] neg_lo:[1,0,0] neg_hi:[1,0,0]
	ds_read_b128 v[70:73], v112 offset:11520
	ds_read_b128 v[74:77], v112 offset:11536
	ds_write_b128 v113, v[144:147] offset:24608
	s_waitcnt lgkmcnt(5)
	v_pk_mul_f32 v[136:137], v[22:23], v[30:31]
	v_pk_mul_f32 v[138:139], v[22:23], v[96:97]
	v_pk_fma_f32 v[136:137], v[24:25], v[32:33], v[136:137]
	v_pk_fma_f32 v[138:139], v[24:25], v[98:99], v[138:139]
	v_pk_fma_f32 v[136:137], v[26:27], v[34:35], v[136:137]
	v_pk_fma_f32 v[138:139], v[26:27], v[100:101], v[138:139]
	v_pk_fma_f32 v[136:137], v[28:29], v[36:37], v[136:137]
	v_pk_fma_f32 v[138:139], v[28:29], v[102:103], v[138:139]
	ds_read_b128 v[30:33], v112 offset:3584
	ds_read_b128 v[34:37], v112 offset:3600
	ds_read_b128 v[96:99], v112 offset:19712
	ds_read_b128 v[100:103], v112 offset:19728
	v_add_f32_e32 v140, v136, v137
	v_add_f32_e32 v144, v138, v139
	s_waitcnt lgkmcnt(7)
	v_pk_mul_f32 v[128:129], v[22:23], v[38:39]
	v_add_f32_dpp v140, v140, v140 row_half_mirror row_mask:0xf bank_mask:0xf
	v_add_f32_dpp v144, v144, v144 row_half_mirror row_mask:0xf bank_mask:0xf
	v_pk_mul_f32 v[130:131], v[24:25], v[40:41]
	v_pk_mul_f32 v[132:133], v[26:27], v[42:43]
	v_add_f32_dpp v140, v140, v140 quad_perm:[1,0,3,2] row_mask:0xf bank_mask:0xf
	v_add_f32_dpp v144, v144, v144 quad_perm:[1,0,3,2] row_mask:0xf bank_mask:0xf
	v_pk_mul_f32 v[134:135], v[28:29], v[44:45]
	ds_read_b128 v[38:41], v112 offset:7680
	ds_read_b128 v[42:45], v112 offset:7696
	v_add_f32_dpp v140, v140, v140 quad_perm:[2,3,0,1] row_mask:0xf bank_mask:0xf
	v_add_f32_dpp v144, v144, v144 quad_perm:[2,3,0,1] row_mask:0xf bank_mask:0xf
	s_waitcnt lgkmcnt(7)
	v_pk_fma_f32 v[22:23], v[140:141], v[70:71], v[128:129] op_sel_hi:[0,1,1] neg_lo:[1,0,0] neg_hi:[1,0,0]
	v_pk_fma_f32 v[24:25], v[140:141], v[72:73], v[130:131] op_sel_hi:[0,1,1] neg_lo:[1,0,0] neg_hi:[1,0,0]
	v_pk_fma_f32 v[26:27], v[140:141], v[74:75], v[132:133] op_sel_hi:[0,1,1] neg_lo:[1,0,0] neg_hi:[1,0,0]
	v_pk_fma_f32 v[28:29], v[140:141], v[76:77], v[134:135] op_sel_hi:[0,1,1] neg_lo:[1,0,0] neg_hi:[1,0,0]
	ds_read_b128 v[70:73], v112 offset:11776
	ds_read_b128 v[74:77], v112 offset:11792
	s_waitcnt lgkmcnt(4)
	v_pk_mul_f32 v[136:137], v[22:23], v[30:31]
	v_pk_mul_f32 v[138:139], v[22:23], v[96:97]
	v_pk_fma_f32 v[136:137], v[24:25], v[32:33], v[136:137]
	v_pk_fma_f32 v[138:139], v[24:25], v[98:99], v[138:139]
	v_pk_fma_f32 v[136:137], v[26:27], v[34:35], v[136:137]
	v_pk_fma_f32 v[138:139], v[26:27], v[100:101], v[138:139]
	v_pk_fma_f32 v[136:137], v[28:29], v[36:37], v[136:137]
	v_pk_fma_f32 v[138:139], v[28:29], v[102:103], v[138:139]
	ds_read_b128 v[30:33], v112 offset:3840
	ds_read_b128 v[34:37], v112 offset:3856
	ds_read_b128 v[96:99], v112 offset:19968
	ds_read_b128 v[100:103], v112 offset:19984
	v_add_f32_e32 v140, v136, v137
	v_add_f32_e32 v145, v138, v139
	s_waitcnt lgkmcnt(6)
	v_pk_mul_f32 v[128:129], v[22:23], v[38:39]
	v_add_f32_dpp v140, v140, v140 row_half_mirror row_mask:0xf bank_mask:0xf
	v_add_f32_dpp v145, v145, v145 row_half_mirror row_mask:0xf bank_mask:0xf
	v_pk_mul_f32 v[130:131], v[24:25], v[40:41]
	v_pk_mul_f32 v[132:133], v[26:27], v[42:43]
	v_add_f32_dpp v140, v140, v140 quad_perm:[1,0,3,2] row_mask:0xf bank_mask:0xf
	v_add_f32_dpp v145, v145, v145 quad_perm:[1,0,3,2] row_mask:0xf bank_mask:0xf
	v_pk_mul_f32 v[134:135], v[28:29], v[44:45]
	ds_read_b128 v[38:41], v112 offset:7936
	ds_read_b128 v[42:45], v112 offset:7952
	v_add_f32_dpp v140, v140, v140 quad_perm:[2,3,0,1] row_mask:0xf bank_mask:0xf
	v_add_f32_dpp v145, v145, v145 quad_perm:[2,3,0,1] row_mask:0xf bank_mask:0xf
	s_waitcnt lgkmcnt(6)
	v_pk_fma_f32 v[22:23], v[140:141], v[70:71], v[128:129] op_sel_hi:[0,1,1] neg_lo:[1,0,0] neg_hi:[1,0,0]
	v_pk_fma_f32 v[24:25], v[140:141], v[72:73], v[130:131] op_sel_hi:[0,1,1] neg_lo:[1,0,0] neg_hi:[1,0,0]
	v_pk_fma_f32 v[26:27], v[140:141], v[74:75], v[132:133] op_sel_hi:[0,1,1] neg_lo:[1,0,0] neg_hi:[1,0,0]
	v_pk_fma_f32 v[28:29], v[140:141], v[76:77], v[134:135] op_sel_hi:[0,1,1] neg_lo:[1,0,0] neg_hi:[1,0,0]
	ds_read_b128 v[70:73], v112 offset:12032
	ds_read_b128 v[74:77], v112 offset:12048
	s_waitcnt lgkmcnt(4)
	v_pk_mul_f32 v[136:137], v[22:23], v[30:31]
	v_pk_mul_f32 v[138:139], v[22:23], v[96:97]
	v_pk_fma_f32 v[136:137], v[24:25], v[32:33], v[136:137]
	v_pk_fma_f32 v[138:139], v[24:25], v[98:99], v[138:139]
	v_pk_fma_f32 v[136:137], v[26:27], v[34:35], v[136:137]
	v_pk_fma_f32 v[138:139], v[26:27], v[100:101], v[138:139]
	v_pk_fma_f32 v[136:137], v[28:29], v[36:37], v[136:137]
	v_pk_fma_f32 v[138:139], v[28:29], v[102:103], v[138:139]
	ds_read_b128 v[96:99], v112 offset:20224
	ds_read_b128 v[100:103], v112 offset:20240
	v_add_f32_e32 v140, v136, v137
	v_add_f32_e32 v146, v138, v139
	s_waitcnt lgkmcnt(4)
	v_pk_mul_f32 v[128:129], v[22:23], v[38:39]
	v_add_f32_dpp v140, v140, v140 row_half_mirror row_mask:0xf bank_mask:0xf
	v_add_f32_dpp v146, v146, v146 row_half_mirror row_mask:0xf bank_mask:0xf
	v_pk_mul_f32 v[130:131], v[24:25], v[40:41]
	v_pk_mul_f32 v[132:133], v[26:27], v[42:43]
	v_add_f32_dpp v140, v140, v140 quad_perm:[1,0,3,2] row_mask:0xf bank_mask:0xf
	v_add_f32_dpp v146, v146, v146 quad_perm:[1,0,3,2] row_mask:0xf bank_mask:0xf
	v_pk_mul_f32 v[134:135], v[28:29], v[44:45]
	v_add_f32_dpp v140, v140, v140 quad_perm:[2,3,0,1] row_mask:0xf bank_mask:0xf
	v_add_f32_dpp v146, v146, v146 quad_perm:[2,3,0,1] row_mask:0xf bank_mask:0xf
	s_waitcnt lgkmcnt(2)
	v_pk_fma_f32 v[22:23], v[140:141], v[70:71], v[128:129] op_sel_hi:[0,1,1] neg_lo:[1,0,0] neg_hi:[1,0,0]
	v_pk_fma_f32 v[24:25], v[140:141], v[72:73], v[130:131] op_sel_hi:[0,1,1] neg_lo:[1,0,0] neg_hi:[1,0,0]
	v_pk_fma_f32 v[26:27], v[140:141], v[74:75], v[132:133] op_sel_hi:[0,1,1] neg_lo:[1,0,0] neg_hi:[1,0,0]
	v_pk_fma_f32 v[28:29], v[140:141], v[76:77], v[134:135] op_sel_hi:[0,1,1] neg_lo:[1,0,0] neg_hi:[1,0,0]
	s_waitcnt lgkmcnt(0)
	v_pk_mul_f32 v[138:139], v[22:23], v[96:97]
	v_pk_fma_f32 v[138:139], v[24:25], v[98:99], v[138:139]
	v_pk_fma_f32 v[138:139], v[26:27], v[100:101], v[138:139]
	v_pk_fma_f32 v[138:139], v[28:29], v[102:103], v[138:139]
	v_add_f32_e32 v147, v138, v139
	s_nop 1
	v_add_f32_dpp v147, v147, v147 row_half_mirror row_mask:0xf bank_mask:0xf
	s_nop 1
	v_add_f32_dpp v147, v147, v147 quad_perm:[1,0,3,2] row_mask:0xf bank_mask:0xf
	s_nop 1
	v_add_f32_dpp v147, v147, v147 quad_perm:[2,3,0,1] row_mask:0xf bank_mask:0xf
	ds_write_b128 v113, v[144:147] offset:24624
.Lrw0_u2e1:
	s_add_u32 s28, s28, 16
	s_cmp_lt_u32 s28, s25
	s_cbranch_scc1 .Lrw0_loop
	s_waitcnt lgkmcnt(0)
	s_barrier
	ds_read_b32 v89, v5 offset:24576
	ds_read_b32 v90, v5 offset:25600
	s_sub_u32 s98, s28, 16
	v_add_u32_e32 v87, s98, v127
	v_mad_i64_i32 v[104:105], vcc, v87, v20, v[18:19]
	s_waitcnt lgkmcnt(0)
	v_cvt_pk_bf16_f32 v89, v89, v90
	global_store_short v[104:105], v89, off
	global_store_short_d16_hi v[104:105], v89, off offset:32
	v_lshrrev_b32_e32 v87, 2, v108
	v_lshl_add_u32 v87, s17, 4, v87
	v_lshl_add_u32 v89, v87, 8, v112
	s_cmp_eq_u32 s18, 3
	s_cbranch_scc0 .Lrw0_f_not3
	s_load_dwordx2 s[36:37], s[14:15], 0x120
	s_waitcnt lgkmcnt(0)
	s_lshl_b32 s98, s42, 14
	s_add_u32 s36, s36, s98
	s_addc_u32 s37, s37, 0
	s_add_u32 s36, s36, 0x5e00000
	s_addc_u32 s37, s37, 0
	global_store_dwordx4 v89, v[22:25], s[36:37]
	global_store_dwordx4 v89, v[26:29], s[36:37] offset:16
	s_branch .Lrw0_f_done

.Lrw1_gdone:
	s_sub_u32 s29, s23, 1
	s_lshr_b32 s30, s23, 1
	s_cmp_eq_u32 s18, 0
	s_cselect_b32 s25, s30, s23
	s_sub_u32 s31, s18, 1
	s_cmp_lt_u32 s31, 2
	s_cselect_b32 s24, s30, 0
	s_cmp_eq_u32 s18, 2
	s_cselect_b32 s40, 0, 1.0
	s_mov_b32 s41, s40
	s_lshl_b32 s42, s21, 1
	s_add_u32 s42, s42, 1
	s_lshl_b32 s42, s42, 1
	s_add_u32 s42, s42, s20
	s_lshl_b32 s42, s42, 2
	s_add_u32 s42, s42, s19
	v_readlane_b32 s14, v246, 10
	v_readlane_b32 s15, v246, 11
	s_nop 4
	s_load_dwordx2 s[4:5], s[14:15], 0x178
	s_load_dwordx2 s[6:7], s[14:15], 0x188
	s_load_dwordx2 s[8:9], s[14:15], 0x198
	s_load_dwordx2 s[10:11], s[14:15], 0x98
	s_load_dwordx2 s[12:13], s[14:15], 0xc8
	s_load_dwordx2 s[26:27], s[14:15], 0xd0
	v_and_b32_e32 v87, 15, v226
	v_lshrrev_b32_e32 v127, 4, v226
	v_lshlrev_b32_e32 v95, 4, v87
	v_lshrrev_b32_e32 v108, 3, v226
	v_lshlrev_b32_e32 v108, 2, v108
	v_and_b32_e32 v112, 7, v226
	v_lshlrev_b32_e32 v112, 5, v112
	v_mul_u32_u24_e32 v93, 80, v87
	v_lshlrev_b32_e32 v110, 4, v226
	v_lshlrev_b32_e32 v115, 2, v226
	v_mul_u32_u24_e32 v1, 0x180, v127
	v_lshl_add_u32 v1, v87, 3, v1
	v_lshlrev_b32_e32 v2, 8, v127
	v_add_u32_e32 v3, v2, v95
	v_lshl_add_u32 v2, v87, 3, v2
	v_lshrrev_b32_e32 v89, 3, v87
	v_and_b32_e32 v90, 7, v87
	v_lshlrev_b32_e32 v91, 7, v127
	v_lshl_add_u32 v91, v90, 4, v91
	s_lshr_b32 s98, s17, 1
	v_add_u32_e32 v91, 0x5000, v91
	v_add_u32_e32 v92, 0xa000, v110
	v_cmp_eq_u32_e32 vcc, s98, v89
	s_nop 1
	v_cndmask_b32_e32 v4, v92, v91, vcc
	v_lshlrev_b32_e32 v5, 2, v127
	v_lshl_add_u32 v5, v87, 6, v5
	v_lshlrev_b32_e32 v113, 4, v108
	s_mov_b32 s30, 0xaaaaaab
	s_lshl_b32 s31, s19, 7
	v_mul_hi_u32 v87, v226, s30
	v_mul_u32_u24_e32 v89, 24, v87
	v_sub_u32_e32 v89, v226, v89
	v_add_u32_e32 v15, -1, v87
	v_lshrrev_b32_e32 v90, 3, v89
	v_and_b32_e32 v89, 7, v89
	v_lshlrev_b32_e32 v90, 9, v90
	v_lshl_add_u32 v91, v89, 4, v90
	v_add_u32_e32 v91, s31, v91
	v_add_u32_e32 v91, 0xd20, v91
	s_add_u32 s34, s22, s29
	s_cmp_eq_u32 s20, 0
	s_cselect_b32 s34, s22, s34
	s_waitcnt lgkmcnt(0)
	s_mul_i32 s98, s34, 0x1520
	s_mul_hi_u32 s99, s34, 0x1520
	s_add_u32 s100, s4, s98
	s_addc_u32 s101, s5, s99
	s_mul_i32 s98, s34, 0xa00
	s_mul_hi_u32 s99, s34, 0xa00
	s_add_u32 s98, s6, s98
	s_addc_u32 s99, s7, s99
	v_mov_b32_e32 v92, 0
	v_mov_b32_e32 v6, s100
	v_mov_b32_e32 v7, s101
	v_add_co_u32_e32 v6, vcc, v6, v91
	s_nop 1
	v_addc_co_u32_e32 v7, vcc, 0, v7, vcc
	s_movk_i32 s36, 0x1520
	s_mul_i32 s37, s36, -1
	s_cmp_eq_u32 s20, 0
	s_cselect_b32 s34, s36, s37
	s_movk_i32 s36, 0xa00
	s_mul_i32 s37, s36, -1
	s_cselect_b32 s35, s36, s37
	v_mov_b32_e32 v12, s34
	v_add_u32_e32 v92, 0x100, v226
	v_mul_hi_u32 v87, v92, s30
	v_mul_u32_u24_e32 v89, 24, v87
	v_sub_u32_e32 v89, v92, v89
	v_add_u32_e32 v16, -1, v87
	v_lshrrev_b32_e32 v90, 3, v89
	v_and_b32_e32 v89, 7, v89
	v_lshlrev_b32_e32 v90, 9, v90
	v_lshl_add_u32 v91, v89, 4, v90
	v_add_u32_e32 v91, s31, v91
	v_add_u32_e32 v91, 0xd20, v91
	s_lshl_b32 s36, s20, 9
	s_add_u32 s36, s36, s31
	v_add_u32_e32 v92, 0xffffff50, v226
	v_lshrrev_b32_e32 v21, 4, v92
	v_and_b32_e32 v87, 15, v92
	v_lshrrev_b32_e32 v89, 3, v87
	v_and_b32_e32 v87, 7, v87
	v_lshlrev_b32_e32 v89, 10, v89
	v_lshl_add_u32 v90, v87, 4, v89
	v_add_u32_e32 v90, s36, v90
	v_cmp_gt_u32_e32 vcc, 0xb0, v226
	s_nop 1
	v_cndmask_b32_e32 v16, v21, v16, vcc
	v_cndmask_b32_e32 v91, v90, v91, vcc
	v_mov_b32_e32 v87, s35
	v_mov_b32_e32 v89, s34
	v_cndmask_b32_e32 v13, v87, v89, vcc
	v_mov_b32_e32 v87, s98
	v_mov_b32_e32 v89, s100
	v_cndmask_b32_e32 v8, v87, v89, vcc
	v_mov_b32_e32 v87, s99
	v_mov_b32_e32 v89, s101
	v_cndmask_b32_e32 v9, v87, v89, vcc
	v_add_co_u32_e32 v8, vcc, v8, v91
	s_nop 1
	v_addc_co_u32_e32 v9, vcc, 0, v9, vcc
	v_add_u32_e32 v92, 0x50, v226
	v_lshrrev_b32_e32 v17, 4, v92
	v_and_b32_e32 v87, 15, v92
	v_lshrrev_b32_e32 v89, 3, v87
	v_and_b32_e32 v87, 7, v87
	v_lshlrev_b32_e32 v89, 10, v89
	v_lshl_add_u32 v91, v87, 4, v89
	v_add_u32_e32 v91, s36, v91
	v_mov_b32_e32 v10, s98
	v_mov_b32_e32 v11, s99
	v_add_co_u32_e32 v10, vcc, v10, v91
	s_nop 1
	v_addc_co_u32_e32 v11, vcc, 0, v11, vcc
	v_mov_b32_e32 v14, s35
	s_add_u32 s30, s22, s29
	s_cmp_eq_u32 s20, 0
	s_cselect_b32 s30, s22, s30
	s_lshl_b32 s36, s19, 7
	s_lshl_b32 s37, s17, 5
	s_add_u32 s36, s36, s37
	s_cmp_eq_u32 s18, 2
	s_cbranch_scc1 .Lrw1_o_u2
	s_lshl_b32 s37, s20, 9
	s_add_u32 s36, s36, s37
	s_mul_i32 s98, s30, 0xa00
	s_mul_hi_u32 s99, s30, 0xa00
	s_add_u32 s98, s98, s36
	s_addc_u32 s99, s99, 0
	s_add_u32 s98, s8, s98
	s_addc_u32 s99, s9, s99
	s_movk_i32 s36, 0xa00
	s_mul_i32 s37, s36, -1
	s_cmp_eq_u32 s20, 0
	s_cselect_b32 s35, s36, s37
	s_branch .Lrw1_o_done
